# Hyena I/O stages rewritten: u16 loads of 8 positions batched (unconditional loads + select at sequence ends) instead of one serialized load per wait
# speedup vs baseline: 1.0414x; 1.0414x over previous
; DI float bf2f(u16 v) { return __uint_as_float(((unsigned)v) << 16); }
; DI void hyena_unit(KP p, int l, int c, char* smem) {
;     ...
;     const int colf = o * 512 + c, colb = 1024 + o * 512 + c;
;     const float skip = p->hy_skip[(l * 2 + o) * 512 + c];
;     __syncthreads();
; #pragma unroll 4
;     for (int jj = 0; jj < 16; ++jj) {
;       const int t = tid + 256 * jj;
;       const float hf = bf2f(Ff[(size_t)colf * 4096 + t]), hb = bf2f(Ff[(size_t)colb * 4096 + t]);
;       if (t == 0) { buf[SW(0)] = mkf2(hf + hb + skip, 0.f); buf[SW(4096)] = mkf2(0.f, 0.f); }
;       else { buf[SW(t)] = mkf2(hf, 0.f); buf[SW(8192 - t)] = mkf2(hb, 0.f); }
;     }
.LBB0_915:
	s_add_i32 s3, s2, s86
	s_add_i32 s4, s3, s74
	s_ashr_i32 s5, s4, 31
	s_xor_b64 s[34:35], s[96:97], -1
	s_lshl_b64 s[4:5], s[4:5], 2
	s_add_u32 s4, s18, s4
	s_addc_u32 s5, s19, s5
	global_load_dword v8, v199, s[4:5]
	s_add_u32 s4, s54, s2
	s_addc_u32 s5, s79, 0
	s_lshl_b64 s[4:5], s[4:5], 13
	s_add_u32 s2, s84, s2
	s_addc_u32 s3, s85, 0
	s_lshl_b64 s[2:3], s[2:3], 13
	v_lshl_add_u64 v[2:3], v[72:73], 0, s[4:5]
	v_lshl_add_u64 v[4:5], v[72:73], 0, s[2:3]
	s_movk_i32 s2, 0xf000
	v_sub_u32_e32 v9, 0x1d00, v66
	s_barrier
	s_mov_b64 s[4:5], 0x1000
	v_lshl_add_u64 v[6:7], v[4:5], 0, s[4:5]
	v_lshl_add_u64 v[10:11], v[2:3], 0, s[4:5]
	global_load_ushort v16, v[4:5], off offset:-1024
	global_load_ushort v18, v[4:5], off offset:-512
	global_load_ushort v20, v[4:5], off offset:0
	global_load_ushort v22, v[4:5], off offset:512
	global_load_ushort v24, v[4:5], off offset:1024
	global_load_ushort v26, v[4:5], off offset:1536
	global_load_ushort v28, v[4:5], off offset:2048
	global_load_ushort v30, v[4:5], off offset:2560
	global_load_ushort v32, v[4:5], off offset:3072
	global_load_ushort v34, v[4:5], off offset:3584
	global_load_ushort v36, v[6:7], off offset:0
	global_load_ushort v38, v[6:7], off offset:512
	global_load_ushort v40, v[6:7], off offset:1024
	global_load_ushort v42, v[6:7], off offset:1536
	global_load_ushort v44, v[6:7], off offset:2048
	global_load_ushort v46, v[6:7], off offset:2560
	global_load_ushort v104, v[2:3], off offset:-1024
	global_load_ushort v106, v[2:3], off offset:-512
	global_load_ushort v108, v[2:3], off offset:0
	global_load_ushort v110, v[2:3], off offset:512
	global_load_ushort v112, v[2:3], off offset:1024
	global_load_ushort v114, v[2:3], off offset:1536
	global_load_ushort v116, v[2:3], off offset:2048
	global_load_ushort v118, v[2:3], off offset:2560
	global_load_ushort v120, v[2:3], off offset:3072
	global_load_ushort v122, v[2:3], off offset:3584
	global_load_ushort v124, v[10:11], off offset:0
	global_load_ushort v126, v[10:11], off offset:512
	global_load_ushort v128, v[10:11], off offset:1024
	global_load_ushort v130, v[10:11], off offset:1536
	global_load_ushort v132, v[10:11], off offset:2048
	global_load_ushort v134, v[10:11], off offset:2560
	v_mov_b32_e32 v17, 0
	v_mov_b32_e32 v105, 0
	v_mov_b32_e32 v19, 0
	v_mov_b32_e32 v107, 0
	v_mov_b32_e32 v21, 0
	v_mov_b32_e32 v109, 0
	v_mov_b32_e32 v23, 0
	v_mov_b32_e32 v111, 0
	v_mov_b32_e32 v25, 0
	v_mov_b32_e32 v113, 0
	v_mov_b32_e32 v27, 0
	v_mov_b32_e32 v115, 0
	v_mov_b32_e32 v29, 0
	v_mov_b32_e32 v117, 0
	v_mov_b32_e32 v31, 0
	v_mov_b32_e32 v119, 0
	v_mov_b32_e32 v33, 0
	v_mov_b32_e32 v121, 0
	v_mov_b32_e32 v35, 0
	v_mov_b32_e32 v123, 0
	v_mov_b32_e32 v37, 0
	v_mov_b32_e32 v125, 0
	v_mov_b32_e32 v39, 0
	v_mov_b32_e32 v127, 0
	v_mov_b32_e32 v41, 0
	v_mov_b32_e32 v129, 0
	v_mov_b32_e32 v43, 0
	v_mov_b32_e32 v131, 0
	v_mov_b32_e32 v45, 0
	v_mov_b32_e32 v133, 0
	v_mov_b32_e32 v47, 0
	v_mov_b32_e32 v135, 0
	v_xor_b32_e32 v12, v66, v155
	v_sub_u32_e32 v14, 0x100, v66
	v_lshlrev_b32_e32 v12, 3, v12
	v_bfe_i32 v13, v14, 5, 1
	v_bfe_i32 v15, v14, 6, 1
	v_and_b32_e32 v13, 5, v13
	v_and_b32_e32 v15, 26, v15
	v_or_b32_e32 v13, v13, v15
	v_xor_b32_e32 v13, v13, v14
	v_lshlrev_b32_e32 v13, 3, v13
	v_cmp_ne_u32_e32 vcc, 0, v66
	s_mov_b64 s[6:7], vcc
	s_waitcnt vmcnt(0)
	v_lshlrev_b32_e32 v16, 16, v16
	v_lshlrev_b32_e32 v104, 16, v104
	v_lshlrev_b32_e32 v18, 16, v18
	v_lshlrev_b32_e32 v106, 16, v106
	v_lshlrev_b32_e32 v20, 16, v20
	v_lshlrev_b32_e32 v108, 16, v108
	v_lshlrev_b32_e32 v22, 16, v22
	v_lshlrev_b32_e32 v110, 16, v110
	v_lshlrev_b32_e32 v24, 16, v24
	v_lshlrev_b32_e32 v112, 16, v112
	v_lshlrev_b32_e32 v26, 16, v26
	v_lshlrev_b32_e32 v114, 16, v114
	v_lshlrev_b32_e32 v28, 16, v28
	v_lshlrev_b32_e32 v116, 16, v116
	v_lshlrev_b32_e32 v30, 16, v30
	v_lshlrev_b32_e32 v118, 16, v118
	v_lshlrev_b32_e32 v32, 16, v32
	v_lshlrev_b32_e32 v120, 16, v120
	v_lshlrev_b32_e32 v34, 16, v34
	v_lshlrev_b32_e32 v122, 16, v122
	v_lshlrev_b32_e32 v36, 16, v36
	v_lshlrev_b32_e32 v124, 16, v124
	v_lshlrev_b32_e32 v38, 16, v38
	v_lshlrev_b32_e32 v126, 16, v126
	v_lshlrev_b32_e32 v40, 16, v40
	v_lshlrev_b32_e32 v128, 16, v128
	v_lshlrev_b32_e32 v42, 16, v42
	v_lshlrev_b32_e32 v130, 16, v130
	v_lshlrev_b32_e32 v44, 16, v44
	v_lshlrev_b32_e32 v132, 16, v132
	v_lshlrev_b32_e32 v46, 16, v46
	v_lshlrev_b32_e32 v134, 16, v134
	s_and_b64 exec, exec, s[6:7]
	ds_write_b64 v12, v[16:17]
	ds_write_b64 v13, v[104:105] offset:63488
	s_andn2_b64 exec, -1, s[6:7]
	s_cbranch_execz .Lhy_fC_not0
	v_add_f32_e32 v16, v16, v104
	v_add_f32_e32 v16, v8, v16
	ds_write2st64_b64 v199, v[16:17], v[252:253] offset1:64
.Lhy_fC_not0:
	s_mov_b64 exec, -1
	ds_write_b64 v12, v[18:19] offset:2048
	ds_write_b64 v13, v[106:107] offset:61440
	ds_write_b64 v12, v[20:21] offset:4096
	ds_write_b64 v13, v[108:109] offset:59392
	ds_write_b64 v12, v[22:23] offset:6144
	ds_write_b64 v13, v[110:111] offset:57344
	ds_write_b64 v12, v[24:25] offset:8192
	ds_write_b64 v13, v[112:113] offset:55296
	ds_write_b64 v12, v[26:27] offset:10240
	ds_write_b64 v13, v[114:115] offset:53248
	ds_write_b64 v12, v[28:29] offset:12288
	ds_write_b64 v13, v[116:117] offset:51200
	ds_write_b64 v12, v[30:31] offset:14336
	ds_write_b64 v13, v[118:119] offset:49152
	ds_write_b64 v12, v[32:33] offset:16384
	ds_write_b64 v13, v[120:121] offset:47104
	ds_write_b64 v12, v[34:35] offset:18432
	ds_write_b64 v13, v[122:123] offset:45056
	ds_write_b64 v12, v[36:37] offset:20480
	ds_write_b64 v13, v[124:125] offset:43008
	ds_write_b64 v12, v[38:39] offset:22528
	ds_write_b64 v13, v[126:127] offset:40960
	ds_write_b64 v12, v[40:41] offset:24576
	ds_write_b64 v13, v[128:129] offset:38912
	ds_write_b64 v12, v[42:43] offset:26624
	ds_write_b64 v13, v[130:131] offset:36864
	ds_write_b64 v12, v[44:45] offset:28672
	ds_write_b64 v13, v[132:133] offset:34816
	ds_write_b64 v12, v[46:47] offset:30720
	ds_write_b64 v13, v[134:135] offset:32768

; DI float bf2f(u16 v) { return __uint_as_float(((unsigned)v) << 16); }
; DI float sconv3(const u16* row, int t, int n, float w0, float w1, float w2, float bias) {
;   float xm = (t > 0) ? bf2f(row[t - 1]) : 0.f, x0 = bf2f(row[t]), xp = (t + 1 < n) ? bf2f(row[t + 1]) : 0.f;
;   return w0 * xm + w1 * x0 + w2 * xp + bias;
; }
; DI void hyena_unit(KP p, int l, int c, char* smem) {
;     ...
;       __syncthreads();
; #pragma unroll 4
;       for (int jj = 0; jj < 16; ++jj) {
;         const int t = tid + 256 * jj;
;         float v0, v1;
;         if (o == 0) { v0 = sconv3(r0, t, 4096, vw0, vw1, vw2, vb); v1 = sconv3(r1, t, 4096, vw0, vw1, vw2, vb); }
;         else { v0 = bf2f(r0[t]); v1 = bf2f(r1[t]); }
;         buf[SW(t)] = mkf2(v0, v1);
;         buf[SW(t + 4096)] = mkf2(0.f, 0.f);
;       }
.LBB0_937:
	s_mul_i32 s82, s83, 0xc00
	s_add_i32 s28, s82, s86
	s_lshl_b32 s2, s83, 1
	s_ashr_i32 s29, s28, 31
	s_xor_b64 s[36:37], s[6:7], -1
	s_or_b32 s78, s2, 1
	s_lshl_b64 s[2:3], s[28:29], 13
	s_add_u32 s24, s80, s2
	s_mul_i32 s29, s78, 0x600
	s_addc_u32 s25, s76, s3
	s_add_i32 s6, s29, s86
	s_ashr_i32 s7, s6, 31
	s_lshl_b64 s[4:5], s[6:7], 13
	s_add_u32 s26, s80, s4
	s_addc_u32 s27, s76, s5
	s_add_i32 s4, s40, s82
	s_ashr_i32 s5, s4, 31
	s_lshl_b64 s[4:5], s[4:5], 13
	v_lshl_add_u64 v[2:3], v[70:71], 0, s[4:5]
	v_lshl_add_u64 v[4:5], v[70:71], 0, s[2:3]
	s_mov_b64 s[22:23], 0
	s_movk_i32 s2, 0x200
	s_barrier
	v_lshlrev_b32_e32 v6, 1, v66
	v_xor_b32_e32 v8, v66, v155
	v_add_u32_e32 v7, 0x1000, v6
	v_lshlrev_b32_e32 v8, 3, v8
	s_and_b64 vcc, exec, s[34:35]
	s_cbranch_vccnz .Lhy_inA_direct
	v_cmp_eq_u32_e64 s[8:9], 0, v66
	v_cmp_eq_u32_e32 vcc, 0xff, v66
	s_mov_b64 s[10:11], vcc
	global_load_ushort v18, v6, s[24:25] offset:-2
	global_load_ushort v16, v6, s[24:25] offset:0
	global_load_ushort v19, v6, s[24:25] offset:2
	global_load_ushort v20, v6, s[26:27] offset:-2
	global_load_ushort v17, v6, s[26:27] offset:0
	global_load_ushort v21, v6, s[26:27] offset:2
	global_load_ushort v24, v6, s[24:25] offset:510
	global_load_ushort v22, v6, s[24:25] offset:512
	global_load_ushort v25, v6, s[24:25] offset:514
	global_load_ushort v26, v6, s[26:27] offset:510
	global_load_ushort v23, v6, s[26:27] offset:512
	global_load_ushort v27, v6, s[26:27] offset:514
	global_load_ushort v30, v6, s[24:25] offset:1022
	global_load_ushort v28, v6, s[24:25] offset:1024
	global_load_ushort v31, v6, s[24:25] offset:1026
	global_load_ushort v32, v6, s[26:27] offset:1022
	global_load_ushort v29, v6, s[26:27] offset:1024
	global_load_ushort v33, v6, s[26:27] offset:1026
	global_load_ushort v36, v6, s[24:25] offset:1534
	global_load_ushort v34, v6, s[24:25] offset:1536
	global_load_ushort v37, v6, s[24:25] offset:1538
	global_load_ushort v38, v6, s[26:27] offset:1534
	global_load_ushort v35, v6, s[26:27] offset:1536
	global_load_ushort v39, v6, s[26:27] offset:1538
	global_load_ushort v42, v6, s[24:25] offset:2046
	global_load_ushort v40, v6, s[24:25] offset:2048
	global_load_ushort v43, v6, s[24:25] offset:2050
	global_load_ushort v44, v6, s[26:27] offset:2046
	global_load_ushort v41, v6, s[26:27] offset:2048
	global_load_ushort v45, v6, s[26:27] offset:2050
	global_load_ushort v48, v6, s[24:25] offset:2558
	global_load_ushort v46, v6, s[24:25] offset:2560
	global_load_ushort v49, v6, s[24:25] offset:2562
	global_load_ushort v50, v6, s[26:27] offset:2558
	global_load_ushort v47, v6, s[26:27] offset:2560
	global_load_ushort v51, v6, s[26:27] offset:2562
	global_load_ushort v54, v6, s[24:25] offset:3070
	global_load_ushort v52, v6, s[24:25] offset:3072
	global_load_ushort v55, v6, s[24:25] offset:3074
	global_load_ushort v56, v6, s[26:27] offset:3070
	global_load_ushort v53, v6, s[26:27] offset:3072
	global_load_ushort v57, v6, s[26:27] offset:3074
	global_load_ushort v60, v6, s[24:25] offset:3582
	global_load_ushort v58, v6, s[24:25] offset:3584
	global_load_ushort v61, v6, s[24:25] offset:3586
	global_load_ushort v62, v6, s[26:27] offset:3582
	global_load_ushort v59, v6, s[26:27] offset:3584
	global_load_ushort v63, v6, s[26:27] offset:3586
	s_waitcnt vmcnt(42)
	v_cndmask_b32_e64 v18, v18, 0, s[8:9]
	v_cndmask_b32_e64 v20, v20, 0, s[8:9]
	v_lshlrev_b32_e32 v16, 16, v16
	v_lshlrev_b32_e32 v17, 16, v17
	v_lshlrev_b32_e32 v18, 16, v18
	v_lshlrev_b32_e32 v19, 16, v19
	v_lshlrev_b32_e32 v20, 16, v20
	v_lshlrev_b32_e32 v21, 16, v21
	v_mul_f32_e32 v16, v197, v16
	v_mul_f32_e32 v17, v197, v17
	v_fmac_f32_e32 v16, v76, v18
	v_fmac_f32_e32 v17, v76, v20
	v_fmac_f32_e32 v16, v77, v19
	v_fmac_f32_e32 v17, v77, v21
	v_add_f32_e32 v16, v200, v16
	v_add_f32_e32 v17, v200, v17
	ds_write_b64 v8, v[16:17]
	ds_write_b64 v8, v[252:253] offset:32768
	s_waitcnt vmcnt(36)
	v_lshlrev_b32_e32 v22, 16, v22
	v_lshlrev_b32_e32 v23, 16, v23
	v_lshlrev_b32_e32 v24, 16, v24
	v_lshlrev_b32_e32 v25, 16, v25
	v_lshlrev_b32_e32 v26, 16, v26
	v_lshlrev_b32_e32 v27, 16, v27
	v_mul_f32_e32 v22, v197, v22
	v_mul_f32_e32 v23, v197, v23
	v_fmac_f32_e32 v22, v76, v24
	v_fmac_f32_e32 v23, v76, v26
	v_fmac_f32_e32 v22, v77, v25
	v_fmac_f32_e32 v23, v77, v27
	v_add_f32_e32 v22, v200, v22
	v_add_f32_e32 v23, v200, v23
	ds_write_b64 v8, v[22:23] offset:2048
	ds_write_b64 v8, v[252:253] offset:34816
	s_waitcnt vmcnt(30)
	v_lshlrev_b32_e32 v28, 16, v28
	v_lshlrev_b32_e32 v29, 16, v29
	v_lshlrev_b32_e32 v30, 16, v30
	v_lshlrev_b32_e32 v31, 16, v31
	v_lshlrev_b32_e32 v32, 16, v32
	v_lshlrev_b32_e32 v33, 16, v33
	v_mul_f32_e32 v28, v197, v28
	v_mul_f32_e32 v29, v197, v29
	v_fmac_f32_e32 v28, v76, v30
	v_fmac_f32_e32 v29, v76, v32
	v_fmac_f32_e32 v28, v77, v31
	v_fmac_f32_e32 v29, v77, v33
	v_add_f32_e32 v28, v200, v28
	v_add_f32_e32 v29, v200, v29
	ds_write_b64 v8, v[28:29] offset:4096
	ds_write_b64 v8, v[252:253] offset:36864
	s_waitcnt vmcnt(24)
	v_lshlrev_b32_e32 v34, 16, v34
	v_lshlrev_b32_e32 v35, 16, v35
	v_lshlrev_b32_e32 v36, 16, v36
	v_lshlrev_b32_e32 v37, 16, v37
	v_lshlrev_b32_e32 v38, 16, v38
	v_lshlrev_b32_e32 v39, 16, v39
	v_mul_f32_e32 v34, v197, v34
	v_mul_f32_e32 v35, v197, v35
	v_fmac_f32_e32 v34, v76, v36
	v_fmac_f32_e32 v35, v76, v38
	v_fmac_f32_e32 v34, v77, v37
	v_fmac_f32_e32 v35, v77, v39
	v_add_f32_e32 v34, v200, v34
	v_add_f32_e32 v35, v200, v35
	ds_write_b64 v8, v[34:35] offset:6144
	ds_write_b64 v8, v[252:253] offset:38912
	s_waitcnt vmcnt(18)
; DI float bf2f(u16 v) { return __uint_as_float(((unsigned)v) << 16); }
; DI float sconv3(const u16* row, int t, int n, float w0, float w1, float w2, float bias) {
;   float xm = (t > 0) ? bf2f(row[t - 1]) : 0.f, x0 = bf2f(row[t]), xp = (t + 1 < n) ? bf2f(row[t + 1]) : 0.f;
;   return w0 * xm + w1 * x0 + w2 * xp + bias;
; }
; DI void hyena_unit(KP p, int l, int c, char* smem) {
;     ...
;       __syncthreads();
; #pragma unroll 4
;       for (int jj = 0; jj < 16; ++jj) {
;         const int t = tid + 256 * jj;
;         float v0, v1;
;         if (o == 0) { v0 = sconv3(r0, t, 4096, vw0, vw1, vw2, vb); v1 = sconv3(r1, t, 4096, vw0, vw1, vw2, vb); }
;         else { v0 = bf2f(r0[t]); v1 = bf2f(r1[t]); }
;         buf[SW(t)] = mkf2(v0, v1);
;         buf[SW(t + 4096)] = mkf2(0.f, 0.f);
;       }
	v_lshlrev_b32_e32 v40, 16, v40
	v_lshlrev_b32_e32 v41, 16, v41
	v_lshlrev_b32_e32 v42, 16, v42
	v_lshlrev_b32_e32 v43, 16, v43
	v_lshlrev_b32_e32 v44, 16, v44
	v_lshlrev_b32_e32 v45, 16, v45
	v_mul_f32_e32 v40, v197, v40
	v_mul_f32_e32 v41, v197, v41
	v_fmac_f32_e32 v40, v76, v42
	v_fmac_f32_e32 v41, v76, v44
	v_fmac_f32_e32 v40, v77, v43
	v_fmac_f32_e32 v41, v77, v45
	v_add_f32_e32 v40, v200, v40
	v_add_f32_e32 v41, v200, v41
	ds_write_b64 v8, v[40:41] offset:8192
	ds_write_b64 v8, v[252:253] offset:40960
	s_waitcnt vmcnt(12)
	v_lshlrev_b32_e32 v46, 16, v46
	v_lshlrev_b32_e32 v47, 16, v47
	v_lshlrev_b32_e32 v48, 16, v48
	v_lshlrev_b32_e32 v49, 16, v49
	v_lshlrev_b32_e32 v50, 16, v50
	v_lshlrev_b32_e32 v51, 16, v51
	v_mul_f32_e32 v46, v197, v46
	v_mul_f32_e32 v47, v197, v47
	v_fmac_f32_e32 v46, v76, v48
	v_fmac_f32_e32 v47, v76, v50
	v_fmac_f32_e32 v46, v77, v49
	v_fmac_f32_e32 v47, v77, v51
	v_add_f32_e32 v46, v200, v46
	v_add_f32_e32 v47, v200, v47
	ds_write_b64 v8, v[46:47] offset:10240
	ds_write_b64 v8, v[252:253] offset:43008
	s_waitcnt vmcnt(6)
	v_lshlrev_b32_e32 v52, 16, v52
	v_lshlrev_b32_e32 v53, 16, v53
	v_lshlrev_b32_e32 v54, 16, v54
	v_lshlrev_b32_e32 v55, 16, v55
	v_lshlrev_b32_e32 v56, 16, v56
	v_lshlrev_b32_e32 v57, 16, v57
	v_mul_f32_e32 v52, v197, v52
	v_mul_f32_e32 v53, v197, v53
	v_fmac_f32_e32 v52, v76, v54
	v_fmac_f32_e32 v53, v76, v56
	v_fmac_f32_e32 v52, v77, v55
	v_fmac_f32_e32 v53, v77, v57
	v_add_f32_e32 v52, v200, v52
	v_add_f32_e32 v53, v200, v53
	ds_write_b64 v8, v[52:53] offset:12288
	ds_write_b64 v8, v[252:253] offset:45056
	s_waitcnt vmcnt(0)
	v_lshlrev_b32_e32 v58, 16, v58
	v_lshlrev_b32_e32 v59, 16, v59
	v_lshlrev_b32_e32 v60, 16, v60
	v_lshlrev_b32_e32 v61, 16, v61
	v_lshlrev_b32_e32 v62, 16, v62
	v_lshlrev_b32_e32 v63, 16, v63
	v_mul_f32_e32 v58, v197, v58
	v_mul_f32_e32 v59, v197, v59
	v_fmac_f32_e32 v58, v76, v60
	v_fmac_f32_e32 v59, v76, v62
	v_fmac_f32_e32 v58, v77, v61
	v_fmac_f32_e32 v59, v77, v63
	v_add_f32_e32 v58, v200, v58
	v_add_f32_e32 v59, v200, v59
	ds_write_b64 v8, v[58:59] offset:14336
	ds_write_b64 v8, v[252:253] offset:47104
	global_load_ushort v18, v7, s[24:25] offset:-2
	global_load_ushort v16, v7, s[24:25] offset:0
	global_load_ushort v19, v7, s[24:25] offset:2
	global_load_ushort v20, v7, s[26:27] offset:-2
	global_load_ushort v17, v7, s[26:27] offset:0
	global_load_ushort v21, v7, s[26:27] offset:2
	global_load_ushort v24, v7, s[24:25] offset:510
	global_load_ushort v22, v7, s[24:25] offset:512
	global_load_ushort v25, v7, s[24:25] offset:514
	global_load_ushort v26, v7, s[26:27] offset:510
	global_load_ushort v23, v7, s[26:27] offset:512
	global_load_ushort v27, v7, s[26:27] offset:514
	global_load_ushort v30, v7, s[24:25] offset:1022
	global_load_ushort v28, v7, s[24:25] offset:1024
	global_load_ushort v31, v7, s[24:25] offset:1026
	global_load_ushort v32, v7, s[26:27] offset:1022
	global_load_ushort v29, v7, s[26:27] offset:1024
	global_load_ushort v33, v7, s[26:27] offset:1026
	global_load_ushort v36, v7, s[24:25] offset:1534
	global_load_ushort v34, v7, s[24:25] offset:1536
	global_load_ushort v37, v7, s[24:25] offset:1538
	global_load_ushort v38, v7, s[26:27] offset:1534
	global_load_ushort v35, v7, s[26:27] offset:1536
	global_load_ushort v39, v7, s[26:27] offset:1538
	global_load_ushort v42, v7, s[24:25] offset:2046
	global_load_ushort v40, v7, s[24:25] offset:2048
	global_load_ushort v43, v7, s[24:25] offset:2050
	global_load_ushort v44, v7, s[26:27] offset:2046
	global_load_ushort v41, v7, s[26:27] offset:2048
	global_load_ushort v45, v7, s[26:27] offset:2050
	global_load_ushort v48, v7, s[24:25] offset:2558
	global_load_ushort v46, v7, s[24:25] offset:2560
	global_load_ushort v49, v7, s[24:25] offset:2562
	global_load_ushort v50, v7, s[26:27] offset:2558
	global_load_ushort v47, v7, s[26:27] offset:2560
	global_load_ushort v51, v7, s[26:27] offset:2562
	global_load_ushort v54, v7, s[24:25] offset:3070
	global_load_ushort v52, v7, s[24:25] offset:3072
	global_load_ushort v55, v7, s[24:25] offset:3074
	global_load_ushort v56, v7, s[26:27] offset:3070
	global_load_ushort v53, v7, s[26:27] offset:3072
	global_load_ushort v57, v7, s[26:27] offset:3074
	global_load_ushort v60, v7, s[24:25] offset:3582
	global_load_ushort v58, v7, s[24:25] offset:3584
	global_load_ushort v61, v7, s[24:25] offset:3586
	global_load_ushort v62, v7, s[26:27] offset:3582
	global_load_ushort v59, v7, s[26:27] offset:3584
	global_load_ushort v63, v7, s[26:27] offset:3586
	s_waitcnt vmcnt(42)
	v_lshlrev_b32_e32 v16, 16, v16
	v_lshlrev_b32_e32 v17, 16, v17
	v_lshlrev_b32_e32 v18, 16, v18
	v_lshlrev_b32_e32 v19, 16, v19
	v_lshlrev_b32_e32 v20, 16, v20
	v_lshlrev_b32_e32 v21, 16, v21
	v_mul_f32_e32 v16, v197, v16
	v_mul_f32_e32 v17, v197, v17
	v_fmac_f32_e32 v16, v76, v18
	v_fmac_f32_e32 v17, v76, v20
	v_fmac_f32_e32 v16, v77, v19
	v_fmac_f32_e32 v17, v77, v21
	v_add_f32_e32 v16, v200, v16
	v_add_f32_e32 v17, v200, v17
	ds_write_b64 v8, v[16:17] offset:16384
	ds_write_b64 v8, v[252:253] offset:49152
	s_waitcnt vmcnt(36)
	v_lshlrev_b32_e32 v22, 16, v22
	v_lshlrev_b32_e32 v23, 16, v23
	v_lshlrev_b32_e32 v24, 16, v24
	v_lshlrev_b32_e32 v25, 16, v25
	v_lshlrev_b32_e32 v26, 16, v26
	v_lshlrev_b32_e32 v27, 16, v27
	v_mul_f32_e32 v22, v197, v22
	v_mul_f32_e32 v23, v197, v23
	v_fmac_f32_e32 v22, v76, v24
	v_fmac_f32_e32 v23, v76, v26
	v_fmac_f32_e32 v22, v77, v25
	v_fmac_f32_e32 v23, v77, v27
	v_add_f32_e32 v22, v200, v22
	v_add_f32_e32 v23, v200, v23
	ds_write_b64 v8, v[22:23] offset:18432
	ds_write_b64 v8, v[252:253] offset:51200
	s_waitcnt vmcnt(30)
; DI float bf2f(u16 v) { return __uint_as_float(((unsigned)v) << 16); }
; DI float sconv3(const u16* row, int t, int n, float w0, float w1, float w2, float bias) {
;   float xm = (t > 0) ? bf2f(row[t - 1]) : 0.f, x0 = bf2f(row[t]), xp = (t + 1 < n) ? bf2f(row[t + 1]) : 0.f;
;   return w0 * xm + w1 * x0 + w2 * xp + bias;
; }
; DI void hyena_unit(KP p, int l, int c, char* smem) {
;     ...
;       __syncthreads();
; #pragma unroll 4
;       for (int jj = 0; jj < 16; ++jj) {
;         const int t = tid + 256 * jj;
;         float v0, v1;
;         if (o == 0) { v0 = sconv3(r0, t, 4096, vw0, vw1, vw2, vb); v1 = sconv3(r1, t, 4096, vw0, vw1, vw2, vb); }
;         else { v0 = bf2f(r0[t]); v1 = bf2f(r1[t]); }
;         buf[SW(t)] = mkf2(v0, v1);
;         buf[SW(t + 4096)] = mkf2(0.f, 0.f);
;       }
	v_lshlrev_b32_e32 v28, 16, v28
	v_lshlrev_b32_e32 v29, 16, v29
	v_lshlrev_b32_e32 v30, 16, v30
	v_lshlrev_b32_e32 v31, 16, v31
	v_lshlrev_b32_e32 v32, 16, v32
	v_lshlrev_b32_e32 v33, 16, v33
	v_mul_f32_e32 v28, v197, v28
	v_mul_f32_e32 v29, v197, v29
	v_fmac_f32_e32 v28, v76, v30
	v_fmac_f32_e32 v29, v76, v32
	v_fmac_f32_e32 v28, v77, v31
	v_fmac_f32_e32 v29, v77, v33
	v_add_f32_e32 v28, v200, v28
	v_add_f32_e32 v29, v200, v29
	ds_write_b64 v8, v[28:29] offset:20480
	ds_write_b64 v8, v[252:253] offset:53248
	s_waitcnt vmcnt(24)
	v_lshlrev_b32_e32 v34, 16, v34
	v_lshlrev_b32_e32 v35, 16, v35
	v_lshlrev_b32_e32 v36, 16, v36
	v_lshlrev_b32_e32 v37, 16, v37
	v_lshlrev_b32_e32 v38, 16, v38
	v_lshlrev_b32_e32 v39, 16, v39
	v_mul_f32_e32 v34, v197, v34
	v_mul_f32_e32 v35, v197, v35
	v_fmac_f32_e32 v34, v76, v36
	v_fmac_f32_e32 v35, v76, v38
	v_fmac_f32_e32 v34, v77, v37
	v_fmac_f32_e32 v35, v77, v39
	v_add_f32_e32 v34, v200, v34
	v_add_f32_e32 v35, v200, v35
	ds_write_b64 v8, v[34:35] offset:22528
	ds_write_b64 v8, v[252:253] offset:55296
	s_waitcnt vmcnt(18)
	v_lshlrev_b32_e32 v40, 16, v40
	v_lshlrev_b32_e32 v41, 16, v41
	v_lshlrev_b32_e32 v42, 16, v42
	v_lshlrev_b32_e32 v43, 16, v43
	v_lshlrev_b32_e32 v44, 16, v44
	v_lshlrev_b32_e32 v45, 16, v45
	v_mul_f32_e32 v40, v197, v40
	v_mul_f32_e32 v41, v197, v41
	v_fmac_f32_e32 v40, v76, v42
	v_fmac_f32_e32 v41, v76, v44
	v_fmac_f32_e32 v40, v77, v43
	v_fmac_f32_e32 v41, v77, v45
	v_add_f32_e32 v40, v200, v40
	v_add_f32_e32 v41, v200, v41
	ds_write_b64 v8, v[40:41] offset:24576
	ds_write_b64 v8, v[252:253] offset:57344
	s_waitcnt vmcnt(12)
	v_lshlrev_b32_e32 v46, 16, v46
	v_lshlrev_b32_e32 v47, 16, v47
	v_lshlrev_b32_e32 v48, 16, v48
	v_lshlrev_b32_e32 v49, 16, v49
	v_lshlrev_b32_e32 v50, 16, v50
	v_lshlrev_b32_e32 v51, 16, v51
	v_mul_f32_e32 v46, v197, v46
	v_mul_f32_e32 v47, v197, v47
	v_fmac_f32_e32 v46, v76, v48
	v_fmac_f32_e32 v47, v76, v50
	v_fmac_f32_e32 v46, v77, v49
	v_fmac_f32_e32 v47, v77, v51
	v_add_f32_e32 v46, v200, v46
	v_add_f32_e32 v47, v200, v47
	ds_write_b64 v8, v[46:47] offset:26624
	ds_write_b64 v8, v[252:253] offset:59392
	s_waitcnt vmcnt(6)
	v_lshlrev_b32_e32 v52, 16, v52
	v_lshlrev_b32_e32 v53, 16, v53
	v_lshlrev_b32_e32 v54, 16, v54
	v_lshlrev_b32_e32 v55, 16, v55
	v_lshlrev_b32_e32 v56, 16, v56
	v_lshlrev_b32_e32 v57, 16, v57
	v_mul_f32_e32 v52, v197, v52
	v_mul_f32_e32 v53, v197, v53
	v_fmac_f32_e32 v52, v76, v54
	v_fmac_f32_e32 v53, v76, v56
	v_fmac_f32_e32 v52, v77, v55
	v_fmac_f32_e32 v53, v77, v57
	v_add_f32_e32 v52, v200, v52
	v_add_f32_e32 v53, v200, v53
	ds_write_b64 v8, v[52:53] offset:28672
	ds_write_b64 v8, v[252:253] offset:61440
	s_waitcnt vmcnt(0)
	v_cndmask_b32_e64 v61, v61, 0, s[10:11]
	v_cndmask_b32_e64 v63, v63, 0, s[10:11]
	v_lshlrev_b32_e32 v58, 16, v58
	v_lshlrev_b32_e32 v59, 16, v59
	v_lshlrev_b32_e32 v60, 16, v60
	v_lshlrev_b32_e32 v61, 16, v61
	v_lshlrev_b32_e32 v62, 16, v62
	v_lshlrev_b32_e32 v63, 16, v63
	v_mul_f32_e32 v58, v197, v58
	v_mul_f32_e32 v59, v197, v59
	v_fmac_f32_e32 v58, v76, v60
	v_fmac_f32_e32 v59, v76, v62
	v_fmac_f32_e32 v58, v77, v61
	v_fmac_f32_e32 v59, v77, v63
	v_add_f32_e32 v58, v200, v58
	v_add_f32_e32 v59, v200, v59
	ds_write_b64 v8, v[58:59] offset:30720
	ds_write_b64 v8, v[252:253] offset:63488
	s_branch .Lhy_inA_done
; DI int tidx() { int t = __builtin_amdgcn_workitem_id_x(); asm volatile("" : "+v"(t)); return t; }
; DI float bf2f(u16 v) { return __uint_as_float(((unsigned)v) << 16); }
; DI void fft8192(f32x2* buf, const f32x2* __restrict__ tw) {
;   const int tid = tidx();
; #pragma unroll 2
;   for (int ls = 0; ls < 12; ls += 2) {
;     const int s = 1 << ls;
;     f32x2 a[8], b[8], c[8], d[8];
;     __syncthreads();
; #pragma unroll
;     for (int e = 0; e < 8; ++e) {
;       const int i = tid + 256 * e;
;       const int pi = SW(i);
;       a[e] = buf[pi]; b[e] = buf[pi + 2048]; c[e] = buf[pi + 4096]; d[e] = buf[pi + 6144];
; DI void hyena_unit(KP p, int l, int c, char* smem) {
;     ...
;       for (int jj = 0; jj < 16; ++jj) {
;         const int t = tid + 256 * jj;
;         float v0, v1;
;         if (o == 0) { v0 = sconv3(r0, t, 4096, vw0, vw1, vw2, vb); v1 = sconv3(r1, t, 4096, vw0, vw1, vw2, vb); }
;         else { v0 = bf2f(r0[t]); v1 = bf2f(r1[t]); }
;         buf[SW(t)] = mkf2(v0, v1);
;         buf[SW(t + 4096)] = mkf2(0.f, 0.f);
;       }
.Lhy_inA_direct:
	global_load_ushort v16, v6, s[24:25]
	global_load_ushort v17, v6, s[26:27]
	global_load_ushort v18, v6, s[24:25] offset:512
	global_load_ushort v19, v6, s[26:27] offset:512
	global_load_ushort v20, v6, s[24:25] offset:1024
	global_load_ushort v21, v6, s[26:27] offset:1024
	global_load_ushort v22, v6, s[24:25] offset:1536
	global_load_ushort v23, v6, s[26:27] offset:1536
	global_load_ushort v24, v6, s[24:25] offset:2048
	global_load_ushort v25, v6, s[26:27] offset:2048
	global_load_ushort v26, v6, s[24:25] offset:2560
	global_load_ushort v27, v6, s[26:27] offset:2560
	global_load_ushort v28, v6, s[24:25] offset:3072
	global_load_ushort v29, v6, s[26:27] offset:3072
	global_load_ushort v30, v6, s[24:25] offset:3584
	global_load_ushort v31, v6, s[26:27] offset:3584
	global_load_ushort v32, v7, s[24:25]
	global_load_ushort v33, v7, s[26:27]
	global_load_ushort v34, v7, s[24:25] offset:512
	global_load_ushort v35, v7, s[26:27] offset:512
	global_load_ushort v36, v7, s[24:25] offset:1024
	global_load_ushort v37, v7, s[26:27] offset:1024
	global_load_ushort v38, v7, s[24:25] offset:1536
	global_load_ushort v39, v7, s[26:27] offset:1536
	global_load_ushort v40, v7, s[24:25] offset:2048
	global_load_ushort v41, v7, s[26:27] offset:2048
	global_load_ushort v42, v7, s[24:25] offset:2560
	global_load_ushort v43, v7, s[26:27] offset:2560
	global_load_ushort v44, v7, s[24:25] offset:3072
	global_load_ushort v45, v7, s[26:27] offset:3072
	global_load_ushort v46, v7, s[24:25] offset:3584
	global_load_ushort v47, v7, s[26:27] offset:3584
	s_waitcnt vmcnt(30)
	v_lshlrev_b32_e32 v16, 16, v16
	v_lshlrev_b32_e32 v17, 16, v17
	ds_write_b64 v8, v[16:17]
	ds_write_b64 v8, v[252:253] offset:32768
	s_waitcnt vmcnt(28)
	v_lshlrev_b32_e32 v18, 16, v18
	v_lshlrev_b32_e32 v19, 16, v19
	ds_write_b64 v8, v[18:19] offset:2048
	ds_write_b64 v8, v[252:253] offset:34816
	s_waitcnt vmcnt(26)
	v_lshlrev_b32_e32 v20, 16, v20
	v_lshlrev_b32_e32 v21, 16, v21
	ds_write_b64 v8, v[20:21] offset:4096
	ds_write_b64 v8, v[252:253] offset:36864
	s_waitcnt vmcnt(24)
	v_lshlrev_b32_e32 v22, 16, v22
	v_lshlrev_b32_e32 v23, 16, v23
	ds_write_b64 v8, v[22:23] offset:6144
	ds_write_b64 v8, v[252:253] offset:38912
	s_waitcnt vmcnt(22)
	v_lshlrev_b32_e32 v24, 16, v24
	v_lshlrev_b32_e32 v25, 16, v25
	ds_write_b64 v8, v[24:25] offset:8192
	ds_write_b64 v8, v[252:253] offset:40960
	s_waitcnt vmcnt(20)
	v_lshlrev_b32_e32 v26, 16, v26
	v_lshlrev_b32_e32 v27, 16, v27
	ds_write_b64 v8, v[26:27] offset:10240
	ds_write_b64 v8, v[252:253] offset:43008
	s_waitcnt vmcnt(18)
	v_lshlrev_b32_e32 v28, 16, v28
	v_lshlrev_b32_e32 v29, 16, v29
	ds_write_b64 v8, v[28:29] offset:12288
	ds_write_b64 v8, v[252:253] offset:45056
	s_waitcnt vmcnt(16)
	v_lshlrev_b32_e32 v30, 16, v30
	v_lshlrev_b32_e32 v31, 16, v31
	ds_write_b64 v8, v[30:31] offset:14336
	ds_write_b64 v8, v[252:253] offset:47104
	s_waitcnt vmcnt(14)
	v_lshlrev_b32_e32 v32, 16, v32
	v_lshlrev_b32_e32 v33, 16, v33
	ds_write_b64 v8, v[32:33] offset:16384
	ds_write_b64 v8, v[252:253] offset:49152
	s_waitcnt vmcnt(12)
	v_lshlrev_b32_e32 v34, 16, v34
	v_lshlrev_b32_e32 v35, 16, v35
	ds_write_b64 v8, v[34:35] offset:18432
	ds_write_b64 v8, v[252:253] offset:51200
	s_waitcnt vmcnt(10)
	v_lshlrev_b32_e32 v36, 16, v36
	v_lshlrev_b32_e32 v37, 16, v37
	ds_write_b64 v8, v[36:37] offset:20480
	ds_write_b64 v8, v[252:253] offset:53248
	s_waitcnt vmcnt(8)
	v_lshlrev_b32_e32 v38, 16, v38
	v_lshlrev_b32_e32 v39, 16, v39
	ds_write_b64 v8, v[38:39] offset:22528
	ds_write_b64 v8, v[252:253] offset:55296
	s_waitcnt vmcnt(6)
	v_lshlrev_b32_e32 v40, 16, v40
	v_lshlrev_b32_e32 v41, 16, v41
	ds_write_b64 v8, v[40:41] offset:24576
	ds_write_b64 v8, v[252:253] offset:57344
	s_waitcnt vmcnt(4)
	v_lshlrev_b32_e32 v42, 16, v42
	v_lshlrev_b32_e32 v43, 16, v43
	ds_write_b64 v8, v[42:43] offset:26624
	ds_write_b64 v8, v[252:253] offset:59392
	s_waitcnt vmcnt(2)
	v_lshlrev_b32_e32 v44, 16, v44
	v_lshlrev_b32_e32 v45, 16, v45
	ds_write_b64 v8, v[44:45] offset:28672
	ds_write_b64 v8, v[252:253] offset:61440
	s_waitcnt vmcnt(0)
	v_lshlrev_b32_e32 v46, 16, v46
	v_lshlrev_b32_e32 v47, 16, v47
	ds_write_b64 v8, v[46:47] offset:30720
	ds_write_b64 v8, v[252:253] offset:63488
.Lhy_inA_done:
.LBB0_987:
	v_mov_b32_e32 v208, v0
	s_mov_b32 s7, 0
	v_bfe_i32 v2, v208, 5, 1
	v_bfe_i32 v3, v208, 6, 1
	v_and_b32_e32 v2, 5, v2
	v_and_b32_e32 v3, 26, v3
	v_bitop3_b32 v4, v3, v208, v2 bitop3:0x36
	v_add_u32_e32 v210, 0x100, v208
	v_lshlrev_b32_e32 v198, 3, v4
	v_bitop3_b32 v4, v3, v210, v2 bitop3:0x36
	v_add_u32_e32 v211, 0x200, v208
	v_lshlrev_b32_e32 v201, 3, v4
	v_bitop3_b32 v4, v3, v211, v2 bitop3:0x36
	v_add_u32_e32 v212, 0x300, v208
	v_lshlrev_b32_e32 v202, 3, v4
	v_bitop3_b32 v4, v3, v212, v2 bitop3:0x36
	v_add_u32_e32 v213, 0x400, v208
	v_lshlrev_b32_e32 v203, 3, v4
	v_bitop3_b32 v4, v3, v213, v2 bitop3:0x36
	v_add_u32_e32 v214, 0x500, v208
	v_lshlrev_b32_e32 v204, 3, v4
	v_bitop3_b32 v4, v3, v214, v2 bitop3:0x36
	v_add_u32_e32 v216, 0x600, v208
	v_add_u32_e32 v237, 0x700, v208
	v_or_b32_e32 v209, v3, v2
	v_lshlrev_b32_e32 v205, 3, v4
	v_bitop3_b32 v4, v3, v216, v2 bitop3:0x36
	v_bitop3_b32 v2, v3, v237, v2 bitop3:0x36
	v_lshlrev_b32_e32 v206, 3, v4
	v_lshlrev_b32_e32 v207, 3, v2
	v_lshlrev_b32_e32 v154, 2, v208
	v_lshlrev_b32_e32 v156, 2, v210
	v_lshlrev_b32_e32 v158, 2, v211
	v_lshlrev_b32_e32 v160, 2, v212
	v_lshlrev_b32_e32 v162, 2, v213
	v_lshlrev_b32_e32 v164, 2, v214
	v_lshlrev_b32_e32 v166, 2, v216
	v_lshlrev_b32_e32 v168, 2, v237

; DI f32x2 cmul(f32x2 a, f32x2 b) { return mkf2(a.x * b.x - a.y * b.y, a.x * b.y + a.y * b.x); }
; DI void fft8192(f32x2* buf, const f32x2* __restrict__ tw) {
;     ...
;   for (int ls = 0; ls < 12; ls += 2) {
;     const int s = 1 << ls;
;     f32x2 a[8], b[8], c[8], d[8];
;     __syncthreads();
; #pragma unroll
;     for (int e = 0; e < 8; ++e) {
;       const int i = tid + 256 * e;
;       const int pi = SW(i);
;       a[e] = buf[pi]; b[e] = buf[pi + 2048]; c[e] = buf[pi + 4096]; d[e] = buf[pi + 6144];
;     }
;     __syncthreads();
; #pragma unroll
;     for (int e = 0; e < 8; ++e) {
;       const int i = tid + 256 * e;
;       const int q = i & (s - 1);
;       const int ps = i - q;
;       const float rev = (float)ps * (1.f / 8192.f);
;       const f32x2 w1 = mkf2(__builtin_amdgcn_cosf(rev), -__builtin_amdgcn_sinf(rev));
;       const f32x2 w2 = cmul(w1, w1), w3 = cmul(w1, w2);
;       const f32x2 apc = mkf2(a[e].x + c[e].x, a[e].y + c[e].y), amc = mkf2(a[e].x - c[e].x, a[e].y - c[e].y);
;       const f32x2 bpd = mkf2(b[e].x + d[e].x, b[e].y + d[e].y), bmd = mkf2(b[e].x - d[e].x, b[e].y - d[e].y);
;       const int o = 4 * i - 3 * q;
;       buf[SW(o)] = mkf2(apc.x + bpd.x, apc.y + bpd.y);
;       buf[SW(o + s)] = cmul(w1, mkf2(amc.x + bmd.y, amc.y - bmd.x));
;       buf[SW(o + 2 * s)] = cmul(w2, mkf2(apc.x - bpd.x, apc.y - bpd.y));
;       buf[SW(o + 3 * s)] = cmul(w3, mkf2(amc.x - bmd.y, amc.y + bmd.x));
;     }
.LBB0_990:
	s_bfm_b32 s5, s7, 0
	v_and_b32_e32 v225, s5, v208
	v_sub_u32_e32 v220, v208, v225
	v_cvt_f32_i32_e32 v220, v220
	v_mad_u64_u32 v[226:227], s[8:9], v225, -3, v[154:155]
	v_bfe_i32 v225, v226, 5, 1
	v_mul_f32_e32 v221, 0x39000000, v220
	v_cos_f32_e32 v220, v221
	v_sin_f32_e32 v221, v221
	v_bfe_i32 v227, v226, 6, 1
	s_waitcnt lgkmcnt(0)
	s_barrier
	ds_read2st64_b64 v[42:45], v198 offset1:32
	ds_read2st64_b64 v[46:49], v198 offset0:64 offset1:96
	ds_read2st64_b64 v[50:53], v201 offset1:32
	ds_read2st64_b64 v[54:57], v201 offset0:64 offset1:96
	ds_read2st64_b64 v[58:61], v202 offset1:32
	ds_read2st64_b64 v[62:65], v202 offset0:64 offset1:96
	ds_read2st64_b64 v[34:37], v203 offset1:32
	ds_read2st64_b64 v[38:41], v203 offset0:64 offset1:96
	ds_read2st64_b64 v[26:29], v204 offset1:32
	ds_read2st64_b64 v[30:33], v204 offset0:64 offset1:96
	ds_read2st64_b64 v[18:21], v205 offset1:32
	ds_read2st64_b64 v[22:25], v205 offset0:64 offset1:96
	ds_read2st64_b64 v[10:13], v206 offset1:32
	ds_read2st64_b64 v[14:17], v206 offset0:64 offset1:96
	ds_read2st64_b64 v[2:5], v207 offset1:32
	ds_read2st64_b64 v[6:9], v207 offset0:64 offset1:96
	v_and_b32_e32 v225, 5, v225
	v_and_b32_e32 v227, 26, v227
	s_waitcnt lgkmcnt(14)
	v_pk_add_f32 v[230:231], v[42:43], v[46:47]
	v_pk_add_f32 v[232:233], v[44:45], v[48:49]
	v_bitop3_b32 v225, v225, v226, v227 bitop3:0x36
	v_pk_add_f32 v[42:43], v[42:43], v[46:47] neg_lo:[0,1] neg_hi:[0,1]
	v_pk_add_f32 v[44:45], v[44:45], v[48:49] neg_lo:[0,1] neg_hi:[0,1]
	v_pk_add_f32 v[238:239], v[230:231], v[232:233]
	v_lshlrev_b32_e32 v225, 3, v225
	v_pk_add_f32 v[46:47], v[42:43], v[44:45] op_sel:[0,1] op_sel_hi:[1,0]
	v_pk_add_f32 v[42:43], v[42:43], v[44:45] op_sel:[0,1] op_sel_hi:[1,0] neg_lo:[0,1] neg_hi:[0,1]
	s_waitcnt lgkmcnt(0)
	s_barrier
	ds_write_b64 v225, v[238:239]
	v_mov_b32_e32 v48, v221
	v_pk_mov_b32 v[238:239], v[42:43], v[46:47] op_sel:[1,0]
	v_mov_b32_e32 v44, v46
	v_mov_b32_e32 v45, v43
	v_pk_mul_f32 v[238:239], v[48:49], v[238:239] op_sel_hi:[0,1]
	s_lshl_b32 s4, 1, s7
	v_pk_fma_f32 v[44:45], v[220:221], v[44:45], v[238:239] op_sel_hi:[0,1,1] neg_lo:[0,0,1] neg_hi:[0,0,1]
	v_pk_fma_f32 v[240:241], v[220:221], v[46:47], v[238:239]
	v_add_u32_e32 v44, s4, v226
	v_mov_b32_e32 v241, v45
	v_bfe_i32 v45, v44, 5, 1
	v_bfe_i32 v49, v44, 6, 1
	v_and_b32_e32 v45, 5, v45
	v_and_b32_e32 v49, 26, v49
	v_bitop3_b32 v44, v45, v44, v49 bitop3:0x36
	v_mul_f32_e64 v224, v220, -v221
	v_lshlrev_b32_e32 v44, 3, v44
	v_mul_f32_e32 v222, v221, v221
	v_add_f32_e32 v224, v224, v224
	ds_write_b64 v44, v[240:241]
	v_pk_add_f32 v[44:45], v[230:231], v[232:233] neg_lo:[0,1] neg_hi:[0,1]
	v_pk_fma_f32 v[222:223], v[220:221], v[220:221], v[222:223] op_sel_hi:[1,1,0] neg_lo:[0,0,1] neg_hi:[0,0,1]
	v_pk_mul_f32 v[230:231], v[224:225], v[44:45] op_sel:[0,1] op_sel_hi:[0,0]
	s_lshl_b32 s3, 2, s7
	v_pk_fma_f32 v[232:233], v[222:223], v[44:45], v[230:231] neg_lo:[0,0,1] neg_hi:[0,0,1]
	v_pk_fma_f32 v[44:45], v[222:223], v[44:45], v[230:231] op_sel_hi:[0,1,1]
	v_add_u32_e32 v44, s3, v226
	v_mov_b32_e32 v233, v45
	v_bfe_i32 v45, v44, 5, 1
	v_bfe_i32 v49, v44, 6, 1
	v_and_b32_e32 v45, 5, v45
	v_and_b32_e32 v49, 26, v49
	v_bitop3_b32 v44, v45, v44, v49 bitop3:0x36
	v_lshlrev_b32_e32 v44, 3, v44
	v_mov_b32_e32 v223, v224
	ds_write_b64 v44, v[232:233]
	v_pk_mul_f32 v[44:45], v[48:49], v[222:223] op_sel:[0,1] op_sel_hi:[0,0]
	v_pk_fma_f32 v[48:49], v[220:221], v[222:223], v[44:45] op_sel_hi:[0,1,1]
	v_pk_fma_f32 v[44:45], v[220:221], v[222:223], v[44:45] op_sel_hi:[0,1,1] neg_lo:[0,0,1] neg_hi:[0,0,1]
	v_mov_b32_e32 v221, v45
	v_pk_mov_b32 v[44:45], v[44:45], v[48:49] op_sel:[1,0]
	v_mov_b32_e32 v220, v48
	v_pk_mul_f32 v[44:45], v[46:47], v[44:45] op_sel:[1,0]
	s_lshl_b32 s2, 3, s7
	v_pk_fma_f32 v[46:47], v[42:43], v[48:49], v[44:45] neg_lo:[0,0,1] neg_hi:[0,0,1]
	v_pk_fma_f32 v[42:43], v[42:43], v[220:221], v[44:45] op_sel_hi:[0,1,1]
	v_add_u32_e32 v42, s2, v226
	v_mov_b32_e32 v47, v43
	v_bfe_i32 v43, v42, 5, 1
	v_bfe_i32 v44, v42, 6, 1
	v_and_b32_e32 v43, 5, v43
	v_and_b32_e32 v44, 26, v44
	v_bitop3_b32 v42, v43, v42, v44 bitop3:0x36
	v_lshlrev_b32_e32 v42, 3, v42
	v_and_b32_e32 v224, s5, v210
	ds_write_b64 v42, v[46:47]
	v_sub_u32_e32 v42, v210, v224
	v_cvt_f32_i32_e32 v42, v42
	v_pk_add_f32 v[226:227], v[52:53], v[56:57]
	v_pk_add_f32 v[52:53], v[52:53], v[56:57] neg_lo:[0,1] neg_hi:[0,1]
	v_mul_f32_e32 v43, 0x39000000, v42
	v_cos_f32_e32 v42, v43
	v_sin_f32_e32 v43, v43
	v_mov_b32_e32 v223, v42
	v_pk_mul_f32 v[44:45], v[42:43], v[42:43]
	v_mul_f32_e64 v47, v42, -v43
	v_mov_b32_e32 v46, v44
	v_mov_b32_e32 v44, v45
	v_mov_b32_e32 v45, v47
	v_pk_add_f32 v[48:49], v[46:47], v[44:45] neg_lo:[0,1] neg_hi:[0,1]
	v_pk_add_f32 v[44:45], v[46:47], v[44:45]
	v_mov_b32_e32 v46, v48
	v_mov_b32_e32 v47, v45
	v_mov_b32_e32 v222, v43
	v_pk_mul_f32 v[220:221], v[42:43], v[46:47]
	v_pk_mul_f32 v[46:47], v[222:223], v[46:47]
	v_mad_u64_u32 v[222:223], s[8:9], v224, -3, v[156:157]
	v_bfe_i32 v223, v222, 5, 1
	v_bfe_i32 v232, v222, 6, 1
	v_and_b32_e32 v223, 5, v223
	v_and_b32_e32 v232, 26, v232
	v_pk_add_f32 v[224:225], v[50:51], v[54:55]
	v_bitop3_b32 v223, v223, v222, v232 bitop3:0x36
	v_pk_add_f32 v[50:51], v[50:51], v[54:55] neg_lo:[0,1] neg_hi:[0,1]
	v_pk_add_f32 v[230:231], v[224:225], v[226:227]
	v_lshlrev_b32_e32 v223, 3, v223
	v_pk_add_f32 v[54:55], v[50:51], v[52:53] op_sel:[0,1] op_sel_hi:[1,0]
	v_pk_add_f32 v[50:51], v[50:51], v[52:53] op_sel:[0,1] op_sel_hi:[1,0] neg_lo:[0,1] neg_hi:[0,1]
	ds_write_b64 v223, v[230:231]
	v_mov_b32_e32 v56, v43
	v_pk_mov_b32 v[230:231], v[50:51], v[54:55] op_sel:[1,0]
	v_mov_b32_e32 v52, v54
	v_mov_b32_e32 v53, v51
; DI f32x2 cmul(f32x2 a, f32x2 b) { return mkf2(a.x * b.x - a.y * b.y, a.x * b.y + a.y * b.x); }
; DI void fft8192(f32x2* buf, const f32x2* __restrict__ tw) {
;     ...
;   for (int ls = 0; ls < 12; ls += 2) {
;     const int s = 1 << ls;
;     f32x2 a[8], b[8], c[8], d[8];
;     __syncthreads();
; #pragma unroll
;     for (int e = 0; e < 8; ++e) {
;       const int i = tid + 256 * e;
;       const int pi = SW(i);
;       a[e] = buf[pi]; b[e] = buf[pi + 2048]; c[e] = buf[pi + 4096]; d[e] = buf[pi + 6144];
;     }
;     __syncthreads();
; #pragma unroll
;     for (int e = 0; e < 8; ++e) {
;       const int i = tid + 256 * e;
;       const int q = i & (s - 1);
;       const int ps = i - q;
;       const float rev = (float)ps * (1.f / 8192.f);
;       const f32x2 w1 = mkf2(__builtin_amdgcn_cosf(rev), -__builtin_amdgcn_sinf(rev));
;       const f32x2 w2 = cmul(w1, w1), w3 = cmul(w1, w2);
;       const f32x2 apc = mkf2(a[e].x + c[e].x, a[e].y + c[e].y), amc = mkf2(a[e].x - c[e].x, a[e].y - c[e].y);
;       const f32x2 bpd = mkf2(b[e].x + d[e].x, b[e].y + d[e].y), bmd = mkf2(b[e].x - d[e].x, b[e].y - d[e].y);
;       const int o = 4 * i - 3 * q;
;       buf[SW(o)] = mkf2(apc.x + bpd.x, apc.y + bpd.y);
;       buf[SW(o + s)] = cmul(w1, mkf2(amc.x + bmd.y, amc.y - bmd.x));
;       buf[SW(o + 2 * s)] = cmul(w2, mkf2(apc.x - bpd.x, apc.y - bpd.y));
;       buf[SW(o + 3 * s)] = cmul(w3, mkf2(amc.x - bmd.y, amc.y + bmd.x));
;     }
	v_pk_mul_f32 v[56:57], v[56:57], v[230:231] op_sel_hi:[0,1]
	v_pk_fma_f32 v[230:231], v[42:43], v[54:55], v[56:57]
	v_pk_fma_f32 v[42:43], v[42:43], v[52:53], v[56:57] op_sel_hi:[0,1,1] neg_lo:[0,0,1] neg_hi:[0,0,1]
	v_add_u32_e32 v42, s4, v222
	v_mov_b32_e32 v231, v43
	v_bfe_i32 v43, v42, 5, 1
	v_bfe_i32 v52, v42, 6, 1
	v_and_b32_e32 v43, 5, v43
	v_and_b32_e32 v52, 26, v52
	v_bitop3_b32 v42, v43, v42, v52 bitop3:0x36
	v_lshlrev_b32_e32 v42, 3, v42
	ds_write_b64 v42, v[230:231]
	v_pk_add_f32 v[42:43], v[224:225], v[226:227] neg_lo:[0,1] neg_hi:[0,1]
	v_pk_add_f32 v[46:47], v[46:47], v[46:47] op_sel:[1,0] op_sel_hi:[1,0] neg_lo:[0,1] neg_hi:[0,1]
	v_pk_mul_f32 v[44:45], v[44:45], v[42:43] op_sel:[1,1] op_sel_hi:[1,0]
	v_pk_add_f32 v[56:57], v[60:61], v[64:65]
	v_pk_fma_f32 v[52:53], v[48:49], v[42:43], v[44:45] neg_lo:[0,0,1] neg_hi:[0,0,1]
	v_pk_fma_f32 v[42:43], v[48:49], v[42:43], v[44:45] op_sel_hi:[0,1,1]
	v_add_u32_e32 v42, s3, v222
	v_mov_b32_e32 v53, v43
	v_bfe_i32 v43, v42, 5, 1
	v_bfe_i32 v44, v42, 6, 1
	v_and_b32_e32 v43, 5, v43
	v_and_b32_e32 v44, 26, v44
	v_bitop3_b32 v42, v43, v42, v44 bitop3:0x36
	v_lshlrev_b32_e32 v42, 3, v42
	v_pk_mov_b32 v[48:49], v[54:55], v[50:51] op_sel:[1,0]
	ds_write_b64 v42, v[52:53]
	v_mov_b32_e32 v42, v50
	v_mov_b32_e32 v43, v55
	v_pk_add_f32 v[44:45], v[220:221], v[220:221] op_sel:[0,1] op_sel_hi:[0,1]
	v_pk_mul_f32 v[46:47], v[46:47], v[48:49]
	v_and_b32_e32 v54, s5, v211
	v_pk_fma_f32 v[42:43], v[44:45], v[42:43], v[46:47]
	v_pk_fma_f32 v[48:49], v[44:45], v[50:51], v[46:47] neg_lo:[0,0,1] neg_hi:[0,0,1]
	v_add_u32_e32 v42, s2, v222
	v_mov_b32_e32 v49, v43
	v_bfe_i32 v43, v42, 5, 1
	v_bfe_i32 v44, v42, 6, 1
	v_and_b32_e32 v43, 5, v43
	v_and_b32_e32 v44, 26, v44
	v_bitop3_b32 v42, v43, v42, v44 bitop3:0x36
	v_lshlrev_b32_e32 v42, 3, v42
	ds_write_b64 v42, v[48:49]
	v_sub_u32_e32 v42, v211, v54
	v_cvt_f32_i32_e32 v42, v42
	v_pk_add_f32 v[60:61], v[60:61], v[64:65] neg_lo:[0,1] neg_hi:[0,1]
	v_mul_f32_e32 v43, 0x39000000, v42
	v_cos_f32_e32 v42, v43
	v_sin_f32_e32 v43, v43
	v_mov_b32_e32 v53, v42
	v_pk_mul_f32 v[44:45], v[42:43], v[42:43]
	v_mul_f32_e64 v47, v42, -v43
	v_mov_b32_e32 v46, v44
	v_mov_b32_e32 v44, v45
	v_mov_b32_e32 v45, v47
	v_pk_add_f32 v[48:49], v[46:47], v[44:45] neg_lo:[0,1] neg_hi:[0,1]
	v_pk_add_f32 v[44:45], v[46:47], v[44:45]
	v_mov_b32_e32 v46, v48
	v_mov_b32_e32 v47, v45
	v_mov_b32_e32 v52, v43
	v_pk_mul_f32 v[50:51], v[42:43], v[46:47]
	v_pk_mul_f32 v[46:47], v[52:53], v[46:47]
	v_mad_u64_u32 v[52:53], s[8:9], v54, -3, v[158:159]
	v_bfe_i32 v53, v52, 5, 1
	v_bfe_i32 v222, v52, 6, 1
	v_and_b32_e32 v53, 5, v53
	v_and_b32_e32 v222, 26, v222
	v_pk_add_f32 v[54:55], v[58:59], v[62:63]
	v_bitop3_b32 v53, v53, v52, v222 bitop3:0x36
	v_pk_add_f32 v[58:59], v[58:59], v[62:63] neg_lo:[0,1] neg_hi:[0,1]
	v_pk_add_f32 v[220:221], v[54:55], v[56:57]
	v_lshlrev_b32_e32 v53, 3, v53
	v_pk_add_f32 v[62:63], v[58:59], v[60:61] op_sel:[0,1] op_sel_hi:[1,0]
	v_pk_add_f32 v[58:59], v[58:59], v[60:61] op_sel:[0,1] op_sel_hi:[1,0] neg_lo:[0,1] neg_hi:[0,1]
	ds_write_b64 v53, v[220:221]
	v_mov_b32_e32 v64, v43
	v_pk_mov_b32 v[220:221], v[58:59], v[62:63] op_sel:[1,0]
	v_mov_b32_e32 v60, v62
	v_mov_b32_e32 v61, v59
	v_pk_mul_f32 v[64:65], v[64:65], v[220:221] op_sel_hi:[0,1]
	v_pk_fma_f32 v[220:221], v[42:43], v[62:63], v[64:65]
	v_pk_fma_f32 v[42:43], v[42:43], v[60:61], v[64:65] op_sel_hi:[0,1,1] neg_lo:[0,0,1] neg_hi:[0,0,1]
	v_add_u32_e32 v42, s4, v52
	v_mov_b32_e32 v221, v43
	v_bfe_i32 v43, v42, 5, 1
	v_bfe_i32 v53, v42, 6, 1
	v_and_b32_e32 v43, 5, v43
	v_and_b32_e32 v53, 26, v53
	v_bitop3_b32 v42, v43, v42, v53 bitop3:0x36
	v_lshlrev_b32_e32 v42, 3, v42
	ds_write_b64 v42, v[220:221]
	v_pk_add_f32 v[42:43], v[54:55], v[56:57] neg_lo:[0,1] neg_hi:[0,1]
	v_pk_add_f32 v[46:47], v[46:47], v[46:47] op_sel:[1,0] op_sel_hi:[1,0] neg_lo:[0,1] neg_hi:[0,1]
	v_pk_mul_f32 v[44:45], v[44:45], v[42:43] op_sel:[1,1] op_sel_hi:[1,0]
	v_pk_add_f32 v[56:57], v[36:37], v[40:41]
	v_pk_fma_f32 v[54:55], v[48:49], v[42:43], v[44:45] neg_lo:[0,0,1] neg_hi:[0,0,1]
	v_pk_fma_f32 v[42:43], v[48:49], v[42:43], v[44:45] op_sel_hi:[0,1,1]
	v_add_u32_e32 v42, s3, v52
	v_mov_b32_e32 v55, v43
	v_bfe_i32 v43, v42, 5, 1
	v_bfe_i32 v44, v42, 6, 1
	v_and_b32_e32 v43, 5, v43
	v_and_b32_e32 v44, 26, v44
	v_bitop3_b32 v42, v43, v42, v44 bitop3:0x36
	v_lshlrev_b32_e32 v42, 3, v42
	v_pk_mov_b32 v[48:49], v[62:63], v[58:59] op_sel:[1,0]
	ds_write_b64 v42, v[54:55]
	v_mov_b32_e32 v42, v58
	v_mov_b32_e32 v43, v63
	v_pk_add_f32 v[44:45], v[50:51], v[50:51] op_sel:[0,1] op_sel_hi:[0,1]
	v_pk_mul_f32 v[46:47], v[46:47], v[48:49]
	v_and_b32_e32 v54, s5, v212
	v_pk_fma_f32 v[42:43], v[44:45], v[42:43], v[46:47]
	v_pk_fma_f32 v[48:49], v[44:45], v[58:59], v[46:47] neg_lo:[0,0,1] neg_hi:[0,0,1]
	v_add_u32_e32 v42, s2, v52
	v_mov_b32_e32 v49, v43
	v_bfe_i32 v43, v42, 5, 1
	v_bfe_i32 v44, v42, 6, 1
	v_and_b32_e32 v43, 5, v43
	v_and_b32_e32 v44, 26, v44
	v_bitop3_b32 v42, v43, v42, v44 bitop3:0x36
	v_lshlrev_b32_e32 v42, 3, v42
	ds_write_b64 v42, v[48:49]
	v_sub_u32_e32 v42, v212, v54
	v_cvt_f32_i32_e32 v42, v42
	v_pk_add_f32 v[36:37], v[36:37], v[40:41] neg_lo:[0,1] neg_hi:[0,1]
	v_mul_f32_e32 v43, 0x39000000, v42
	v_cos_f32_e32 v42, v43
	v_sin_f32_e32 v43, v43
	v_mov_b32_e32 v53, v42
	v_pk_mul_f32 v[44:45], v[42:43], v[42:43]
	v_mul_f32_e64 v47, v42, -v43
	v_mov_b32_e32 v46, v44
	v_mov_b32_e32 v44, v45
	v_mov_b32_e32 v45, v47
	v_pk_add_f32 v[48:49], v[46:47], v[44:45] neg_lo:[0,1] neg_hi:[0,1]
	v_pk_add_f32 v[44:45], v[46:47], v[44:45]
	v_mov_b32_e32 v46, v48
	v_mov_b32_e32 v47, v45
	v_mov_b32_e32 v52, v43
	v_pk_mul_f32 v[50:51], v[42:43], v[46:47]
; DI f32x2 cmul(f32x2 a, f32x2 b) { return mkf2(a.x * b.x - a.y * b.y, a.x * b.y + a.y * b.x); }
; DI void fft8192(f32x2* buf, const f32x2* __restrict__ tw) {
;     ...
;   for (int ls = 0; ls < 12; ls += 2) {
;     const int s = 1 << ls;
;     f32x2 a[8], b[8], c[8], d[8];
;     __syncthreads();
; #pragma unroll
;     for (int e = 0; e < 8; ++e) {
;       const int i = tid + 256 * e;
;       const int pi = SW(i);
;       a[e] = buf[pi]; b[e] = buf[pi + 2048]; c[e] = buf[pi + 4096]; d[e] = buf[pi + 6144];
;     }
;     __syncthreads();
; #pragma unroll
;     for (int e = 0; e < 8; ++e) {
;       const int i = tid + 256 * e;
;       const int q = i & (s - 1);
;       const int ps = i - q;
;       const float rev = (float)ps * (1.f / 8192.f);
;       const f32x2 w1 = mkf2(__builtin_amdgcn_cosf(rev), -__builtin_amdgcn_sinf(rev));
;       const f32x2 w2 = cmul(w1, w1), w3 = cmul(w1, w2);
;       const f32x2 apc = mkf2(a[e].x + c[e].x, a[e].y + c[e].y), amc = mkf2(a[e].x - c[e].x, a[e].y - c[e].y);
;       const f32x2 bpd = mkf2(b[e].x + d[e].x, b[e].y + d[e].y), bmd = mkf2(b[e].x - d[e].x, b[e].y - d[e].y);
;       const int o = 4 * i - 3 * q;
;       buf[SW(o)] = mkf2(apc.x + bpd.x, apc.y + bpd.y);
;       buf[SW(o + s)] = cmul(w1, mkf2(amc.x + bmd.y, amc.y - bmd.x));
;       buf[SW(o + 2 * s)] = cmul(w2, mkf2(apc.x - bpd.x, apc.y - bpd.y));
;       buf[SW(o + 3 * s)] = cmul(w3, mkf2(amc.x - bmd.y, amc.y + bmd.x));
;     }
	v_pk_mul_f32 v[46:47], v[52:53], v[46:47]
	v_mad_u64_u32 v[52:53], s[8:9], v54, -3, v[160:161]
	v_bfe_i32 v53, v52, 5, 1
	v_bfe_i32 v60, v52, 6, 1
	v_and_b32_e32 v53, 5, v53
	v_and_b32_e32 v60, 26, v60
	v_pk_add_f32 v[54:55], v[34:35], v[38:39]
	v_bitop3_b32 v53, v53, v52, v60 bitop3:0x36
	v_pk_add_f32 v[34:35], v[34:35], v[38:39] neg_lo:[0,1] neg_hi:[0,1]
	v_pk_add_f32 v[58:59], v[54:55], v[56:57]
	v_lshlrev_b32_e32 v53, 3, v53
	v_pk_add_f32 v[38:39], v[34:35], v[36:37] op_sel:[0,1] op_sel_hi:[1,0]
	v_pk_add_f32 v[34:35], v[34:35], v[36:37] op_sel:[0,1] op_sel_hi:[1,0] neg_lo:[0,1] neg_hi:[0,1]
	ds_write_b64 v53, v[58:59]
	v_mov_b32_e32 v40, v43
	v_pk_mov_b32 v[58:59], v[34:35], v[38:39] op_sel:[1,0]
	v_mov_b32_e32 v36, v38
	v_mov_b32_e32 v37, v35
	v_pk_mul_f32 v[40:41], v[40:41], v[58:59] op_sel_hi:[0,1]
	v_pk_fma_f32 v[36:37], v[42:43], v[36:37], v[40:41] op_sel_hi:[0,1,1] neg_lo:[0,0,1] neg_hi:[0,0,1]
	v_pk_fma_f32 v[58:59], v[42:43], v[38:39], v[40:41]
	v_add_u32_e32 v36, s4, v52
	v_mov_b32_e32 v59, v37
	v_bfe_i32 v37, v36, 5, 1
	v_bfe_i32 v40, v36, 6, 1
	v_and_b32_e32 v37, 5, v37
	v_and_b32_e32 v40, 26, v40
	v_bitop3_b32 v36, v37, v36, v40 bitop3:0x36
	v_lshlrev_b32_e32 v36, 3, v36
	ds_write_b64 v36, v[58:59]
	v_pk_add_f32 v[36:37], v[54:55], v[56:57] neg_lo:[0,1] neg_hi:[0,1]
	s_nop 0
	v_pk_mul_f32 v[40:41], v[44:45], v[36:37] op_sel:[1,1] op_sel_hi:[1,0]
	s_nop 0
	v_pk_fma_f32 v[42:43], v[48:49], v[36:37], v[40:41] neg_lo:[0,0,1] neg_hi:[0,0,1]
	v_pk_fma_f32 v[36:37], v[48:49], v[36:37], v[40:41] op_sel_hi:[0,1,1]
	v_add_u32_e32 v36, s3, v52
	v_mov_b32_e32 v43, v37
	v_bfe_i32 v37, v36, 5, 1
	v_bfe_i32 v40, v36, 6, 1
	v_and_b32_e32 v37, 5, v37
	v_and_b32_e32 v40, 26, v40
	v_bitop3_b32 v36, v37, v36, v40 bitop3:0x36
	v_lshlrev_b32_e32 v36, 3, v36
	ds_write_b64 v36, v[42:43]
	v_mov_b32_e32 v37, v39
	v_pk_add_f32 v[42:43], v[46:47], v[46:47] op_sel:[1,0] op_sel_hi:[1,0] neg_lo:[0,1] neg_hi:[0,1]
	v_pk_mov_b32 v[38:39], v[38:39], v[34:35] op_sel:[1,0]
	v_mov_b32_e32 v36, v34
	v_pk_add_f32 v[40:41], v[50:51], v[50:51] op_sel:[0,1] op_sel_hi:[0,1]
	v_pk_mul_f32 v[38:39], v[42:43], v[38:39]
	v_and_b32_e32 v46, s5, v213
	v_pk_fma_f32 v[36:37], v[40:41], v[36:37], v[38:39]
	v_pk_fma_f32 v[34:35], v[40:41], v[34:35], v[38:39] neg_lo:[0,0,1] neg_hi:[0,0,1]
	v_add_u32_e32 v36, s2, v52
	v_mov_b32_e32 v35, v37
	v_bfe_i32 v37, v36, 5, 1
	v_bfe_i32 v38, v36, 6, 1
	v_and_b32_e32 v37, 5, v37
	v_and_b32_e32 v38, 26, v38
	v_bitop3_b32 v36, v37, v36, v38 bitop3:0x36
	v_lshlrev_b32_e32 v36, 3, v36
	ds_write_b64 v36, v[34:35]
	v_sub_u32_e32 v34, v213, v46
	v_cvt_f32_i32_e32 v34, v34
	v_pk_add_f32 v[48:49], v[28:29], v[32:33]
	v_pk_add_f32 v[28:29], v[28:29], v[32:33] neg_lo:[0,1] neg_hi:[0,1]
	v_mul_f32_e32 v35, 0x39000000, v34
	v_cos_f32_e32 v34, v35
	v_sin_f32_e32 v35, v35
	v_mov_b32_e32 v45, v34
	v_pk_mul_f32 v[36:37], v[34:35], v[34:35]
	v_mul_f32_e64 v39, v34, -v35
	v_mov_b32_e32 v38, v36
	v_mov_b32_e32 v36, v37
	v_mov_b32_e32 v37, v39
	v_pk_add_f32 v[40:41], v[38:39], v[36:37] neg_lo:[0,1] neg_hi:[0,1]
	v_pk_add_f32 v[36:37], v[38:39], v[36:37]
	v_mov_b32_e32 v38, v40
	v_mov_b32_e32 v39, v37
	v_mov_b32_e32 v44, v35
	v_pk_mul_f32 v[42:43], v[34:35], v[38:39]
	v_pk_mul_f32 v[38:39], v[44:45], v[38:39]
	v_mad_u64_u32 v[44:45], s[8:9], v46, -3, v[162:163]
	v_bfe_i32 v45, v44, 5, 1
	v_bfe_i32 v52, v44, 6, 1
	v_and_b32_e32 v45, 5, v45
	v_and_b32_e32 v52, 26, v52
	v_pk_add_f32 v[46:47], v[26:27], v[30:31]
	v_bitop3_b32 v45, v45, v44, v52 bitop3:0x36
	v_pk_add_f32 v[26:27], v[26:27], v[30:31] neg_lo:[0,1] neg_hi:[0,1]
	v_pk_add_f32 v[50:51], v[46:47], v[48:49]
	v_lshlrev_b32_e32 v45, 3, v45
	v_pk_add_f32 v[30:31], v[26:27], v[28:29] op_sel:[0,1] op_sel_hi:[1,0]
	v_pk_add_f32 v[26:27], v[26:27], v[28:29] op_sel:[0,1] op_sel_hi:[1,0] neg_lo:[0,1] neg_hi:[0,1]
	ds_write_b64 v45, v[50:51]
	v_mov_b32_e32 v32, v35
	v_pk_mov_b32 v[50:51], v[26:27], v[30:31] op_sel:[1,0]
	v_mov_b32_e32 v28, v30
	v_mov_b32_e32 v29, v27
	v_pk_mul_f32 v[32:33], v[32:33], v[50:51] op_sel_hi:[0,1]
	v_pk_fma_f32 v[28:29], v[34:35], v[28:29], v[32:33] op_sel_hi:[0,1,1] neg_lo:[0,0,1] neg_hi:[0,0,1]
	v_pk_fma_f32 v[50:51], v[34:35], v[30:31], v[32:33]
	v_add_u32_e32 v28, s4, v44
	v_mov_b32_e32 v51, v29
	v_bfe_i32 v29, v28, 5, 1
	v_bfe_i32 v32, v28, 6, 1
	v_and_b32_e32 v29, 5, v29
	v_and_b32_e32 v32, 26, v32
	v_bitop3_b32 v28, v29, v28, v32 bitop3:0x36
	v_lshlrev_b32_e32 v28, 3, v28
	ds_write_b64 v28, v[50:51]
	v_pk_add_f32 v[28:29], v[46:47], v[48:49] neg_lo:[0,1] neg_hi:[0,1]
	s_nop 0
	v_pk_mul_f32 v[32:33], v[36:37], v[28:29] op_sel:[1,1] op_sel_hi:[1,0]
	s_nop 0
	v_pk_fma_f32 v[34:35], v[40:41], v[28:29], v[32:33] neg_lo:[0,0,1] neg_hi:[0,0,1]
	v_pk_fma_f32 v[28:29], v[40:41], v[28:29], v[32:33] op_sel_hi:[0,1,1]
	v_add_u32_e32 v28, s3, v44
	v_mov_b32_e32 v35, v29
	v_bfe_i32 v29, v28, 5, 1
	v_bfe_i32 v32, v28, 6, 1
	v_and_b32_e32 v29, 5, v29
	v_and_b32_e32 v32, 26, v32
	v_bitop3_b32 v28, v29, v28, v32 bitop3:0x36
	v_lshlrev_b32_e32 v28, 3, v28
	ds_write_b64 v28, v[34:35]
	v_mov_b32_e32 v29, v31
	v_pk_add_f32 v[34:35], v[38:39], v[38:39] op_sel:[1,0] op_sel_hi:[1,0] neg_lo:[0,1] neg_hi:[0,1]
	v_pk_mov_b32 v[30:31], v[30:31], v[26:27] op_sel:[1,0]
	v_mov_b32_e32 v28, v26
	v_pk_add_f32 v[32:33], v[42:43], v[42:43] op_sel:[0,1] op_sel_hi:[0,1]
	v_pk_mul_f32 v[30:31], v[34:35], v[30:31]
	v_and_b32_e32 v38, s5, v214
	v_pk_fma_f32 v[28:29], v[32:33], v[28:29], v[30:31]
	v_pk_fma_f32 v[26:27], v[32:33], v[26:27], v[30:31] neg_lo:[0,0,1] neg_hi:[0,0,1]
	v_add_u32_e32 v28, s2, v44
	v_mov_b32_e32 v27, v29
	v_bfe_i32 v29, v28, 5, 1
	v_bfe_i32 v30, v28, 6, 1
	v_and_b32_e32 v29, 5, v29
; DI f32x2 cmul(f32x2 a, f32x2 b) { return mkf2(a.x * b.x - a.y * b.y, a.x * b.y + a.y * b.x); }
; DI void fft8192(f32x2* buf, const f32x2* __restrict__ tw) {
;     ...
;   for (int ls = 0; ls < 12; ls += 2) {
;     const int s = 1 << ls;
;     f32x2 a[8], b[8], c[8], d[8];
;     __syncthreads();
; #pragma unroll
;     for (int e = 0; e < 8; ++e) {
;       const int i = tid + 256 * e;
;       const int pi = SW(i);
;       a[e] = buf[pi]; b[e] = buf[pi + 2048]; c[e] = buf[pi + 4096]; d[e] = buf[pi + 6144];
;     }
;     __syncthreads();
; #pragma unroll
;     for (int e = 0; e < 8; ++e) {
;       const int i = tid + 256 * e;
;       const int q = i & (s - 1);
;       const int ps = i - q;
;       const float rev = (float)ps * (1.f / 8192.f);
;       const f32x2 w1 = mkf2(__builtin_amdgcn_cosf(rev), -__builtin_amdgcn_sinf(rev));
;       const f32x2 w2 = cmul(w1, w1), w3 = cmul(w1, w2);
;       const f32x2 apc = mkf2(a[e].x + c[e].x, a[e].y + c[e].y), amc = mkf2(a[e].x - c[e].x, a[e].y - c[e].y);
;       const f32x2 bpd = mkf2(b[e].x + d[e].x, b[e].y + d[e].y), bmd = mkf2(b[e].x - d[e].x, b[e].y - d[e].y);
;       const int o = 4 * i - 3 * q;
;       buf[SW(o)] = mkf2(apc.x + bpd.x, apc.y + bpd.y);
;       buf[SW(o + s)] = cmul(w1, mkf2(amc.x + bmd.y, amc.y - bmd.x));
;       buf[SW(o + 2 * s)] = cmul(w2, mkf2(apc.x - bpd.x, apc.y - bpd.y));
;       buf[SW(o + 3 * s)] = cmul(w3, mkf2(amc.x - bmd.y, amc.y + bmd.x));
;     }
	v_and_b32_e32 v30, 26, v30
	v_bitop3_b32 v28, v29, v28, v30 bitop3:0x36
	v_lshlrev_b32_e32 v28, 3, v28
	ds_write_b64 v28, v[26:27]
	v_sub_u32_e32 v26, v214, v38
	v_cvt_f32_i32_e32 v26, v26
	v_pk_add_f32 v[40:41], v[20:21], v[24:25]
	v_pk_add_f32 v[20:21], v[20:21], v[24:25] neg_lo:[0,1] neg_hi:[0,1]
	v_mul_f32_e32 v27, 0x39000000, v26
	v_cos_f32_e32 v26, v27
	v_sin_f32_e32 v27, v27
	v_mov_b32_e32 v37, v26
	v_pk_mul_f32 v[28:29], v[26:27], v[26:27]
	v_mul_f32_e64 v31, v26, -v27
	v_mov_b32_e32 v30, v28
	v_mov_b32_e32 v28, v29
	v_mov_b32_e32 v29, v31
	v_pk_add_f32 v[32:33], v[30:31], v[28:29] neg_lo:[0,1] neg_hi:[0,1]
	v_pk_add_f32 v[28:29], v[30:31], v[28:29]
	v_mov_b32_e32 v30, v32
	v_mov_b32_e32 v31, v29
	v_mov_b32_e32 v36, v27
	v_pk_mul_f32 v[34:35], v[26:27], v[30:31]
	v_pk_mul_f32 v[30:31], v[36:37], v[30:31]
	v_mad_u64_u32 v[36:37], s[8:9], v38, -3, v[164:165]
	v_bfe_i32 v37, v36, 5, 1
	v_bfe_i32 v44, v36, 6, 1
	v_and_b32_e32 v37, 5, v37
	v_and_b32_e32 v44, 26, v44
	v_pk_add_f32 v[38:39], v[18:19], v[22:23]
	v_bitop3_b32 v37, v37, v36, v44 bitop3:0x36
	v_pk_add_f32 v[18:19], v[18:19], v[22:23] neg_lo:[0,1] neg_hi:[0,1]
	v_pk_add_f32 v[42:43], v[38:39], v[40:41]
	v_lshlrev_b32_e32 v37, 3, v37
	v_pk_add_f32 v[22:23], v[18:19], v[20:21] op_sel:[0,1] op_sel_hi:[1,0]
	v_pk_add_f32 v[18:19], v[18:19], v[20:21] op_sel:[0,1] op_sel_hi:[1,0] neg_lo:[0,1] neg_hi:[0,1]
	ds_write_b64 v37, v[42:43]
	v_mov_b32_e32 v24, v27
	v_pk_mov_b32 v[42:43], v[18:19], v[22:23] op_sel:[1,0]
	v_mov_b32_e32 v20, v22
	v_mov_b32_e32 v21, v19
	v_pk_mul_f32 v[24:25], v[24:25], v[42:43] op_sel_hi:[0,1]
	v_pk_fma_f32 v[20:21], v[26:27], v[20:21], v[24:25] op_sel_hi:[0,1,1] neg_lo:[0,0,1] neg_hi:[0,0,1]
	v_pk_fma_f32 v[42:43], v[26:27], v[22:23], v[24:25]
	v_add_u32_e32 v20, s4, v36
	v_mov_b32_e32 v43, v21
	v_bfe_i32 v21, v20, 5, 1
	v_bfe_i32 v24, v20, 6, 1
	v_and_b32_e32 v21, 5, v21
	v_and_b32_e32 v24, 26, v24
	v_bitop3_b32 v20, v21, v20, v24 bitop3:0x36
	v_lshlrev_b32_e32 v20, 3, v20
	ds_write_b64 v20, v[42:43]
	v_pk_add_f32 v[20:21], v[38:39], v[40:41] neg_lo:[0,1] neg_hi:[0,1]
	s_nop 0
	v_pk_mul_f32 v[24:25], v[28:29], v[20:21] op_sel:[1,1] op_sel_hi:[1,0]
	s_nop 0
	v_pk_fma_f32 v[26:27], v[32:33], v[20:21], v[24:25] neg_lo:[0,0,1] neg_hi:[0,0,1]
	v_pk_fma_f32 v[20:21], v[32:33], v[20:21], v[24:25] op_sel_hi:[0,1,1]
	v_add_u32_e32 v20, s3, v36
	v_mov_b32_e32 v27, v21
	v_bfe_i32 v21, v20, 5, 1
	v_bfe_i32 v24, v20, 6, 1
	v_and_b32_e32 v21, 5, v21
	v_and_b32_e32 v24, 26, v24
	v_bitop3_b32 v20, v21, v20, v24 bitop3:0x36
	v_lshlrev_b32_e32 v20, 3, v20
	ds_write_b64 v20, v[26:27]
	v_mov_b32_e32 v21, v23
	v_pk_add_f32 v[26:27], v[30:31], v[30:31] op_sel:[1,0] op_sel_hi:[1,0] neg_lo:[0,1] neg_hi:[0,1]
	v_pk_mov_b32 v[22:23], v[22:23], v[18:19] op_sel:[1,0]
	v_mov_b32_e32 v20, v18
	v_pk_add_f32 v[24:25], v[34:35], v[34:35] op_sel:[0,1] op_sel_hi:[0,1]
	v_pk_mul_f32 v[22:23], v[26:27], v[22:23]
	v_and_b32_e32 v30, s5, v216
	v_pk_fma_f32 v[20:21], v[24:25], v[20:21], v[22:23]
	v_pk_fma_f32 v[18:19], v[24:25], v[18:19], v[22:23] neg_lo:[0,0,1] neg_hi:[0,0,1]
	v_add_u32_e32 v20, s2, v36
	v_mov_b32_e32 v19, v21
	v_bfe_i32 v21, v20, 5, 1
	v_bfe_i32 v22, v20, 6, 1
	v_and_b32_e32 v21, 5, v21
	v_and_b32_e32 v22, 26, v22
	v_bitop3_b32 v20, v21, v20, v22 bitop3:0x36
	v_lshlrev_b32_e32 v20, 3, v20
	ds_write_b64 v20, v[18:19]
	v_sub_u32_e32 v18, v216, v30
	v_cvt_f32_i32_e32 v18, v18
	v_pk_add_f32 v[32:33], v[12:13], v[16:17]
	v_pk_add_f32 v[12:13], v[12:13], v[16:17] neg_lo:[0,1] neg_hi:[0,1]
	v_mul_f32_e32 v19, 0x39000000, v18
	v_cos_f32_e32 v18, v19
	v_sin_f32_e32 v19, v19
	v_mov_b32_e32 v29, v18
	v_pk_mul_f32 v[20:21], v[18:19], v[18:19]
	v_mul_f32_e64 v23, v18, -v19
	v_mov_b32_e32 v22, v20
	v_mov_b32_e32 v20, v21
	v_mov_b32_e32 v21, v23
	v_pk_add_f32 v[24:25], v[22:23], v[20:21] neg_lo:[0,1] neg_hi:[0,1]
	v_pk_add_f32 v[20:21], v[22:23], v[20:21]
	v_mov_b32_e32 v22, v24
	v_mov_b32_e32 v23, v21
	v_mov_b32_e32 v28, v19
	v_pk_mul_f32 v[26:27], v[18:19], v[22:23]
	v_pk_mul_f32 v[22:23], v[28:29], v[22:23]
	v_mad_u64_u32 v[28:29], s[8:9], v30, -3, v[166:167]
	v_bfe_i32 v29, v28, 5, 1
	v_bfe_i32 v36, v28, 6, 1
	v_and_b32_e32 v29, 5, v29
	v_and_b32_e32 v36, 26, v36
	v_pk_add_f32 v[30:31], v[10:11], v[14:15]
	v_bitop3_b32 v29, v29, v28, v36 bitop3:0x36
	v_pk_add_f32 v[10:11], v[10:11], v[14:15] neg_lo:[0,1] neg_hi:[0,1]
	v_pk_add_f32 v[34:35], v[30:31], v[32:33]
	v_lshlrev_b32_e32 v29, 3, v29
	v_pk_add_f32 v[14:15], v[10:11], v[12:13] op_sel:[0,1] op_sel_hi:[1,0]
	v_pk_add_f32 v[10:11], v[10:11], v[12:13] op_sel:[0,1] op_sel_hi:[1,0] neg_lo:[0,1] neg_hi:[0,1]
	ds_write_b64 v29, v[34:35]
	v_mov_b32_e32 v16, v19
	v_pk_mov_b32 v[34:35], v[10:11], v[14:15] op_sel:[1,0]
	v_mov_b32_e32 v12, v14
	v_mov_b32_e32 v13, v11
	v_pk_mul_f32 v[16:17], v[16:17], v[34:35] op_sel_hi:[0,1]
	v_pk_fma_f32 v[12:13], v[18:19], v[12:13], v[16:17] op_sel_hi:[0,1,1] neg_lo:[0,0,1] neg_hi:[0,0,1]
	v_pk_fma_f32 v[34:35], v[18:19], v[14:15], v[16:17]
	v_add_u32_e32 v12, s4, v28
	v_mov_b32_e32 v35, v13
	v_bfe_i32 v13, v12, 5, 1
	v_bfe_i32 v16, v12, 6, 1
	v_and_b32_e32 v13, 5, v13
	v_and_b32_e32 v16, 26, v16
	v_bitop3_b32 v12, v13, v12, v16 bitop3:0x36
	v_lshlrev_b32_e32 v12, 3, v12
	ds_write_b64 v12, v[34:35]
	v_pk_add_f32 v[12:13], v[30:31], v[32:33] neg_lo:[0,1] neg_hi:[0,1]
	s_nop 0
	v_pk_mul_f32 v[16:17], v[20:21], v[12:13] op_sel:[1,1] op_sel_hi:[1,0]
	s_nop 0
	v_pk_fma_f32 v[18:19], v[24:25], v[12:13], v[16:17] neg_lo:[0,0,1] neg_hi:[0,0,1]
	v_pk_fma_f32 v[12:13], v[24:25], v[12:13], v[16:17] op_sel_hi:[0,1,1]
	v_add_u32_e32 v12, s3, v28
	v_mov_b32_e32 v19, v13
	v_bfe_i32 v13, v12, 5, 1
	v_bfe_i32 v16, v12, 6, 1
; DI f32x2 cmul(f32x2 a, f32x2 b) { return mkf2(a.x * b.x - a.y * b.y, a.x * b.y + a.y * b.x); }
; DI void fft8192(f32x2* buf, const f32x2* __restrict__ tw) {
;     ...
;   for (int ls = 0; ls < 12; ls += 2) {
;     const int s = 1 << ls;
;     f32x2 a[8], b[8], c[8], d[8];
;     __syncthreads();
; #pragma unroll
;     for (int e = 0; e < 8; ++e) {
;       const int i = tid + 256 * e;
;       const int pi = SW(i);
;       a[e] = buf[pi]; b[e] = buf[pi + 2048]; c[e] = buf[pi + 4096]; d[e] = buf[pi + 6144];
;     }
;     __syncthreads();
; #pragma unroll
;     for (int e = 0; e < 8; ++e) {
;       const int i = tid + 256 * e;
;       const int q = i & (s - 1);
;       const int ps = i - q;
;       const float rev = (float)ps * (1.f / 8192.f);
;       const f32x2 w1 = mkf2(__builtin_amdgcn_cosf(rev), -__builtin_amdgcn_sinf(rev));
;       const f32x2 w2 = cmul(w1, w1), w3 = cmul(w1, w2);
;       const f32x2 apc = mkf2(a[e].x + c[e].x, a[e].y + c[e].y), amc = mkf2(a[e].x - c[e].x, a[e].y - c[e].y);
;       const f32x2 bpd = mkf2(b[e].x + d[e].x, b[e].y + d[e].y), bmd = mkf2(b[e].x - d[e].x, b[e].y - d[e].y);
;       const int o = 4 * i - 3 * q;
;       buf[SW(o)] = mkf2(apc.x + bpd.x, apc.y + bpd.y);
;       buf[SW(o + s)] = cmul(w1, mkf2(amc.x + bmd.y, amc.y - bmd.x));
;       buf[SW(o + 2 * s)] = cmul(w2, mkf2(apc.x - bpd.x, apc.y - bpd.y));
;       buf[SW(o + 3 * s)] = cmul(w3, mkf2(amc.x - bmd.y, amc.y + bmd.x));
;     }
	v_and_b32_e32 v13, 5, v13
	v_and_b32_e32 v16, 26, v16
	v_bitop3_b32 v12, v13, v12, v16 bitop3:0x36
	v_lshlrev_b32_e32 v12, 3, v12
	ds_write_b64 v12, v[18:19]
	v_mov_b32_e32 v13, v15
	v_pk_add_f32 v[18:19], v[22:23], v[22:23] op_sel:[1,0] op_sel_hi:[1,0] neg_lo:[0,1] neg_hi:[0,1]
	v_pk_mov_b32 v[14:15], v[14:15], v[10:11] op_sel:[1,0]
	v_mov_b32_e32 v12, v10
	v_pk_add_f32 v[16:17], v[26:27], v[26:27] op_sel:[0,1] op_sel_hi:[0,1]
	v_pk_mul_f32 v[14:15], v[18:19], v[14:15]
	v_and_b32_e32 v22, s5, v237
	v_pk_fma_f32 v[12:13], v[16:17], v[12:13], v[14:15]
	v_pk_fma_f32 v[10:11], v[16:17], v[10:11], v[14:15] neg_lo:[0,0,1] neg_hi:[0,0,1]
	v_add_u32_e32 v12, s2, v28
	v_mov_b32_e32 v11, v13
	v_bfe_i32 v13, v12, 5, 1
	v_bfe_i32 v14, v12, 6, 1
	v_and_b32_e32 v13, 5, v13
	v_and_b32_e32 v14, 26, v14
	v_bitop3_b32 v12, v13, v12, v14 bitop3:0x36
	v_lshlrev_b32_e32 v12, 3, v12
	ds_write_b64 v12, v[10:11]
	v_sub_u32_e32 v10, v237, v22
	v_cvt_f32_i32_e32 v10, v10
	v_pk_add_f32 v[24:25], v[4:5], v[8:9]
	v_pk_add_f32 v[4:5], v[4:5], v[8:9] neg_lo:[0,1] neg_hi:[0,1]
	v_mul_f32_e32 v11, 0x39000000, v10
	v_cos_f32_e32 v10, v11
	v_sin_f32_e32 v11, v11
	v_mov_b32_e32 v21, v10
	v_pk_mul_f32 v[12:13], v[10:11], v[10:11]
	v_mul_f32_e64 v15, v10, -v11
	v_mov_b32_e32 v14, v12
	v_mov_b32_e32 v12, v13
	v_mov_b32_e32 v13, v15
	v_pk_add_f32 v[16:17], v[14:15], v[12:13] neg_lo:[0,1] neg_hi:[0,1]
	v_pk_add_f32 v[12:13], v[14:15], v[12:13]
	v_mov_b32_e32 v14, v16
	v_mov_b32_e32 v15, v13
	v_mov_b32_e32 v20, v11
	v_pk_mul_f32 v[18:19], v[10:11], v[14:15]
	v_pk_mul_f32 v[14:15], v[20:21], v[14:15]
	v_mad_u64_u32 v[20:21], s[8:9], v22, -3, v[168:169]
	v_bfe_i32 v21, v20, 5, 1
	v_bfe_i32 v28, v20, 6, 1
	v_and_b32_e32 v21, 5, v21
	v_and_b32_e32 v28, 26, v28
	v_pk_add_f32 v[22:23], v[2:3], v[6:7]
	v_bitop3_b32 v21, v21, v20, v28 bitop3:0x36
	v_pk_add_f32 v[2:3], v[2:3], v[6:7] neg_lo:[0,1] neg_hi:[0,1]
	v_pk_add_f32 v[26:27], v[22:23], v[24:25]
	v_lshlrev_b32_e32 v21, 3, v21
	v_pk_add_f32 v[6:7], v[2:3], v[4:5] op_sel:[0,1] op_sel_hi:[1,0]
	v_pk_add_f32 v[2:3], v[2:3], v[4:5] op_sel:[0,1] op_sel_hi:[1,0] neg_lo:[0,1] neg_hi:[0,1]
	ds_write_b64 v21, v[26:27]
	v_mov_b32_e32 v8, v11
	v_pk_mov_b32 v[26:27], v[2:3], v[6:7] op_sel:[1,0]
	v_mov_b32_e32 v4, v6
	v_mov_b32_e32 v5, v3
	v_pk_mul_f32 v[8:9], v[8:9], v[26:27] op_sel_hi:[0,1]
	v_pk_fma_f32 v[4:5], v[10:11], v[4:5], v[8:9] op_sel_hi:[0,1,1] neg_lo:[0,0,1] neg_hi:[0,0,1]
	v_pk_fma_f32 v[26:27], v[10:11], v[6:7], v[8:9]
	v_add_u32_e32 v4, s4, v20
	v_mov_b32_e32 v27, v5
	v_bfe_i32 v5, v4, 5, 1
	v_bfe_i32 v8, v4, 6, 1
	v_and_b32_e32 v5, 5, v5
	v_and_b32_e32 v8, 26, v8
	v_bitop3_b32 v4, v5, v4, v8 bitop3:0x36
	v_lshlrev_b32_e32 v4, 3, v4
	ds_write_b64 v4, v[26:27]
	v_pk_add_f32 v[4:5], v[22:23], v[24:25] neg_lo:[0,1] neg_hi:[0,1]
	s_lshl_b32 s4, 8, s7
	v_pk_mul_f32 v[8:9], v[12:13], v[4:5] op_sel:[1,1] op_sel_hi:[1,0]
	s_nop 0
	v_pk_fma_f32 v[10:11], v[16:17], v[4:5], v[8:9] neg_lo:[0,0,1] neg_hi:[0,0,1]
	v_pk_fma_f32 v[4:5], v[16:17], v[4:5], v[8:9] op_sel_hi:[0,1,1]
	v_add_u32_e32 v4, s3, v20
	v_mov_b32_e32 v11, v5
	v_bfe_i32 v5, v4, 5, 1
	v_bfe_i32 v8, v4, 6, 1
	v_and_b32_e32 v5, 5, v5
	v_and_b32_e32 v8, 26, v8
	v_bitop3_b32 v4, v5, v4, v8 bitop3:0x36
	s_lshl_b32 s3, 4, s7
	v_lshlrev_b32_e32 v4, 3, v4
	s_add_i32 s5, s3, -1
	ds_write_b64 v4, v[10:11]
	v_mov_b32_e32 v5, v7
	v_pk_add_f32 v[10:11], v[14:15], v[14:15] op_sel:[1,0] op_sel_hi:[1,0] neg_lo:[0,1] neg_hi:[0,1]
	v_pk_mov_b32 v[6:7], v[6:7], v[2:3] op_sel:[1,0]
	v_and_b32_e32 v225, s5, v208
	v_mov_b32_e32 v4, v2
	v_pk_add_f32 v[8:9], v[18:19], v[18:19] op_sel:[0,1] op_sel_hi:[0,1]
	v_pk_mul_f32 v[6:7], v[10:11], v[6:7]
	v_sub_u32_e32 v220, v208, v225
	v_pk_fma_f32 v[4:5], v[8:9], v[4:5], v[6:7]
	v_cvt_f32_i32_e32 v220, v220
	v_pk_fma_f32 v[2:3], v[8:9], v[2:3], v[6:7] neg_lo:[0,0,1] neg_hi:[0,0,1]
	v_add_u32_e32 v4, s2, v20
	v_mov_b32_e32 v3, v5
	v_bfe_i32 v5, v4, 5, 1
	v_bfe_i32 v6, v4, 6, 1
	v_and_b32_e32 v5, 5, v5
	v_and_b32_e32 v6, 26, v6
	v_bitop3_b32 v4, v5, v4, v6 bitop3:0x36
	v_mul_f32_e32 v221, 0x39000000, v220
	v_mad_u64_u32 v[226:227], s[8:9], v225, -3, v[154:155]
	v_lshlrev_b32_e32 v4, 3, v4
	v_cos_f32_e32 v220, v221
	v_sin_f32_e32 v221, v221
	v_bfe_i32 v225, v226, 5, 1
	v_bfe_i32 v227, v226, 6, 1
	ds_write_b64 v4, v[2:3]
	s_waitcnt lgkmcnt(0)
	s_barrier
	ds_read2st64_b64 v[58:61], v198 offset1:32
	ds_read2st64_b64 v[62:65], v198 offset0:64 offset1:96
	ds_read2st64_b64 v[50:53], v201 offset1:32
	ds_read2st64_b64 v[54:57], v201 offset0:64 offset1:96
	ds_read2st64_b64 v[42:45], v202 offset1:32
	ds_read2st64_b64 v[46:49], v202 offset0:64 offset1:96
	ds_read2st64_b64 v[34:37], v203 offset1:32
	ds_read2st64_b64 v[38:41], v203 offset0:64 offset1:96
	ds_read2st64_b64 v[26:29], v204 offset1:32
	ds_read2st64_b64 v[30:33], v204 offset0:64 offset1:96
	ds_read2st64_b64 v[18:21], v205 offset1:32
	ds_read2st64_b64 v[22:25], v205 offset0:64 offset1:96
	ds_read2st64_b64 v[10:13], v206 offset1:32
	ds_read2st64_b64 v[14:17], v206 offset0:64 offset1:96
	ds_read2st64_b64 v[2:5], v207 offset1:32
	ds_read2st64_b64 v[6:9], v207 offset0:64 offset1:96
	v_and_b32_e32 v225, 5, v225
	v_and_b32_e32 v227, 26, v227
	s_waitcnt lgkmcnt(14)
	v_pk_add_f32 v[230:231], v[58:59], v[62:63]
	v_pk_add_f32 v[232:233], v[60:61], v[64:65]
	v_bitop3_b32 v225, v225, v226, v227 bitop3:0x36
	v_pk_add_f32 v[58:59], v[58:59], v[62:63] neg_lo:[0,1] neg_hi:[0,1]
	v_pk_add_f32 v[60:61], v[60:61], v[64:65] neg_lo:[0,1] neg_hi:[0,1]
	v_pk_add_f32 v[238:239], v[230:231], v[232:233]
	v_lshlrev_b32_e32 v225, 3, v225
	v_pk_add_f32 v[62:63], v[58:59], v[60:61] op_sel:[0,1] op_sel_hi:[1,0]
	v_pk_add_f32 v[58:59], v[58:59], v[60:61] op_sel:[0,1] op_sel_hi:[1,0] neg_lo:[0,1] neg_hi:[0,1]
	s_waitcnt lgkmcnt(0)
	s_barrier
; DI f32x2 cmul(f32x2 a, f32x2 b) { return mkf2(a.x * b.x - a.y * b.y, a.x * b.y + a.y * b.x); }
; DI void fft8192(f32x2* buf, const f32x2* __restrict__ tw) {
;     ...
;   for (int ls = 0; ls < 12; ls += 2) {
;     const int s = 1 << ls;
;     f32x2 a[8], b[8], c[8], d[8];
;     __syncthreads();
; #pragma unroll
;     for (int e = 0; e < 8; ++e) {
;       const int i = tid + 256 * e;
;       const int pi = SW(i);
;       a[e] = buf[pi]; b[e] = buf[pi + 2048]; c[e] = buf[pi + 4096]; d[e] = buf[pi + 6144];
;     }
;     __syncthreads();
; #pragma unroll
;     for (int e = 0; e < 8; ++e) {
;       const int i = tid + 256 * e;
;       const int q = i & (s - 1);
;       const int ps = i - q;
;       const float rev = (float)ps * (1.f / 8192.f);
;       const f32x2 w1 = mkf2(__builtin_amdgcn_cosf(rev), -__builtin_amdgcn_sinf(rev));
;       const f32x2 w2 = cmul(w1, w1), w3 = cmul(w1, w2);
;       const f32x2 apc = mkf2(a[e].x + c[e].x, a[e].y + c[e].y), amc = mkf2(a[e].x - c[e].x, a[e].y - c[e].y);
;       const f32x2 bpd = mkf2(b[e].x + d[e].x, b[e].y + d[e].y), bmd = mkf2(b[e].x - d[e].x, b[e].y - d[e].y);
;       const int o = 4 * i - 3 * q;
;       buf[SW(o)] = mkf2(apc.x + bpd.x, apc.y + bpd.y);
;       buf[SW(o + s)] = cmul(w1, mkf2(amc.x + bmd.y, amc.y - bmd.x));
;       buf[SW(o + 2 * s)] = cmul(w2, mkf2(apc.x - bpd.x, apc.y - bpd.y));
;       buf[SW(o + 3 * s)] = cmul(w3, mkf2(amc.x - bmd.y, amc.y + bmd.x));
;     }
	ds_write_b64 v225, v[238:239]
	v_mov_b32_e32 v64, v221
	v_pk_mov_b32 v[238:239], v[58:59], v[62:63] op_sel:[1,0]
	v_mov_b32_e32 v60, v62
	v_mov_b32_e32 v61, v59
	v_pk_mul_f32 v[238:239], v[64:65], v[238:239] op_sel_hi:[0,1]
	v_pk_fma_f32 v[60:61], v[220:221], v[60:61], v[238:239] op_sel_hi:[0,1,1] neg_lo:[0,0,1] neg_hi:[0,0,1]
	v_pk_fma_f32 v[240:241], v[220:221], v[62:63], v[238:239]
	v_add_u32_e32 v60, s3, v226
	v_mov_b32_e32 v241, v61
	v_bfe_i32 v61, v60, 5, 1
	v_bfe_i32 v65, v60, 6, 1
	v_and_b32_e32 v61, 5, v61
	v_and_b32_e32 v65, 26, v65
	v_bitop3_b32 v60, v61, v60, v65 bitop3:0x36
	v_mul_f32_e64 v224, v220, -v221
	v_lshlrev_b32_e32 v60, 3, v60
	v_mul_f32_e32 v222, v221, v221
	v_add_f32_e32 v224, v224, v224
	ds_write_b64 v60, v[240:241]
	v_pk_add_f32 v[60:61], v[230:231], v[232:233] neg_lo:[0,1] neg_hi:[0,1]
	v_pk_fma_f32 v[222:223], v[220:221], v[220:221], v[222:223] op_sel_hi:[1,1,0] neg_lo:[0,0,1] neg_hi:[0,0,1]
	v_pk_mul_f32 v[230:231], v[224:225], v[60:61] op_sel:[0,1] op_sel_hi:[0,0]
	v_pk_fma_f32 v[232:233], v[222:223], v[60:61], v[230:231] neg_lo:[0,0,1] neg_hi:[0,0,1]
	v_pk_fma_f32 v[60:61], v[222:223], v[60:61], v[230:231] op_sel_hi:[0,1,1]
	v_add_u32_e32 v60, s4, v226
	v_mov_b32_e32 v233, v61
	v_bfe_i32 v61, v60, 5, 1
	v_bfe_i32 v65, v60, 6, 1
	v_and_b32_e32 v61, 5, v61
	v_and_b32_e32 v65, 26, v65
	v_bitop3_b32 v60, v61, v60, v65 bitop3:0x36
	v_lshlrev_b32_e32 v60, 3, v60
	v_mov_b32_e32 v223, v224
	ds_write_b64 v60, v[232:233]
	v_pk_mul_f32 v[60:61], v[64:65], v[222:223] op_sel:[0,1] op_sel_hi:[0,0]
	v_pk_fma_f32 v[64:65], v[220:221], v[222:223], v[60:61] op_sel_hi:[0,1,1]
	v_pk_fma_f32 v[60:61], v[220:221], v[222:223], v[60:61] op_sel_hi:[0,1,1] neg_lo:[0,0,1] neg_hi:[0,0,1]
	v_mov_b32_e32 v221, v61
	v_pk_mov_b32 v[60:61], v[60:61], v[64:65] op_sel:[1,0]
	v_mov_b32_e32 v220, v64
	v_pk_mul_f32 v[60:61], v[62:63], v[60:61] op_sel:[1,0]
	s_lshl_b32 s2, 12, s7
	v_pk_fma_f32 v[62:63], v[58:59], v[64:65], v[60:61] neg_lo:[0,0,1] neg_hi:[0,0,1]
	v_pk_fma_f32 v[58:59], v[58:59], v[220:221], v[60:61] op_sel_hi:[0,1,1]
	v_add_u32_e32 v58, s2, v226
	v_mov_b32_e32 v63, v59
	v_bfe_i32 v59, v58, 5, 1
	v_bfe_i32 v60, v58, 6, 1
	v_and_b32_e32 v59, 5, v59
	v_and_b32_e32 v60, 26, v60
	v_bitop3_b32 v58, v59, v58, v60 bitop3:0x36
	v_lshlrev_b32_e32 v58, 3, v58
	v_and_b32_e32 v224, s5, v210
	ds_write_b64 v58, v[62:63]
	v_sub_u32_e32 v58, v210, v224
	v_cvt_f32_i32_e32 v58, v58
	v_pk_add_f32 v[226:227], v[52:53], v[56:57]
	v_pk_add_f32 v[52:53], v[52:53], v[56:57] neg_lo:[0,1] neg_hi:[0,1]
	v_mul_f32_e32 v59, 0x39000000, v58
	v_cos_f32_e32 v58, v59
	v_sin_f32_e32 v59, v59
	v_mov_b32_e32 v223, v58
	v_pk_mul_f32 v[60:61], v[58:59], v[58:59]
	v_mul_f32_e64 v63, v58, -v59
	v_mov_b32_e32 v62, v60
	v_mov_b32_e32 v60, v61
	v_mov_b32_e32 v61, v63
	v_pk_add_f32 v[64:65], v[62:63], v[60:61] neg_lo:[0,1] neg_hi:[0,1]
	v_pk_add_f32 v[60:61], v[62:63], v[60:61]
	v_mov_b32_e32 v62, v64
	v_mov_b32_e32 v63, v61
	v_mov_b32_e32 v222, v59
	v_pk_mul_f32 v[220:221], v[58:59], v[62:63]
	v_pk_mul_f32 v[62:63], v[222:223], v[62:63]
	v_mad_u64_u32 v[222:223], s[8:9], v224, -3, v[156:157]
	v_bfe_i32 v223, v222, 5, 1
	v_bfe_i32 v232, v222, 6, 1
	v_and_b32_e32 v223, 5, v223
	v_and_b32_e32 v232, 26, v232
	v_pk_add_f32 v[224:225], v[50:51], v[54:55]
	v_bitop3_b32 v223, v223, v222, v232 bitop3:0x36
	v_pk_add_f32 v[50:51], v[50:51], v[54:55] neg_lo:[0,1] neg_hi:[0,1]
	v_pk_add_f32 v[230:231], v[224:225], v[226:227]
	v_lshlrev_b32_e32 v223, 3, v223
	v_pk_add_f32 v[54:55], v[50:51], v[52:53] op_sel:[0,1] op_sel_hi:[1,0]
	v_pk_add_f32 v[50:51], v[50:51], v[52:53] op_sel:[0,1] op_sel_hi:[1,0] neg_lo:[0,1] neg_hi:[0,1]
	ds_write_b64 v223, v[230:231]
	v_mov_b32_e32 v56, v59
	v_pk_mov_b32 v[230:231], v[50:51], v[54:55] op_sel:[1,0]
	v_mov_b32_e32 v52, v54
	v_mov_b32_e32 v53, v51
	v_pk_mul_f32 v[56:57], v[56:57], v[230:231] op_sel_hi:[0,1]
	v_pk_fma_f32 v[52:53], v[58:59], v[52:53], v[56:57] op_sel_hi:[0,1,1] neg_lo:[0,0,1] neg_hi:[0,0,1]
	v_pk_fma_f32 v[230:231], v[58:59], v[54:55], v[56:57]
	v_add_u32_e32 v52, s3, v222
	v_mov_b32_e32 v231, v53
	v_bfe_i32 v53, v52, 5, 1
	v_bfe_i32 v56, v52, 6, 1
	v_and_b32_e32 v53, 5, v53
	v_and_b32_e32 v56, 26, v56
	v_bitop3_b32 v52, v53, v52, v56 bitop3:0x36
	v_lshlrev_b32_e32 v52, 3, v52
	ds_write_b64 v52, v[230:231]
	v_pk_add_f32 v[52:53], v[224:225], v[226:227] neg_lo:[0,1] neg_hi:[0,1]
	s_nop 0
	v_pk_mul_f32 v[56:57], v[60:61], v[52:53] op_sel:[1,1] op_sel_hi:[1,0]
	s_nop 0
	v_pk_fma_f32 v[58:59], v[64:65], v[52:53], v[56:57] neg_lo:[0,0,1] neg_hi:[0,0,1]
	v_pk_fma_f32 v[52:53], v[64:65], v[52:53], v[56:57] op_sel_hi:[0,1,1]
	v_add_u32_e32 v52, s4, v222
	v_mov_b32_e32 v59, v53
	v_bfe_i32 v53, v52, 5, 1
	v_bfe_i32 v56, v52, 6, 1
	v_and_b32_e32 v53, 5, v53
	v_and_b32_e32 v56, 26, v56
	v_bitop3_b32 v52, v53, v52, v56 bitop3:0x36
	v_lshlrev_b32_e32 v52, 3, v52
	ds_write_b64 v52, v[58:59]
	v_mov_b32_e32 v53, v55
	v_pk_add_f32 v[58:59], v[62:63], v[62:63] op_sel:[1,0] op_sel_hi:[1,0] neg_lo:[0,1] neg_hi:[0,1]
	v_pk_mov_b32 v[54:55], v[54:55], v[50:51] op_sel:[1,0]
	v_mov_b32_e32 v52, v50
	v_pk_add_f32 v[56:57], v[220:221], v[220:221] op_sel:[0,1] op_sel_hi:[0,1]
	v_pk_mul_f32 v[54:55], v[58:59], v[54:55]
	v_and_b32_e32 v62, s5, v211
	v_pk_fma_f32 v[52:53], v[56:57], v[52:53], v[54:55]
	v_pk_fma_f32 v[50:51], v[56:57], v[50:51], v[54:55] neg_lo:[0,0,1] neg_hi:[0,0,1]
	v_add_u32_e32 v52, s2, v222
	v_mov_b32_e32 v51, v53
	v_bfe_i32 v53, v52, 5, 1
	v_bfe_i32 v54, v52, 6, 1
	v_and_b32_e32 v53, 5, v53
	v_and_b32_e32 v54, 26, v54
	v_bitop3_b32 v52, v53, v52, v54 bitop3:0x36
	v_lshlrev_b32_e32 v52, 3, v52
	ds_write_b64 v52, v[50:51]
	v_sub_u32_e32 v50, v211, v62
; DI f32x2 cmul(f32x2 a, f32x2 b) { return mkf2(a.x * b.x - a.y * b.y, a.x * b.y + a.y * b.x); }
; DI void fft8192(f32x2* buf, const f32x2* __restrict__ tw) {
;     ...
;   for (int ls = 0; ls < 12; ls += 2) {
;     const int s = 1 << ls;
;     f32x2 a[8], b[8], c[8], d[8];
;     __syncthreads();
; #pragma unroll
;     for (int e = 0; e < 8; ++e) {
;       const int i = tid + 256 * e;
;       const int pi = SW(i);
;       a[e] = buf[pi]; b[e] = buf[pi + 2048]; c[e] = buf[pi + 4096]; d[e] = buf[pi + 6144];
;     }
;     __syncthreads();
; #pragma unroll
;     for (int e = 0; e < 8; ++e) {
;       const int i = tid + 256 * e;
;       const int q = i & (s - 1);
;       const int ps = i - q;
;       const float rev = (float)ps * (1.f / 8192.f);
;       const f32x2 w1 = mkf2(__builtin_amdgcn_cosf(rev), -__builtin_amdgcn_sinf(rev));
;       const f32x2 w2 = cmul(w1, w1), w3 = cmul(w1, w2);
;       const f32x2 apc = mkf2(a[e].x + c[e].x, a[e].y + c[e].y), amc = mkf2(a[e].x - c[e].x, a[e].y - c[e].y);
;       const f32x2 bpd = mkf2(b[e].x + d[e].x, b[e].y + d[e].y), bmd = mkf2(b[e].x - d[e].x, b[e].y - d[e].y);
;       const int o = 4 * i - 3 * q;
;       buf[SW(o)] = mkf2(apc.x + bpd.x, apc.y + bpd.y);
;       buf[SW(o + s)] = cmul(w1, mkf2(amc.x + bmd.y, amc.y - bmd.x));
;       buf[SW(o + 2 * s)] = cmul(w2, mkf2(apc.x - bpd.x, apc.y - bpd.y));
;       buf[SW(o + 3 * s)] = cmul(w3, mkf2(amc.x - bmd.y, amc.y + bmd.x));
;     }
	v_cvt_f32_i32_e32 v50, v50
	v_pk_add_f32 v[64:65], v[44:45], v[48:49]
	v_pk_add_f32 v[44:45], v[44:45], v[48:49] neg_lo:[0,1] neg_hi:[0,1]
	v_mul_f32_e32 v51, 0x39000000, v50
	v_cos_f32_e32 v50, v51
	v_sin_f32_e32 v51, v51
	v_mov_b32_e32 v61, v50
	v_pk_mul_f32 v[52:53], v[50:51], v[50:51]
	v_mul_f32_e64 v55, v50, -v51
	v_mov_b32_e32 v54, v52
	v_mov_b32_e32 v52, v53
	v_mov_b32_e32 v53, v55
	v_pk_add_f32 v[56:57], v[54:55], v[52:53] neg_lo:[0,1] neg_hi:[0,1]
	v_pk_add_f32 v[52:53], v[54:55], v[52:53]
	v_mov_b32_e32 v54, v56
	v_mov_b32_e32 v55, v53
	v_mov_b32_e32 v60, v51
	v_pk_mul_f32 v[58:59], v[50:51], v[54:55]
	v_pk_mul_f32 v[54:55], v[60:61], v[54:55]
	v_mad_u64_u32 v[60:61], s[8:9], v62, -3, v[158:159]
	v_bfe_i32 v61, v60, 5, 1
	v_bfe_i32 v222, v60, 6, 1
	v_and_b32_e32 v61, 5, v61
	v_and_b32_e32 v222, 26, v222
	v_pk_add_f32 v[62:63], v[42:43], v[46:47]
	v_bitop3_b32 v61, v61, v60, v222 bitop3:0x36
	v_pk_add_f32 v[42:43], v[42:43], v[46:47] neg_lo:[0,1] neg_hi:[0,1]
	v_pk_add_f32 v[220:221], v[62:63], v[64:65]
	v_lshlrev_b32_e32 v61, 3, v61
	v_pk_add_f32 v[46:47], v[42:43], v[44:45] op_sel:[0,1] op_sel_hi:[1,0]
	v_pk_add_f32 v[42:43], v[42:43], v[44:45] op_sel:[0,1] op_sel_hi:[1,0] neg_lo:[0,1] neg_hi:[0,1]
	ds_write_b64 v61, v[220:221]
	v_mov_b32_e32 v48, v51
	v_pk_mov_b32 v[220:221], v[42:43], v[46:47] op_sel:[1,0]
	v_mov_b32_e32 v44, v46
	v_mov_b32_e32 v45, v43
	v_pk_mul_f32 v[48:49], v[48:49], v[220:221] op_sel_hi:[0,1]
	v_pk_fma_f32 v[44:45], v[50:51], v[44:45], v[48:49] op_sel_hi:[0,1,1] neg_lo:[0,0,1] neg_hi:[0,0,1]
	v_pk_fma_f32 v[220:221], v[50:51], v[46:47], v[48:49]
	v_add_u32_e32 v44, s3, v60
	v_mov_b32_e32 v221, v45
	v_bfe_i32 v45, v44, 5, 1
	v_bfe_i32 v48, v44, 6, 1
	v_and_b32_e32 v45, 5, v45
	v_and_b32_e32 v48, 26, v48
	v_bitop3_b32 v44, v45, v44, v48 bitop3:0x36
	v_lshlrev_b32_e32 v44, 3, v44
	ds_write_b64 v44, v[220:221]
	v_pk_add_f32 v[44:45], v[62:63], v[64:65] neg_lo:[0,1] neg_hi:[0,1]
	s_nop 0
	v_pk_mul_f32 v[48:49], v[52:53], v[44:45] op_sel:[1,1] op_sel_hi:[1,0]
	s_nop 0
	v_pk_fma_f32 v[50:51], v[56:57], v[44:45], v[48:49] neg_lo:[0,0,1] neg_hi:[0,0,1]
	v_pk_fma_f32 v[44:45], v[56:57], v[44:45], v[48:49] op_sel_hi:[0,1,1]
	v_add_u32_e32 v44, s4, v60
	v_mov_b32_e32 v51, v45
	v_bfe_i32 v45, v44, 5, 1
	v_bfe_i32 v48, v44, 6, 1
	v_and_b32_e32 v45, 5, v45
	v_and_b32_e32 v48, 26, v48
	v_bitop3_b32 v44, v45, v44, v48 bitop3:0x36
	v_lshlrev_b32_e32 v44, 3, v44
	ds_write_b64 v44, v[50:51]
	v_mov_b32_e32 v45, v47
	v_pk_add_f32 v[50:51], v[54:55], v[54:55] op_sel:[1,0] op_sel_hi:[1,0] neg_lo:[0,1] neg_hi:[0,1]
	v_pk_mov_b32 v[46:47], v[46:47], v[42:43] op_sel:[1,0]
	v_mov_b32_e32 v44, v42
	v_pk_add_f32 v[48:49], v[58:59], v[58:59] op_sel:[0,1] op_sel_hi:[0,1]
	v_pk_mul_f32 v[46:47], v[50:51], v[46:47]
	v_and_b32_e32 v54, s5, v212
	v_pk_fma_f32 v[44:45], v[48:49], v[44:45], v[46:47]
	v_pk_fma_f32 v[42:43], v[48:49], v[42:43], v[46:47] neg_lo:[0,0,1] neg_hi:[0,0,1]
	v_add_u32_e32 v44, s2, v60
	v_mov_b32_e32 v43, v45
	v_bfe_i32 v45, v44, 5, 1
	v_bfe_i32 v46, v44, 6, 1
	v_and_b32_e32 v45, 5, v45
	v_and_b32_e32 v46, 26, v46
	v_bitop3_b32 v44, v45, v44, v46 bitop3:0x36
	v_lshlrev_b32_e32 v44, 3, v44
	ds_write_b64 v44, v[42:43]
	v_sub_u32_e32 v42, v212, v54
	v_cvt_f32_i32_e32 v42, v42
	v_pk_add_f32 v[56:57], v[36:37], v[40:41]
	v_pk_add_f32 v[36:37], v[36:37], v[40:41] neg_lo:[0,1] neg_hi:[0,1]
	v_mul_f32_e32 v43, 0x39000000, v42
	v_cos_f32_e32 v42, v43
	v_sin_f32_e32 v43, v43
	v_mov_b32_e32 v53, v42
	v_pk_mul_f32 v[44:45], v[42:43], v[42:43]
	v_mul_f32_e64 v47, v42, -v43
	v_mov_b32_e32 v46, v44
	v_mov_b32_e32 v44, v45
	v_mov_b32_e32 v45, v47
	v_pk_add_f32 v[48:49], v[46:47], v[44:45] neg_lo:[0,1] neg_hi:[0,1]
	v_pk_add_f32 v[44:45], v[46:47], v[44:45]
	v_mov_b32_e32 v46, v48
	v_mov_b32_e32 v47, v45
	v_mov_b32_e32 v52, v43
	v_pk_mul_f32 v[50:51], v[42:43], v[46:47]
	v_pk_mul_f32 v[46:47], v[52:53], v[46:47]
	v_mad_u64_u32 v[52:53], s[8:9], v54, -3, v[160:161]
	v_bfe_i32 v53, v52, 5, 1
	v_bfe_i32 v60, v52, 6, 1
	v_and_b32_e32 v53, 5, v53
	v_and_b32_e32 v60, 26, v60
	v_pk_add_f32 v[54:55], v[34:35], v[38:39]
	v_bitop3_b32 v53, v53, v52, v60 bitop3:0x36
	v_pk_add_f32 v[34:35], v[34:35], v[38:39] neg_lo:[0,1] neg_hi:[0,1]
	v_pk_add_f32 v[58:59], v[54:55], v[56:57]
	v_lshlrev_b32_e32 v53, 3, v53
	v_pk_add_f32 v[38:39], v[34:35], v[36:37] op_sel:[0,1] op_sel_hi:[1,0]
	v_pk_add_f32 v[34:35], v[34:35], v[36:37] op_sel:[0,1] op_sel_hi:[1,0] neg_lo:[0,1] neg_hi:[0,1]
	ds_write_b64 v53, v[58:59]
	v_mov_b32_e32 v40, v43
	v_pk_mov_b32 v[58:59], v[34:35], v[38:39] op_sel:[1,0]
	v_mov_b32_e32 v36, v38
	v_mov_b32_e32 v37, v35
	v_pk_mul_f32 v[40:41], v[40:41], v[58:59] op_sel_hi:[0,1]
	v_pk_fma_f32 v[36:37], v[42:43], v[36:37], v[40:41] op_sel_hi:[0,1,1] neg_lo:[0,0,1] neg_hi:[0,0,1]
	v_pk_fma_f32 v[58:59], v[42:43], v[38:39], v[40:41]
	v_add_u32_e32 v36, s3, v52
	v_mov_b32_e32 v59, v37
	v_bfe_i32 v37, v36, 5, 1
	v_bfe_i32 v40, v36, 6, 1
	v_and_b32_e32 v37, 5, v37
	v_and_b32_e32 v40, 26, v40
	v_bitop3_b32 v36, v37, v36, v40 bitop3:0x36
	v_lshlrev_b32_e32 v36, 3, v36
	ds_write_b64 v36, v[58:59]
	v_pk_add_f32 v[36:37], v[54:55], v[56:57] neg_lo:[0,1] neg_hi:[0,1]
	s_nop 0
	v_pk_mul_f32 v[40:41], v[44:45], v[36:37] op_sel:[1,1] op_sel_hi:[1,0]
	s_nop 0
	v_pk_fma_f32 v[42:43], v[48:49], v[36:37], v[40:41] neg_lo:[0,0,1] neg_hi:[0,0,1]
	v_pk_fma_f32 v[36:37], v[48:49], v[36:37], v[40:41] op_sel_hi:[0,1,1]
	v_add_u32_e32 v36, s4, v52
	v_mov_b32_e32 v43, v37
	v_bfe_i32 v37, v36, 5, 1
	v_bfe_i32 v40, v36, 6, 1
	v_and_b32_e32 v37, 5, v37
	v_and_b32_e32 v40, 26, v40
	v_bitop3_b32 v36, v37, v36, v40 bitop3:0x36
	v_lshlrev_b32_e32 v36, 3, v36
; DI f32x2 cmul(f32x2 a, f32x2 b) { return mkf2(a.x * b.x - a.y * b.y, a.x * b.y + a.y * b.x); }
; DI void fft8192(f32x2* buf, const f32x2* __restrict__ tw) {
;     ...
;   for (int ls = 0; ls < 12; ls += 2) {
;     const int s = 1 << ls;
;     f32x2 a[8], b[8], c[8], d[8];
;     __syncthreads();
; #pragma unroll
;     for (int e = 0; e < 8; ++e) {
;       const int i = tid + 256 * e;
;       const int pi = SW(i);
;       a[e] = buf[pi]; b[e] = buf[pi + 2048]; c[e] = buf[pi + 4096]; d[e] = buf[pi + 6144];
;     }
;     __syncthreads();
; #pragma unroll
;     for (int e = 0; e < 8; ++e) {
;       const int i = tid + 256 * e;
;       const int q = i & (s - 1);
;       const int ps = i - q;
;       const float rev = (float)ps * (1.f / 8192.f);
;       const f32x2 w1 = mkf2(__builtin_amdgcn_cosf(rev), -__builtin_amdgcn_sinf(rev));
;       const f32x2 w2 = cmul(w1, w1), w3 = cmul(w1, w2);
;       const f32x2 apc = mkf2(a[e].x + c[e].x, a[e].y + c[e].y), amc = mkf2(a[e].x - c[e].x, a[e].y - c[e].y);
;       const f32x2 bpd = mkf2(b[e].x + d[e].x, b[e].y + d[e].y), bmd = mkf2(b[e].x - d[e].x, b[e].y - d[e].y);
;       const int o = 4 * i - 3 * q;
;       buf[SW(o)] = mkf2(apc.x + bpd.x, apc.y + bpd.y);
;       buf[SW(o + s)] = cmul(w1, mkf2(amc.x + bmd.y, amc.y - bmd.x));
;       buf[SW(o + 2 * s)] = cmul(w2, mkf2(apc.x - bpd.x, apc.y - bpd.y));
;       buf[SW(o + 3 * s)] = cmul(w3, mkf2(amc.x - bmd.y, amc.y + bmd.x));
;     }
	ds_write_b64 v36, v[42:43]
	v_mov_b32_e32 v37, v39
	v_pk_add_f32 v[42:43], v[46:47], v[46:47] op_sel:[1,0] op_sel_hi:[1,0] neg_lo:[0,1] neg_hi:[0,1]
	v_pk_mov_b32 v[38:39], v[38:39], v[34:35] op_sel:[1,0]
	v_mov_b32_e32 v36, v34
	v_pk_add_f32 v[40:41], v[50:51], v[50:51] op_sel:[0,1] op_sel_hi:[0,1]
	v_pk_mul_f32 v[38:39], v[42:43], v[38:39]
	v_and_b32_e32 v46, s5, v213
	v_pk_fma_f32 v[36:37], v[40:41], v[36:37], v[38:39]
	v_pk_fma_f32 v[34:35], v[40:41], v[34:35], v[38:39] neg_lo:[0,0,1] neg_hi:[0,0,1]
	v_add_u32_e32 v36, s2, v52
	v_mov_b32_e32 v35, v37
	v_bfe_i32 v37, v36, 5, 1
	v_bfe_i32 v38, v36, 6, 1
	v_and_b32_e32 v37, 5, v37
	v_and_b32_e32 v38, 26, v38
	v_bitop3_b32 v36, v37, v36, v38 bitop3:0x36
	v_lshlrev_b32_e32 v36, 3, v36
	ds_write_b64 v36, v[34:35]
	v_sub_u32_e32 v34, v213, v46
	v_cvt_f32_i32_e32 v34, v34
	v_pk_add_f32 v[48:49], v[28:29], v[32:33]
	v_pk_add_f32 v[28:29], v[28:29], v[32:33] neg_lo:[0,1] neg_hi:[0,1]
	v_mul_f32_e32 v35, 0x39000000, v34
	v_cos_f32_e32 v34, v35
	v_sin_f32_e32 v35, v35
	v_mov_b32_e32 v45, v34
	v_pk_mul_f32 v[36:37], v[34:35], v[34:35]
	v_mul_f32_e64 v39, v34, -v35
	v_mov_b32_e32 v38, v36
	v_mov_b32_e32 v36, v37
	v_mov_b32_e32 v37, v39
	v_pk_add_f32 v[40:41], v[38:39], v[36:37] neg_lo:[0,1] neg_hi:[0,1]
	v_pk_add_f32 v[36:37], v[38:39], v[36:37]
	v_mov_b32_e32 v38, v40
	v_mov_b32_e32 v39, v37
	v_mov_b32_e32 v44, v35
	v_pk_mul_f32 v[42:43], v[34:35], v[38:39]
	v_pk_mul_f32 v[38:39], v[44:45], v[38:39]
	v_mad_u64_u32 v[44:45], s[8:9], v46, -3, v[162:163]
	v_bfe_i32 v45, v44, 5, 1
	v_bfe_i32 v52, v44, 6, 1
	v_and_b32_e32 v45, 5, v45
	v_and_b32_e32 v52, 26, v52
	v_pk_add_f32 v[46:47], v[26:27], v[30:31]
	v_bitop3_b32 v45, v45, v44, v52 bitop3:0x36
	v_pk_add_f32 v[26:27], v[26:27], v[30:31] neg_lo:[0,1] neg_hi:[0,1]
	v_pk_add_f32 v[50:51], v[46:47], v[48:49]
	v_lshlrev_b32_e32 v45, 3, v45
	v_pk_add_f32 v[30:31], v[26:27], v[28:29] op_sel:[0,1] op_sel_hi:[1,0]
	v_pk_add_f32 v[26:27], v[26:27], v[28:29] op_sel:[0,1] op_sel_hi:[1,0] neg_lo:[0,1] neg_hi:[0,1]
	ds_write_b64 v45, v[50:51]
	v_mov_b32_e32 v32, v35
	v_pk_mov_b32 v[50:51], v[26:27], v[30:31] op_sel:[1,0]
	v_mov_b32_e32 v28, v30
	v_mov_b32_e32 v29, v27
	v_pk_mul_f32 v[32:33], v[32:33], v[50:51] op_sel_hi:[0,1]
	v_pk_fma_f32 v[28:29], v[34:35], v[28:29], v[32:33] op_sel_hi:[0,1,1] neg_lo:[0,0,1] neg_hi:[0,0,1]
	v_pk_fma_f32 v[50:51], v[34:35], v[30:31], v[32:33]
	v_add_u32_e32 v28, s3, v44
	v_mov_b32_e32 v51, v29
	v_bfe_i32 v29, v28, 5, 1
	v_bfe_i32 v32, v28, 6, 1
	v_and_b32_e32 v29, 5, v29
	v_and_b32_e32 v32, 26, v32
	v_bitop3_b32 v28, v29, v28, v32 bitop3:0x36
	v_lshlrev_b32_e32 v28, 3, v28
	ds_write_b64 v28, v[50:51]
	v_pk_add_f32 v[28:29], v[46:47], v[48:49] neg_lo:[0,1] neg_hi:[0,1]
	s_nop 0
	v_pk_mul_f32 v[32:33], v[36:37], v[28:29] op_sel:[1,1] op_sel_hi:[1,0]
	s_nop 0
	v_pk_fma_f32 v[34:35], v[40:41], v[28:29], v[32:33] neg_lo:[0,0,1] neg_hi:[0,0,1]
	v_pk_fma_f32 v[28:29], v[40:41], v[28:29], v[32:33] op_sel_hi:[0,1,1]
	v_add_u32_e32 v28, s4, v44
	v_mov_b32_e32 v35, v29
	v_bfe_i32 v29, v28, 5, 1
	v_bfe_i32 v32, v28, 6, 1
	v_and_b32_e32 v29, 5, v29
	v_and_b32_e32 v32, 26, v32
	v_bitop3_b32 v28, v29, v28, v32 bitop3:0x36
	v_lshlrev_b32_e32 v28, 3, v28
	ds_write_b64 v28, v[34:35]
	v_mov_b32_e32 v29, v31
	v_pk_add_f32 v[34:35], v[38:39], v[38:39] op_sel:[1,0] op_sel_hi:[1,0] neg_lo:[0,1] neg_hi:[0,1]
	v_pk_mov_b32 v[30:31], v[30:31], v[26:27] op_sel:[1,0]
	v_mov_b32_e32 v28, v26
	v_pk_add_f32 v[32:33], v[42:43], v[42:43] op_sel:[0,1] op_sel_hi:[0,1]
	v_pk_mul_f32 v[30:31], v[34:35], v[30:31]
	v_and_b32_e32 v38, s5, v214
	v_pk_fma_f32 v[28:29], v[32:33], v[28:29], v[30:31]
	v_pk_fma_f32 v[26:27], v[32:33], v[26:27], v[30:31] neg_lo:[0,0,1] neg_hi:[0,0,1]
	v_add_u32_e32 v28, s2, v44
	v_mov_b32_e32 v27, v29
	v_bfe_i32 v29, v28, 5, 1
	v_bfe_i32 v30, v28, 6, 1
	v_and_b32_e32 v29, 5, v29
	v_and_b32_e32 v30, 26, v30
	v_bitop3_b32 v28, v29, v28, v30 bitop3:0x36
	v_lshlrev_b32_e32 v28, 3, v28
	ds_write_b64 v28, v[26:27]
	v_sub_u32_e32 v26, v214, v38
	v_cvt_f32_i32_e32 v26, v26
	v_pk_add_f32 v[40:41], v[20:21], v[24:25]
	v_pk_add_f32 v[20:21], v[20:21], v[24:25] neg_lo:[0,1] neg_hi:[0,1]
	v_mul_f32_e32 v27, 0x39000000, v26
	v_cos_f32_e32 v26, v27
	v_sin_f32_e32 v27, v27
	v_mov_b32_e32 v37, v26
	v_pk_mul_f32 v[28:29], v[26:27], v[26:27]
	v_mul_f32_e64 v31, v26, -v27
	v_mov_b32_e32 v30, v28
	v_mov_b32_e32 v28, v29
	v_mov_b32_e32 v29, v31
	v_pk_add_f32 v[32:33], v[30:31], v[28:29] neg_lo:[0,1] neg_hi:[0,1]
	v_pk_add_f32 v[28:29], v[30:31], v[28:29]
	v_mov_b32_e32 v30, v32
	v_mov_b32_e32 v31, v29
	v_mov_b32_e32 v36, v27
	v_pk_mul_f32 v[34:35], v[26:27], v[30:31]
	v_pk_mul_f32 v[30:31], v[36:37], v[30:31]
	v_mad_u64_u32 v[36:37], s[8:9], v38, -3, v[164:165]
	v_bfe_i32 v37, v36, 5, 1
	v_bfe_i32 v44, v36, 6, 1
	v_and_b32_e32 v37, 5, v37
	v_and_b32_e32 v44, 26, v44
	v_pk_add_f32 v[38:39], v[18:19], v[22:23]
	v_bitop3_b32 v37, v37, v36, v44 bitop3:0x36
	v_pk_add_f32 v[18:19], v[18:19], v[22:23] neg_lo:[0,1] neg_hi:[0,1]
	v_pk_add_f32 v[42:43], v[38:39], v[40:41]
	v_lshlrev_b32_e32 v37, 3, v37
	v_pk_add_f32 v[22:23], v[18:19], v[20:21] op_sel:[0,1] op_sel_hi:[1,0]
	v_pk_add_f32 v[18:19], v[18:19], v[20:21] op_sel:[0,1] op_sel_hi:[1,0] neg_lo:[0,1] neg_hi:[0,1]
	ds_write_b64 v37, v[42:43]
	v_mov_b32_e32 v24, v27
	v_pk_mov_b32 v[42:43], v[18:19], v[22:23] op_sel:[1,0]
	v_mov_b32_e32 v20, v22
	v_mov_b32_e32 v21, v19
	v_pk_mul_f32 v[24:25], v[24:25], v[42:43] op_sel_hi:[0,1]
	v_pk_fma_f32 v[20:21], v[26:27], v[20:21], v[24:25] op_sel_hi:[0,1,1] neg_lo:[0,0,1] neg_hi:[0,0,1]
	v_pk_fma_f32 v[42:43], v[26:27], v[22:23], v[24:25]
	v_add_u32_e32 v20, s3, v36
; DI f32x2 cmul(f32x2 a, f32x2 b) { return mkf2(a.x * b.x - a.y * b.y, a.x * b.y + a.y * b.x); }
; DI void fft8192(f32x2* buf, const f32x2* __restrict__ tw) {
;     ...
;   for (int ls = 0; ls < 12; ls += 2) {
;     const int s = 1 << ls;
;     f32x2 a[8], b[8], c[8], d[8];
;     __syncthreads();
; #pragma unroll
;     for (int e = 0; e < 8; ++e) {
;       const int i = tid + 256 * e;
;       const int pi = SW(i);
;       a[e] = buf[pi]; b[e] = buf[pi + 2048]; c[e] = buf[pi + 4096]; d[e] = buf[pi + 6144];
;     }
;     __syncthreads();
; #pragma unroll
;     for (int e = 0; e < 8; ++e) {
;       const int i = tid + 256 * e;
;       const int q = i & (s - 1);
;       const int ps = i - q;
;       const float rev = (float)ps * (1.f / 8192.f);
;       const f32x2 w1 = mkf2(__builtin_amdgcn_cosf(rev), -__builtin_amdgcn_sinf(rev));
;       const f32x2 w2 = cmul(w1, w1), w3 = cmul(w1, w2);
;       const f32x2 apc = mkf2(a[e].x + c[e].x, a[e].y + c[e].y), amc = mkf2(a[e].x - c[e].x, a[e].y - c[e].y);
;       const f32x2 bpd = mkf2(b[e].x + d[e].x, b[e].y + d[e].y), bmd = mkf2(b[e].x - d[e].x, b[e].y - d[e].y);
;       const int o = 4 * i - 3 * q;
;       buf[SW(o)] = mkf2(apc.x + bpd.x, apc.y + bpd.y);
;       buf[SW(o + s)] = cmul(w1, mkf2(amc.x + bmd.y, amc.y - bmd.x));
;       buf[SW(o + 2 * s)] = cmul(w2, mkf2(apc.x - bpd.x, apc.y - bpd.y));
;       buf[SW(o + 3 * s)] = cmul(w3, mkf2(amc.x - bmd.y, amc.y + bmd.x));
;     }
	v_mov_b32_e32 v43, v21
	v_bfe_i32 v21, v20, 5, 1
	v_bfe_i32 v24, v20, 6, 1
	v_and_b32_e32 v21, 5, v21
	v_and_b32_e32 v24, 26, v24
	v_bitop3_b32 v20, v21, v20, v24 bitop3:0x36
	v_lshlrev_b32_e32 v20, 3, v20
	ds_write_b64 v20, v[42:43]
	v_pk_add_f32 v[20:21], v[38:39], v[40:41] neg_lo:[0,1] neg_hi:[0,1]
	s_nop 0
	v_pk_mul_f32 v[24:25], v[28:29], v[20:21] op_sel:[1,1] op_sel_hi:[1,0]
	s_nop 0
	v_pk_fma_f32 v[26:27], v[32:33], v[20:21], v[24:25] neg_lo:[0,0,1] neg_hi:[0,0,1]
	v_pk_fma_f32 v[20:21], v[32:33], v[20:21], v[24:25] op_sel_hi:[0,1,1]
	v_add_u32_e32 v20, s4, v36
	v_mov_b32_e32 v27, v21
	v_bfe_i32 v21, v20, 5, 1
	v_bfe_i32 v24, v20, 6, 1
	v_and_b32_e32 v21, 5, v21
	v_and_b32_e32 v24, 26, v24
	v_bitop3_b32 v20, v21, v20, v24 bitop3:0x36
	v_lshlrev_b32_e32 v20, 3, v20
	ds_write_b64 v20, v[26:27]
	v_mov_b32_e32 v21, v23
	v_pk_add_f32 v[26:27], v[30:31], v[30:31] op_sel:[1,0] op_sel_hi:[1,0] neg_lo:[0,1] neg_hi:[0,1]
	v_pk_mov_b32 v[22:23], v[22:23], v[18:19] op_sel:[1,0]
	v_mov_b32_e32 v20, v18
	v_pk_add_f32 v[24:25], v[34:35], v[34:35] op_sel:[0,1] op_sel_hi:[0,1]
	v_pk_mul_f32 v[22:23], v[26:27], v[22:23]
	v_and_b32_e32 v30, s5, v216
	v_pk_fma_f32 v[20:21], v[24:25], v[20:21], v[22:23]
	v_pk_fma_f32 v[18:19], v[24:25], v[18:19], v[22:23] neg_lo:[0,0,1] neg_hi:[0,0,1]
	v_add_u32_e32 v20, s2, v36
	v_mov_b32_e32 v19, v21
	v_bfe_i32 v21, v20, 5, 1
	v_bfe_i32 v22, v20, 6, 1
	v_and_b32_e32 v21, 5, v21
	v_and_b32_e32 v22, 26, v22
	v_bitop3_b32 v20, v21, v20, v22 bitop3:0x36
	v_lshlrev_b32_e32 v20, 3, v20
	ds_write_b64 v20, v[18:19]
	v_sub_u32_e32 v18, v216, v30
	v_cvt_f32_i32_e32 v18, v18
	v_pk_add_f32 v[32:33], v[12:13], v[16:17]
	v_pk_add_f32 v[12:13], v[12:13], v[16:17] neg_lo:[0,1] neg_hi:[0,1]
	v_mul_f32_e32 v19, 0x39000000, v18
	v_cos_f32_e32 v18, v19
	v_sin_f32_e32 v19, v19
	v_mov_b32_e32 v29, v18
	v_pk_mul_f32 v[20:21], v[18:19], v[18:19]
	v_mul_f32_e64 v23, v18, -v19
	v_mov_b32_e32 v22, v20
	v_mov_b32_e32 v20, v21
	v_mov_b32_e32 v21, v23
	v_pk_add_f32 v[24:25], v[22:23], v[20:21] neg_lo:[0,1] neg_hi:[0,1]
	v_pk_add_f32 v[20:21], v[22:23], v[20:21]
	v_mov_b32_e32 v22, v24
	v_mov_b32_e32 v23, v21
	v_mov_b32_e32 v28, v19
	v_pk_mul_f32 v[26:27], v[18:19], v[22:23]
	v_pk_mul_f32 v[22:23], v[28:29], v[22:23]
	v_mad_u64_u32 v[28:29], s[8:9], v30, -3, v[166:167]
	v_bfe_i32 v29, v28, 5, 1
	v_bfe_i32 v36, v28, 6, 1
	v_and_b32_e32 v29, 5, v29
	v_and_b32_e32 v36, 26, v36
	v_pk_add_f32 v[30:31], v[10:11], v[14:15]
	v_bitop3_b32 v29, v29, v28, v36 bitop3:0x36
	v_pk_add_f32 v[10:11], v[10:11], v[14:15] neg_lo:[0,1] neg_hi:[0,1]
	v_pk_add_f32 v[34:35], v[30:31], v[32:33]
	v_lshlrev_b32_e32 v29, 3, v29
	v_pk_add_f32 v[14:15], v[10:11], v[12:13] op_sel:[0,1] op_sel_hi:[1,0]
	v_pk_add_f32 v[10:11], v[10:11], v[12:13] op_sel:[0,1] op_sel_hi:[1,0] neg_lo:[0,1] neg_hi:[0,1]
	ds_write_b64 v29, v[34:35]
	v_mov_b32_e32 v16, v19
	v_pk_mov_b32 v[34:35], v[10:11], v[14:15] op_sel:[1,0]
	v_mov_b32_e32 v12, v14
	v_mov_b32_e32 v13, v11
	v_pk_mul_f32 v[16:17], v[16:17], v[34:35] op_sel_hi:[0,1]
	v_pk_fma_f32 v[12:13], v[18:19], v[12:13], v[16:17] op_sel_hi:[0,1,1] neg_lo:[0,0,1] neg_hi:[0,0,1]
	v_pk_fma_f32 v[34:35], v[18:19], v[14:15], v[16:17]
	v_add_u32_e32 v12, s3, v28
	v_mov_b32_e32 v35, v13
	v_bfe_i32 v13, v12, 5, 1
	v_bfe_i32 v16, v12, 6, 1
	v_and_b32_e32 v13, 5, v13
	v_and_b32_e32 v16, 26, v16
	v_bitop3_b32 v12, v13, v12, v16 bitop3:0x36
	v_lshlrev_b32_e32 v12, 3, v12
	ds_write_b64 v12, v[34:35]
	v_pk_add_f32 v[12:13], v[30:31], v[32:33] neg_lo:[0,1] neg_hi:[0,1]
	s_nop 0
	v_pk_mul_f32 v[16:17], v[20:21], v[12:13] op_sel:[1,1] op_sel_hi:[1,0]
	s_nop 0
	v_pk_fma_f32 v[18:19], v[24:25], v[12:13], v[16:17] neg_lo:[0,0,1] neg_hi:[0,0,1]
	v_pk_fma_f32 v[12:13], v[24:25], v[12:13], v[16:17] op_sel_hi:[0,1,1]
	v_add_u32_e32 v12, s4, v28
	v_mov_b32_e32 v19, v13
	v_bfe_i32 v13, v12, 5, 1
	v_bfe_i32 v16, v12, 6, 1
	v_and_b32_e32 v13, 5, v13
	v_and_b32_e32 v16, 26, v16
	v_bitop3_b32 v12, v13, v12, v16 bitop3:0x36
	v_lshlrev_b32_e32 v12, 3, v12
	ds_write_b64 v12, v[18:19]
	v_mov_b32_e32 v13, v15
	v_pk_add_f32 v[18:19], v[22:23], v[22:23] op_sel:[1,0] op_sel_hi:[1,0] neg_lo:[0,1] neg_hi:[0,1]
	v_pk_mov_b32 v[14:15], v[14:15], v[10:11] op_sel:[1,0]
	v_mov_b32_e32 v12, v10
	v_pk_add_f32 v[16:17], v[26:27], v[26:27] op_sel:[0,1] op_sel_hi:[0,1]
	v_pk_mul_f32 v[14:15], v[18:19], v[14:15]
	v_and_b32_e32 v22, s5, v237
	v_pk_fma_f32 v[12:13], v[16:17], v[12:13], v[14:15]
	v_pk_fma_f32 v[10:11], v[16:17], v[10:11], v[14:15] neg_lo:[0,0,1] neg_hi:[0,0,1]
	v_add_u32_e32 v12, s2, v28
	v_mov_b32_e32 v11, v13
	v_bfe_i32 v13, v12, 5, 1
	v_bfe_i32 v14, v12, 6, 1
	v_and_b32_e32 v13, 5, v13
	v_and_b32_e32 v14, 26, v14
	v_bitop3_b32 v12, v13, v12, v14 bitop3:0x36
	v_lshlrev_b32_e32 v12, 3, v12
	ds_write_b64 v12, v[10:11]
	v_sub_u32_e32 v10, v237, v22
	v_cvt_f32_i32_e32 v10, v10
	v_pk_add_f32 v[24:25], v[4:5], v[8:9]
	v_pk_add_f32 v[4:5], v[4:5], v[8:9] neg_lo:[0,1] neg_hi:[0,1]
	v_mul_f32_e32 v11, 0x39000000, v10
	v_cos_f32_e32 v10, v11
	v_sin_f32_e32 v11, v11
	v_mov_b32_e32 v21, v10
	v_pk_mul_f32 v[12:13], v[10:11], v[10:11]
	v_mul_f32_e64 v15, v10, -v11
	v_mov_b32_e32 v14, v12
	v_mov_b32_e32 v12, v13
	v_mov_b32_e32 v13, v15
	v_pk_add_f32 v[16:17], v[14:15], v[12:13] neg_lo:[0,1] neg_hi:[0,1]
	v_pk_add_f32 v[12:13], v[14:15], v[12:13]
	v_mov_b32_e32 v14, v16
	v_mov_b32_e32 v15, v13
	v_mov_b32_e32 v20, v11
	v_pk_mul_f32 v[18:19], v[10:11], v[14:15]
	v_pk_mul_f32 v[14:15], v[20:21], v[14:15]
	v_mad_u64_u32 v[20:21], s[8:9], v22, -3, v[168:169]
	v_bfe_i32 v21, v20, 5, 1
	v_bfe_i32 v28, v20, 6, 1
	v_and_b32_e32 v21, 5, v21
	v_and_b32_e32 v28, 26, v28
	v_pk_add_f32 v[22:23], v[2:3], v[6:7]
; DI f32x2 cmul(f32x2 a, f32x2 b) { return mkf2(a.x * b.x - a.y * b.y, a.x * b.y + a.y * b.x); }
; DI void fft8192(f32x2* buf, const f32x2* __restrict__ tw) {
;     ...
;   for (int ls = 0; ls < 12; ls += 2) {
;     const int s = 1 << ls;
;     f32x2 a[8], b[8], c[8], d[8];
;     __syncthreads();
; #pragma unroll
;     for (int e = 0; e < 8; ++e) {
;       const int i = tid + 256 * e;
;       const int pi = SW(i);
;       a[e] = buf[pi]; b[e] = buf[pi + 2048]; c[e] = buf[pi + 4096]; d[e] = buf[pi + 6144];
;     }
;     __syncthreads();
; #pragma unroll
;     for (int e = 0; e < 8; ++e) {
;       const int i = tid + 256 * e;
;       const int q = i & (s - 1);
;       const int ps = i - q;
;       const float rev = (float)ps * (1.f / 8192.f);
;       const f32x2 w1 = mkf2(__builtin_amdgcn_cosf(rev), -__builtin_amdgcn_sinf(rev));
;       const f32x2 w2 = cmul(w1, w1), w3 = cmul(w1, w2);
;       const f32x2 apc = mkf2(a[e].x + c[e].x, a[e].y + c[e].y), amc = mkf2(a[e].x - c[e].x, a[e].y - c[e].y);
;       const f32x2 bpd = mkf2(b[e].x + d[e].x, b[e].y + d[e].y), bmd = mkf2(b[e].x - d[e].x, b[e].y - d[e].y);
;       const int o = 4 * i - 3 * q;
;       buf[SW(o)] = mkf2(apc.x + bpd.x, apc.y + bpd.y);
;       buf[SW(o + s)] = cmul(w1, mkf2(amc.x + bmd.y, amc.y - bmd.x));
;       buf[SW(o + 2 * s)] = cmul(w2, mkf2(apc.x - bpd.x, apc.y - bpd.y));
;       buf[SW(o + 3 * s)] = cmul(w3, mkf2(amc.x - bmd.y, amc.y + bmd.x));
;     }
;   }
;   {
;     f32x2 a[16], b[16];
;     __syncthreads();
; #pragma unroll
;     for (int e = 0; e < 16; ++e) { const int pi = SW(tid + 256 * e); a[e] = buf[pi]; b[e] = buf[pi + 4096]; }
;     __syncthreads();
; #pragma unroll
;     for (int e = 0; e < 16; ++e) {
;       const int pi = SW(tid + 256 * e);
;       buf[pi] = mkf2(a[e].x + b[e].x, a[e].y + b[e].y);
;       buf[pi + 4096] = mkf2(a[e].x - b[e].x, a[e].y - b[e].y);
;     }
;     __syncthreads();
	v_bitop3_b32 v21, v21, v20, v28 bitop3:0x36
	v_pk_add_f32 v[2:3], v[2:3], v[6:7] neg_lo:[0,1] neg_hi:[0,1]
	v_pk_add_f32 v[26:27], v[22:23], v[24:25]
	v_lshlrev_b32_e32 v21, 3, v21
	v_pk_add_f32 v[6:7], v[2:3], v[4:5] op_sel:[0,1] op_sel_hi:[1,0]
	v_pk_add_f32 v[2:3], v[2:3], v[4:5] op_sel:[0,1] op_sel_hi:[1,0] neg_lo:[0,1] neg_hi:[0,1]
	ds_write_b64 v21, v[26:27]
	v_mov_b32_e32 v8, v11
	v_pk_mov_b32 v[26:27], v[2:3], v[6:7] op_sel:[1,0]
	v_mov_b32_e32 v4, v6
	v_mov_b32_e32 v5, v3
	v_pk_mul_f32 v[8:9], v[8:9], v[26:27] op_sel_hi:[0,1]
	v_pk_fma_f32 v[4:5], v[10:11], v[4:5], v[8:9] op_sel_hi:[0,1,1] neg_lo:[0,0,1] neg_hi:[0,0,1]
	v_pk_fma_f32 v[26:27], v[10:11], v[6:7], v[8:9]
	v_add_u32_e32 v4, s3, v20
	v_mov_b32_e32 v27, v5
	v_bfe_i32 v5, v4, 5, 1
	v_bfe_i32 v8, v4, 6, 1
	v_and_b32_e32 v5, 5, v5
	v_and_b32_e32 v8, 26, v8
	v_bitop3_b32 v4, v5, v4, v8 bitop3:0x36
	v_lshlrev_b32_e32 v4, 3, v4
	ds_write_b64 v4, v[26:27]
	v_pk_add_f32 v[4:5], v[22:23], v[24:25] neg_lo:[0,1] neg_hi:[0,1]
	s_nop 0
	v_pk_mul_f32 v[8:9], v[12:13], v[4:5] op_sel:[1,1] op_sel_hi:[1,0]
	s_nop 0
	v_pk_fma_f32 v[10:11], v[16:17], v[4:5], v[8:9] neg_lo:[0,0,1] neg_hi:[0,0,1]
	v_pk_fma_f32 v[4:5], v[16:17], v[4:5], v[8:9] op_sel_hi:[0,1,1]
	v_add_u32_e32 v4, s4, v20
	v_mov_b32_e32 v11, v5
	v_bfe_i32 v5, v4, 5, 1
	v_bfe_i32 v8, v4, 6, 1
	v_and_b32_e32 v5, 5, v5
	v_and_b32_e32 v8, 26, v8
	v_bitop3_b32 v4, v5, v4, v8 bitop3:0x36
	v_lshlrev_b32_e32 v4, 3, v4
	ds_write_b64 v4, v[10:11]
	v_mov_b32_e32 v5, v7
	v_pk_add_f32 v[10:11], v[14:15], v[14:15] op_sel:[1,0] op_sel_hi:[1,0] neg_lo:[0,1] neg_hi:[0,1]
	v_pk_mov_b32 v[6:7], v[6:7], v[2:3] op_sel:[1,0]
	v_mov_b32_e32 v4, v2
	v_pk_add_f32 v[8:9], v[18:19], v[18:19] op_sel:[0,1] op_sel_hi:[0,1]
	v_pk_mul_f32 v[6:7], v[10:11], v[6:7]
	s_nop 0
	v_pk_fma_f32 v[4:5], v[8:9], v[4:5], v[6:7]
	v_pk_fma_f32 v[2:3], v[8:9], v[2:3], v[6:7] neg_lo:[0,0,1] neg_hi:[0,0,1]
	v_add_u32_e32 v4, s2, v20
	v_mov_b32_e32 v3, v5
	v_bfe_i32 v5, v4, 5, 1
	v_bfe_i32 v6, v4, 6, 1
	v_and_b32_e32 v5, 5, v5
	v_and_b32_e32 v6, 26, v6
	v_bitop3_b32 v4, v5, v4, v6 bitop3:0x36
	s_add_i32 s2, s7, 2
	s_add_i32 s7, s7, 4
	v_lshlrev_b32_e32 v4, 3, v4
	s_cmp_lt_u32 s2, 10
	ds_write_b64 v4, v[2:3]
	s_cbranch_scc1 .LBB0_990
	s_lshl_b32 s2, s83, 11
	s_lshl_b32 s4, s78, 10
	v_add_u32_e32 v34, 0x800, v208
	v_add_u32_e32 v38, 0x900, v208
	v_add_u32_e32 v42, 0xa00, v208
	v_add_u32_e32 v46, 0xb00, v208
	v_add_u32_e32 v50, 0xc00, v208
	v_add_u32_e32 v54, 0xd00, v208
	v_add_u32_e32 v58, 0xe00, v208
	v_add_u32_e32 v62, 0xf00, v208
	s_sub_i32 s2, s28, s2
	s_sub_i32 s4, s6, s4
	s_waitcnt lgkmcnt(0)
	s_barrier
	ds_read2st64_b64 v[2:5], v198 offset1:64
	ds_read2st64_b64 v[6:9], v201 offset1:64
	ds_read2st64_b64 v[10:13], v202 offset1:64
	ds_read2st64_b64 v[14:17], v203 offset1:64
	ds_read2st64_b64 v[18:21], v204 offset1:64
	ds_read2st64_b64 v[22:25], v205 offset1:64
	ds_read2st64_b64 v[26:29], v206 offset1:64
	ds_read2st64_b64 v[30:33], v207 offset1:64
	v_xor_b32_e32 v34, v209, v34
	v_xor_b32_e32 v38, v209, v38
	v_xor_b32_e32 v42, v209, v42
	v_xor_b32_e32 v46, v209, v46
	v_xor_b32_e32 v50, v209, v50
	v_xor_b32_e32 v54, v209, v54
	v_xor_b32_e32 v58, v209, v58
	v_xor_b32_e32 v62, v209, v62
	s_ashr_i32 s3, s2, 31
	s_ashr_i32 s5, s4, 31
	v_lshlrev_b32_e32 v154, 3, v34
	v_lshlrev_b32_e32 v156, 3, v38
	v_lshlrev_b32_e32 v158, 3, v42
	v_lshlrev_b32_e32 v160, 3, v46
	v_lshlrev_b32_e32 v162, 3, v50
	v_lshlrev_b32_e32 v164, 3, v54
	v_lshlrev_b32_e32 v166, 3, v58
	v_lshlrev_b32_e32 v168, 3, v62
	s_waitcnt lgkmcnt(7)
	v_pk_add_f32 v[208:209], v[2:3], v[4:5]
	v_pk_add_f32 v[2:3], v[2:3], v[4:5] neg_lo:[0,1] neg_hi:[0,1]
	s_lshl_b64 s[2:3], s[2:3], 13
	s_lshl_b64 s[4:5], s[4:5], 13
	ds_read2st64_b64 v[34:37], v154 offset1:64
	ds_read2st64_b64 v[38:41], v156 offset1:64
	ds_read2st64_b64 v[42:45], v158 offset1:64
	ds_read2st64_b64 v[46:49], v160 offset1:64
	ds_read2st64_b64 v[50:53], v162 offset1:64
	ds_read2st64_b64 v[54:57], v164 offset1:64
	ds_read2st64_b64 v[58:61], v166 offset1:64
	ds_read2st64_b64 v[62:65], v168 offset1:64
	s_waitcnt lgkmcnt(0)
	s_barrier
	ds_write2st64_b64 v198, v[208:209], v[2:3] offset1:64
	v_pk_add_f32 v[2:3], v[6:7], v[8:9]
	v_pk_add_f32 v[4:5], v[6:7], v[8:9] neg_lo:[0,1] neg_hi:[0,1]
	s_add_u32 s8, s55, s2
	ds_write2st64_b64 v201, v[2:3], v[4:5] offset1:64
	v_pk_add_f32 v[2:3], v[10:11], v[12:13]
	v_pk_add_f32 v[4:5], v[10:11], v[12:13] neg_lo:[0,1] neg_hi:[0,1]
	s_addc_u32 s9, s81, s3
	ds_write2st64_b64 v202, v[2:3], v[4:5] offset1:64
	v_pk_add_f32 v[2:3], v[14:15], v[16:17]
	v_pk_add_f32 v[4:5], v[14:15], v[16:17] neg_lo:[0,1] neg_hi:[0,1]
	s_add_u32 s10, s55, s4
	ds_write2st64_b64 v203, v[2:3], v[4:5] offset1:64
	v_pk_add_f32 v[2:3], v[18:19], v[20:21]
	v_pk_add_f32 v[4:5], v[18:19], v[20:21] neg_lo:[0,1] neg_hi:[0,1]
	s_addc_u32 s11, s81, s5
	ds_write2st64_b64 v204, v[2:3], v[4:5] offset1:64
	v_pk_add_f32 v[2:3], v[22:23], v[24:25]
	v_pk_add_f32 v[4:5], v[22:23], v[24:25] neg_lo:[0,1] neg_hi:[0,1]
	s_add_i32 s2, s82, s21
	ds_write2st64_b64 v205, v[2:3], v[4:5] offset1:64
	v_pk_add_f32 v[2:3], v[26:27], v[28:29]
	v_pk_add_f32 v[4:5], v[26:27], v[28:29] neg_lo:[0,1] neg_hi:[0,1]
	s_ashr_i32 s3, s2, 31
	ds_write2st64_b64 v206, v[2:3], v[4:5] offset1:64
	v_pk_add_f32 v[2:3], v[30:31], v[32:33]
	v_pk_add_f32 v[4:5], v[30:31], v[32:33] neg_lo:[0,1] neg_hi:[0,1]
	s_lshl_b64 s[2:3], s[2:3], 13
	ds_write2st64_b64 v207, v[2:3], v[4:5] offset1:64
	v_pk_add_f32 v[2:3], v[34:35], v[36:37]
	v_pk_add_f32 v[4:5], v[34:35], v[36:37] neg_lo:[0,1] neg_hi:[0,1]
	s_add_u32 s6, s80, s2
	ds_write2st64_b64 v154, v[2:3], v[4:5] offset1:64
	v_pk_add_f32 v[2:3], v[38:39], v[40:41]
; DI void fft8192(f32x2* buf, const f32x2* __restrict__ tw) {
;     ...
;     __syncthreads();
; #pragma unroll
;     for (int e = 0; e < 16; ++e) { const int pi = SW(tid + 256 * e); a[e] = buf[pi]; b[e] = buf[pi + 4096]; }
;     __syncthreads();
; #pragma unroll
;     for (int e = 0; e < 16; ++e) {
;       const int pi = SW(tid + 256 * e);
;       buf[pi] = mkf2(a[e].x + b[e].x, a[e].y + b[e].y);
;       buf[pi + 4096] = mkf2(a[e].x - b[e].x, a[e].y - b[e].y);
;     }
;     __syncthreads();
; DI void hyena_unit(KP p, int l, int c, char* smem) {
;     ...
;       const u16* g0 = Zhy + (size_t)(b0 * 1536 + gcol) * 4096;
;       const u16* g1 = Zhy + (size_t)(b1 * 1536 + gcol) * 4096;
; #pragma unroll 4
;       for (int jj = 0; jj < 16; ++jj) {
;         const int t = tid + 256 * jj;
;         const f32x2 r = buf[SW(t)];
;         const float y0 = r.x * (1.f / 8192.f), y1 = -r.y * (1.f / 8192.f);
;         const float x0 = sconv3(g0, t, 4096, gw0, gw1, gw2, gb), x1 = sconv3(g1, t, 4096, gw0, gw1, gw2, gb);
;         if (o == 0) { r0[t] = f2bf(x0 * y0); r1[t] = f2bf(x1 * y1); }
;         else { y0p[t] = f2bf(x0 * y0); y1p[t] = f2bf(x1 * y1); }
;       }
	v_pk_add_f32 v[4:5], v[38:39], v[40:41] neg_lo:[0,1] neg_hi:[0,1]
	s_addc_u32 s7, s76, s3
	s_add_i32 s4, s29, s21
	ds_write2st64_b64 v156, v[2:3], v[4:5] offset1:64
	v_pk_add_f32 v[2:3], v[42:43], v[44:45]
	v_pk_add_f32 v[4:5], v[42:43], v[44:45] neg_lo:[0,1] neg_hi:[0,1]
	s_ashr_i32 s5, s4, 31
	ds_write2st64_b64 v158, v[2:3], v[4:5] offset1:64
	v_pk_add_f32 v[2:3], v[46:47], v[48:49]
	v_pk_add_f32 v[4:5], v[46:47], v[48:49] neg_lo:[0,1] neg_hi:[0,1]
	s_lshl_b64 s[4:5], s[4:5], 13
	ds_write2st64_b64 v160, v[2:3], v[4:5] offset1:64
	v_pk_add_f32 v[2:3], v[50:51], v[52:53]
	v_pk_add_f32 v[4:5], v[50:51], v[52:53] neg_lo:[0,1] neg_hi:[0,1]
	s_add_u32 s12, s80, s4
	ds_write2st64_b64 v162, v[2:3], v[4:5] offset1:64
	v_pk_add_f32 v[2:3], v[54:55], v[56:57]
	v_pk_add_f32 v[4:5], v[54:55], v[56:57] neg_lo:[0,1] neg_hi:[0,1]
	s_addc_u32 s13, s76, s5
	ds_write2st64_b64 v164, v[2:3], v[4:5] offset1:64
	v_pk_add_f32 v[2:3], v[58:59], v[60:61]
	v_pk_add_f32 v[4:5], v[58:59], v[60:61] neg_lo:[0,1] neg_hi:[0,1]
	s_and_b64 s[4:5], s[96:97], exec
	ds_write2st64_b64 v166, v[2:3], v[4:5] offset1:64
	v_pk_add_f32 v[2:3], v[62:63], v[64:65]
	v_pk_add_f32 v[4:5], v[62:63], v[64:65] neg_lo:[0,1] neg_hi:[0,1]
	s_cselect_b32 s5, s25, s9
	s_cselect_b32 s4, s24, s8
	ds_write2st64_b64 v168, v[2:3], v[4:5] offset1:64
	s_cselect_b32 s9, s27, s11
	s_cselect_b32 s8, s26, s10
	v_lshl_add_u64 v[4:5], s[4:5], 0, v[68:69]
	s_add_i32 s4, s77, s82
	s_ashr_i32 s5, s4, 31
	s_lshl_b64 s[4:5], s[4:5], 13
	v_lshl_add_u64 v[2:3], s[8:9], 0, v[68:69]
	v_lshl_add_u64 v[6:7], v[70:71], 0, s[4:5]
	v_lshl_add_u64 v[8:9], v[70:71], 0, s[2:3]
	s_mov_b64 s[22:23], 0
	v_mov_b32_e32 v198, v66
	s_waitcnt lgkmcnt(0)
	s_barrier
	v_lshlrev_b32_e32 v201, 1, v66
	v_xor_b32_e32 v203, v66, v155
	v_add_u32_e32 v202, 0x1000, v201
	v_lshlrev_b32_e32 v203, 3, v203
	s_mov_b64 s[8:9], 0x1000
	v_lshl_add_u64 v[204:205], v[4:5], 0, s[8:9]
	v_lshl_add_u64 v[206:207], v[2:3], 0, s[8:9]
	v_cmp_eq_u32_e64 s[8:9], 0, v66
	v_cmp_eq_u32_e32 vcc, 0xff, v66
	s_mov_b64 s[10:11], vcc
	ds_read_b64 v[224:225], v203
	ds_read_b64 v[226:227], v203 offset:2048
	ds_read_b64 v[230:231], v203 offset:4096
	ds_read_b64 v[232:233], v203 offset:6144
	ds_read_b64 v[236:237], v203 offset:8192
	ds_read_b64 v[238:239], v203 offset:10240
	ds_read_b64 v[240:241], v203 offset:12288
	ds_read_b64 v[244:245], v203 offset:14336
	global_load_ushort v10, v201, s[6:7] offset:-2
	global_load_ushort v11, v201, s[6:7] offset:0
	global_load_ushort v12, v201, s[6:7] offset:2
	global_load_ushort v13, v201, s[12:13] offset:-2
	global_load_ushort v14, v201, s[12:13] offset:0
	global_load_ushort v15, v201, s[12:13] offset:2
	global_load_ushort v16, v201, s[6:7] offset:510
	global_load_ushort v17, v201, s[6:7] offset:512
	global_load_ushort v18, v201, s[6:7] offset:514
	global_load_ushort v19, v201, s[12:13] offset:510
	global_load_ushort v20, v201, s[12:13] offset:512
	global_load_ushort v21, v201, s[12:13] offset:514
	global_load_ushort v22, v201, s[6:7] offset:1022
	global_load_ushort v23, v201, s[6:7] offset:1024
	global_load_ushort v24, v201, s[6:7] offset:1026
	global_load_ushort v25, v201, s[12:13] offset:1022
	global_load_ushort v26, v201, s[12:13] offset:1024
	global_load_ushort v27, v201, s[12:13] offset:1026
	global_load_ushort v28, v201, s[6:7] offset:1534
	global_load_ushort v29, v201, s[6:7] offset:1536
	global_load_ushort v30, v201, s[6:7] offset:1538
	global_load_ushort v31, v201, s[12:13] offset:1534
	global_load_ushort v32, v201, s[12:13] offset:1536
	global_load_ushort v34, v201, s[12:13] offset:1538
	global_load_ushort v35, v201, s[6:7] offset:2046
	global_load_ushort v36, v201, s[6:7] offset:2048
	global_load_ushort v37, v201, s[6:7] offset:2050
	global_load_ushort v38, v201, s[12:13] offset:2046
	global_load_ushort v39, v201, s[12:13] offset:2048
	global_load_ushort v40, v201, s[12:13] offset:2050
	global_load_ushort v41, v201, s[6:7] offset:2558
	global_load_ushort v42, v201, s[6:7] offset:2560
	global_load_ushort v43, v201, s[6:7] offset:2562
	global_load_ushort v44, v201, s[12:13] offset:2558
	global_load_ushort v45, v201, s[12:13] offset:2560
	global_load_ushort v46, v201, s[12:13] offset:2562
	global_load_ushort v47, v201, s[6:7] offset:3070
	global_load_ushort v48, v201, s[6:7] offset:3072
	global_load_ushort v49, v201, s[6:7] offset:3074
	global_load_ushort v50, v201, s[12:13] offset:3070
	global_load_ushort v51, v201, s[12:13] offset:3072
	global_load_ushort v52, v201, s[12:13] offset:3074
	global_load_ushort v53, v201, s[6:7] offset:3582
	global_load_ushort v54, v201, s[6:7] offset:3584
	global_load_ushort v55, v201, s[6:7] offset:3586
	global_load_ushort v56, v201, s[12:13] offset:3582
	global_load_ushort v57, v201, s[12:13] offset:3584
	global_load_ushort v58, v201, s[12:13] offset:3586
	s_waitcnt vmcnt(42)
	s_waitcnt lgkmcnt(0)
	v_cndmask_b32_e64 v10, v10, 0, s[8:9]
	v_cndmask_b32_e64 v13, v13, 0, s[8:9]
	v_lshlrev_b32_e32 v10, 16, v10
	v_lshlrev_b32_e32 v11, 16, v11
	v_lshlrev_b32_e32 v12, 16, v12
	v_lshlrev_b32_e32 v13, 16, v13
	v_lshlrev_b32_e32 v14, 16, v14
	v_lshlrev_b32_e32 v15, 16, v15
	v_mul_f32_e32 v11, v196, v11
	v_mul_f32_e32 v14, v196, v14
	v_fmac_f32_e32 v11, v74, v10
	v_fmac_f32_e32 v14, v74, v13
	v_fmac_f32_e32 v11, v75, v12
	v_fmac_f32_e32 v14, v75, v15
	v_mul_f32_e32 v10, 0x39000000, v224
	v_mul_f32_e32 v13, 0xb9000000, v225
	v_add_f32_e32 v11, v195, v11
	v_add_f32_e32 v14, v195, v14
	v_mul_f32_e32 v10, v10, v11
	v_mul_f32_e32 v13, v13, v14
	v_cvt_pk_bf16_f32 v10, v10, v10
	v_cvt_pk_bf16_f32 v13, v13, v13
	global_store_short v[4:5], v10, off
	global_store_short v[2:3], v13, off
	s_waitcnt vmcnt(38)
; DI float bf2f(u16 v) { return __uint_as_float(((unsigned)v) << 16); }
; DI float sconv3(const u16* row, int t, int n, float w0, float w1, float w2, float bias) {
;   float xm = (t > 0) ? bf2f(row[t - 1]) : 0.f, x0 = bf2f(row[t]), xp = (t + 1 < n) ? bf2f(row[t + 1]) : 0.f;
;   return w0 * xm + w1 * x0 + w2 * xp + bias;
; }
; DI void hyena_unit(KP p, int l, int c, char* smem) {
;     ...
;       const u16* g0 = Zhy + (size_t)(b0 * 1536 + gcol) * 4096;
;       const u16* g1 = Zhy + (size_t)(b1 * 1536 + gcol) * 4096;
; #pragma unroll 4
;       for (int jj = 0; jj < 16; ++jj) {
;         const int t = tid + 256 * jj;
;         const f32x2 r = buf[SW(t)];
;         const float y0 = r.x * (1.f / 8192.f), y1 = -r.y * (1.f / 8192.f);
;         const float x0 = sconv3(g0, t, 4096, gw0, gw1, gw2, gb), x1 = sconv3(g1, t, 4096, gw0, gw1, gw2, gb);
;         if (o == 0) { r0[t] = f2bf(x0 * y0); r1[t] = f2bf(x1 * y1); }
;         else { y0p[t] = f2bf(x0 * y0); y1p[t] = f2bf(x1 * y1); }
;       }
	v_lshlrev_b32_e32 v16, 16, v16
	v_lshlrev_b32_e32 v17, 16, v17
	v_lshlrev_b32_e32 v18, 16, v18
	v_lshlrev_b32_e32 v19, 16, v19
	v_lshlrev_b32_e32 v20, 16, v20
	v_lshlrev_b32_e32 v21, 16, v21
	v_mul_f32_e32 v17, v196, v17
	v_mul_f32_e32 v20, v196, v20
	v_fmac_f32_e32 v17, v74, v16
	v_fmac_f32_e32 v20, v74, v19
	v_fmac_f32_e32 v17, v75, v18
	v_fmac_f32_e32 v20, v75, v21
	v_mul_f32_e32 v16, 0x39000000, v226
	v_mul_f32_e32 v19, 0xb9000000, v227
	v_add_f32_e32 v17, v195, v17
	v_add_f32_e32 v20, v195, v20
	v_mul_f32_e32 v16, v16, v17
	v_mul_f32_e32 v19, v19, v20
	v_cvt_pk_bf16_f32 v16, v16, v16
	v_cvt_pk_bf16_f32 v19, v19, v19
	global_store_short v[4:5], v16, off offset:512
	global_store_short v[2:3], v19, off offset:512
	s_waitcnt vmcnt(34)
	v_lshlrev_b32_e32 v22, 16, v22
	v_lshlrev_b32_e32 v23, 16, v23
	v_lshlrev_b32_e32 v24, 16, v24
	v_lshlrev_b32_e32 v25, 16, v25
	v_lshlrev_b32_e32 v26, 16, v26
	v_lshlrev_b32_e32 v27, 16, v27
	v_mul_f32_e32 v23, v196, v23
	v_mul_f32_e32 v26, v196, v26
	v_fmac_f32_e32 v23, v74, v22
	v_fmac_f32_e32 v26, v74, v25
	v_fmac_f32_e32 v23, v75, v24
	v_fmac_f32_e32 v26, v75, v27
	v_mul_f32_e32 v22, 0x39000000, v230
	v_mul_f32_e32 v25, 0xb9000000, v231
	v_add_f32_e32 v23, v195, v23
	v_add_f32_e32 v26, v195, v26
	v_mul_f32_e32 v22, v22, v23
	v_mul_f32_e32 v25, v25, v26
	v_cvt_pk_bf16_f32 v22, v22, v22
	v_cvt_pk_bf16_f32 v25, v25, v25
	global_store_short v[4:5], v22, off offset:1024
	global_store_short v[2:3], v25, off offset:1024
	s_waitcnt vmcnt(30)
	v_lshlrev_b32_e32 v28, 16, v28
	v_lshlrev_b32_e32 v29, 16, v29
	v_lshlrev_b32_e32 v30, 16, v30
	v_lshlrev_b32_e32 v31, 16, v31
	v_lshlrev_b32_e32 v32, 16, v32
	v_lshlrev_b32_e32 v34, 16, v34
	v_mul_f32_e32 v29, v196, v29
	v_mul_f32_e32 v32, v196, v32
	v_fmac_f32_e32 v29, v74, v28
	v_fmac_f32_e32 v32, v74, v31
	v_fmac_f32_e32 v29, v75, v30
	v_fmac_f32_e32 v32, v75, v34
	v_mul_f32_e32 v28, 0x39000000, v232
	v_mul_f32_e32 v31, 0xb9000000, v233
	v_add_f32_e32 v29, v195, v29
	v_add_f32_e32 v32, v195, v32
	v_mul_f32_e32 v28, v28, v29
	v_mul_f32_e32 v31, v31, v32
	v_cvt_pk_bf16_f32 v28, v28, v28
	v_cvt_pk_bf16_f32 v31, v31, v31
	global_store_short v[4:5], v28, off offset:1536
	global_store_short v[2:3], v31, off offset:1536
	s_waitcnt vmcnt(26)
	v_lshlrev_b32_e32 v35, 16, v35
	v_lshlrev_b32_e32 v36, 16, v36
	v_lshlrev_b32_e32 v37, 16, v37
	v_lshlrev_b32_e32 v38, 16, v38
	v_lshlrev_b32_e32 v39, 16, v39
	v_lshlrev_b32_e32 v40, 16, v40
	v_mul_f32_e32 v36, v196, v36
	v_mul_f32_e32 v39, v196, v39
	v_fmac_f32_e32 v36, v74, v35
	v_fmac_f32_e32 v39, v74, v38
	v_fmac_f32_e32 v36, v75, v37
	v_fmac_f32_e32 v39, v75, v40
	v_mul_f32_e32 v35, 0x39000000, v236
	v_mul_f32_e32 v38, 0xb9000000, v237
	v_add_f32_e32 v36, v195, v36
	v_add_f32_e32 v39, v195, v39
	v_mul_f32_e32 v35, v35, v36
	v_mul_f32_e32 v38, v38, v39
	v_cvt_pk_bf16_f32 v35, v35, v35
	v_cvt_pk_bf16_f32 v38, v38, v38
	global_store_short v[4:5], v35, off offset:2048
	global_store_short v[2:3], v38, off offset:2048
	s_waitcnt vmcnt(22)
	v_lshlrev_b32_e32 v41, 16, v41
	v_lshlrev_b32_e32 v42, 16, v42
	v_lshlrev_b32_e32 v43, 16, v43
	v_lshlrev_b32_e32 v44, 16, v44
	v_lshlrev_b32_e32 v45, 16, v45
	v_lshlrev_b32_e32 v46, 16, v46
	v_mul_f32_e32 v42, v196, v42
	v_mul_f32_e32 v45, v196, v45
	v_fmac_f32_e32 v42, v74, v41
	v_fmac_f32_e32 v45, v74, v44
	v_fmac_f32_e32 v42, v75, v43
	v_fmac_f32_e32 v45, v75, v46
	v_mul_f32_e32 v41, 0x39000000, v238
	v_mul_f32_e32 v44, 0xb9000000, v239
	v_add_f32_e32 v42, v195, v42
	v_add_f32_e32 v45, v195, v45
	v_mul_f32_e32 v41, v41, v42
	v_mul_f32_e32 v44, v44, v45
	v_cvt_pk_bf16_f32 v41, v41, v41
	v_cvt_pk_bf16_f32 v44, v44, v44
	global_store_short v[4:5], v41, off offset:2560
	global_store_short v[2:3], v44, off offset:2560
	s_waitcnt vmcnt(18)
	v_lshlrev_b32_e32 v47, 16, v47
	v_lshlrev_b32_e32 v48, 16, v48
	v_lshlrev_b32_e32 v49, 16, v49
	v_lshlrev_b32_e32 v50, 16, v50
	v_lshlrev_b32_e32 v51, 16, v51
	v_lshlrev_b32_e32 v52, 16, v52
	v_mul_f32_e32 v48, v196, v48
	v_mul_f32_e32 v51, v196, v51
	v_fmac_f32_e32 v48, v74, v47
	v_fmac_f32_e32 v51, v74, v50
	v_fmac_f32_e32 v48, v75, v49
	v_fmac_f32_e32 v51, v75, v52
	v_mul_f32_e32 v47, 0x39000000, v240
	v_mul_f32_e32 v50, 0xb9000000, v241
	v_add_f32_e32 v48, v195, v48
	v_add_f32_e32 v51, v195, v51
	v_mul_f32_e32 v47, v47, v48
	v_mul_f32_e32 v50, v50, v51
	v_cvt_pk_bf16_f32 v47, v47, v47
	v_cvt_pk_bf16_f32 v50, v50, v50
	global_store_short v[4:5], v47, off offset:3072
	global_store_short v[2:3], v50, off offset:3072
	s_waitcnt vmcnt(14)
; DI float bf2f(u16 v) { return __uint_as_float(((unsigned)v) << 16); }
; DI float sconv3(const u16* row, int t, int n, float w0, float w1, float w2, float bias) {
;   float xm = (t > 0) ? bf2f(row[t - 1]) : 0.f, x0 = bf2f(row[t]), xp = (t + 1 < n) ? bf2f(row[t + 1]) : 0.f;
;   return w0 * xm + w1 * x0 + w2 * xp + bias;
; }
; DI void hyena_unit(KP p, int l, int c, char* smem) {
;     ...
;       const u16* g0 = Zhy + (size_t)(b0 * 1536 + gcol) * 4096;
;       const u16* g1 = Zhy + (size_t)(b1 * 1536 + gcol) * 4096;
; #pragma unroll 4
;       for (int jj = 0; jj < 16; ++jj) {
;         const int t = tid + 256 * jj;
;         const f32x2 r = buf[SW(t)];
;         const float y0 = r.x * (1.f / 8192.f), y1 = -r.y * (1.f / 8192.f);
;         const float x0 = sconv3(g0, t, 4096, gw0, gw1, gw2, gb), x1 = sconv3(g1, t, 4096, gw0, gw1, gw2, gb);
;         if (o == 0) { r0[t] = f2bf(x0 * y0); r1[t] = f2bf(x1 * y1); }
;         else { y0p[t] = f2bf(x0 * y0); y1p[t] = f2bf(x1 * y1); }
;       }
	v_lshlrev_b32_e32 v53, 16, v53
	v_lshlrev_b32_e32 v54, 16, v54
	v_lshlrev_b32_e32 v55, 16, v55
	v_lshlrev_b32_e32 v56, 16, v56
	v_lshlrev_b32_e32 v57, 16, v57
	v_lshlrev_b32_e32 v58, 16, v58
	v_mul_f32_e32 v54, v196, v54
	v_mul_f32_e32 v57, v196, v57
	v_fmac_f32_e32 v54, v74, v53
	v_fmac_f32_e32 v57, v74, v56
	v_fmac_f32_e32 v54, v75, v55
	v_fmac_f32_e32 v57, v75, v58
	v_mul_f32_e32 v53, 0x39000000, v244
	v_mul_f32_e32 v56, 0xb9000000, v245
	v_add_f32_e32 v54, v195, v54
	v_add_f32_e32 v57, v195, v57
	v_mul_f32_e32 v53, v53, v54
	v_mul_f32_e32 v56, v56, v57
	v_cvt_pk_bf16_f32 v53, v53, v53
	v_cvt_pk_bf16_f32 v56, v56, v56
	global_store_short v[4:5], v53, off offset:3584
	global_store_short v[2:3], v56, off offset:3584
	ds_read_b64 v[224:225], v203 offset:16384
	ds_read_b64 v[226:227], v203 offset:18432
	ds_read_b64 v[230:231], v203 offset:20480
	ds_read_b64 v[232:233], v203 offset:22528
	ds_read_b64 v[236:237], v203 offset:24576
	ds_read_b64 v[238:239], v203 offset:26624
	ds_read_b64 v[240:241], v203 offset:28672
	ds_read_b64 v[244:245], v203 offset:30720
	global_load_ushort v10, v202, s[6:7] offset:-2
	global_load_ushort v11, v202, s[6:7] offset:0
	global_load_ushort v12, v202, s[6:7] offset:2
	global_load_ushort v13, v202, s[12:13] offset:-2
	global_load_ushort v14, v202, s[12:13] offset:0
	global_load_ushort v15, v202, s[12:13] offset:2
	global_load_ushort v16, v202, s[6:7] offset:510
	global_load_ushort v17, v202, s[6:7] offset:512
	global_load_ushort v18, v202, s[6:7] offset:514
	global_load_ushort v19, v202, s[12:13] offset:510
	global_load_ushort v20, v202, s[12:13] offset:512
	global_load_ushort v21, v202, s[12:13] offset:514
	global_load_ushort v22, v202, s[6:7] offset:1022
	global_load_ushort v23, v202, s[6:7] offset:1024
	global_load_ushort v24, v202, s[6:7] offset:1026
	global_load_ushort v25, v202, s[12:13] offset:1022
	global_load_ushort v26, v202, s[12:13] offset:1024
	global_load_ushort v27, v202, s[12:13] offset:1026
	global_load_ushort v28, v202, s[6:7] offset:1534
	global_load_ushort v29, v202, s[6:7] offset:1536
	global_load_ushort v30, v202, s[6:7] offset:1538
	global_load_ushort v31, v202, s[12:13] offset:1534
	global_load_ushort v32, v202, s[12:13] offset:1536
	global_load_ushort v34, v202, s[12:13] offset:1538
	global_load_ushort v35, v202, s[6:7] offset:2046
	global_load_ushort v36, v202, s[6:7] offset:2048
	global_load_ushort v37, v202, s[6:7] offset:2050
	global_load_ushort v38, v202, s[12:13] offset:2046
	global_load_ushort v39, v202, s[12:13] offset:2048
	global_load_ushort v40, v202, s[12:13] offset:2050
	global_load_ushort v41, v202, s[6:7] offset:2558
	global_load_ushort v42, v202, s[6:7] offset:2560
	global_load_ushort v43, v202, s[6:7] offset:2562
	global_load_ushort v44, v202, s[12:13] offset:2558
	global_load_ushort v45, v202, s[12:13] offset:2560
	global_load_ushort v46, v202, s[12:13] offset:2562
	global_load_ushort v47, v202, s[6:7] offset:3070
	global_load_ushort v48, v202, s[6:7] offset:3072
	global_load_ushort v49, v202, s[6:7] offset:3074
	global_load_ushort v50, v202, s[12:13] offset:3070
	global_load_ushort v51, v202, s[12:13] offset:3072
	global_load_ushort v52, v202, s[12:13] offset:3074
	global_load_ushort v53, v202, s[6:7] offset:3582
	global_load_ushort v54, v202, s[6:7] offset:3584
	global_load_ushort v55, v202, s[6:7] offset:3586
	global_load_ushort v56, v202, s[12:13] offset:3582
	global_load_ushort v57, v202, s[12:13] offset:3584
	global_load_ushort v58, v202, s[12:13] offset:3586
	s_waitcnt vmcnt(42)
	s_waitcnt lgkmcnt(0)
	v_lshlrev_b32_e32 v10, 16, v10
	v_lshlrev_b32_e32 v11, 16, v11
	v_lshlrev_b32_e32 v12, 16, v12
	v_lshlrev_b32_e32 v13, 16, v13
	v_lshlrev_b32_e32 v14, 16, v14
	v_lshlrev_b32_e32 v15, 16, v15
	v_mul_f32_e32 v11, v196, v11
	v_mul_f32_e32 v14, v196, v14
	v_fmac_f32_e32 v11, v74, v10
	v_fmac_f32_e32 v14, v74, v13
	v_fmac_f32_e32 v11, v75, v12
	v_fmac_f32_e32 v14, v75, v15
	v_mul_f32_e32 v10, 0x39000000, v224
	v_mul_f32_e32 v13, 0xb9000000, v225
	v_add_f32_e32 v11, v195, v11
	v_add_f32_e32 v14, v195, v14
	v_mul_f32_e32 v10, v10, v11
	v_mul_f32_e32 v13, v13, v14
	v_cvt_pk_bf16_f32 v10, v10, v10
	v_cvt_pk_bf16_f32 v13, v13, v13
	global_store_short v[204:205], v10, off
	global_store_short v[206:207], v13, off
	s_waitcnt vmcnt(38)
	v_lshlrev_b32_e32 v16, 16, v16
	v_lshlrev_b32_e32 v17, 16, v17
	v_lshlrev_b32_e32 v18, 16, v18
	v_lshlrev_b32_e32 v19, 16, v19
	v_lshlrev_b32_e32 v20, 16, v20
	v_lshlrev_b32_e32 v21, 16, v21
	v_mul_f32_e32 v17, v196, v17
	v_mul_f32_e32 v20, v196, v20
	v_fmac_f32_e32 v17, v74, v16
	v_fmac_f32_e32 v20, v74, v19
	v_fmac_f32_e32 v17, v75, v18
	v_fmac_f32_e32 v20, v75, v21
	v_mul_f32_e32 v16, 0x39000000, v226
	v_mul_f32_e32 v19, 0xb9000000, v227
	v_add_f32_e32 v17, v195, v17
	v_add_f32_e32 v20, v195, v20
	v_mul_f32_e32 v16, v16, v17
	v_mul_f32_e32 v19, v19, v20
	v_cvt_pk_bf16_f32 v16, v16, v16
	v_cvt_pk_bf16_f32 v19, v19, v19
	global_store_short v[204:205], v16, off offset:512
	global_store_short v[206:207], v19, off offset:512
	s_waitcnt vmcnt(34)
; DI float bf2f(u16 v) { return __uint_as_float(((unsigned)v) << 16); }
; DI float sconv3(const u16* row, int t, int n, float w0, float w1, float w2, float bias) {
;   float xm = (t > 0) ? bf2f(row[t - 1]) : 0.f, x0 = bf2f(row[t]), xp = (t + 1 < n) ? bf2f(row[t + 1]) : 0.f;
;   return w0 * xm + w1 * x0 + w2 * xp + bias;
; }
; DI void hyena_unit(KP p, int l, int c, char* smem) {
;     ...
;       const u16* g0 = Zhy + (size_t)(b0 * 1536 + gcol) * 4096;
;       const u16* g1 = Zhy + (size_t)(b1 * 1536 + gcol) * 4096;
; #pragma unroll 4
;       for (int jj = 0; jj < 16; ++jj) {
;         const int t = tid + 256 * jj;
;         const f32x2 r = buf[SW(t)];
;         const float y0 = r.x * (1.f / 8192.f), y1 = -r.y * (1.f / 8192.f);
;         const float x0 = sconv3(g0, t, 4096, gw0, gw1, gw2, gb), x1 = sconv3(g1, t, 4096, gw0, gw1, gw2, gb);
;         if (o == 0) { r0[t] = f2bf(x0 * y0); r1[t] = f2bf(x1 * y1); }
;         else { y0p[t] = f2bf(x0 * y0); y1p[t] = f2bf(x1 * y1); }
;       }
	v_lshlrev_b32_e32 v22, 16, v22
	v_lshlrev_b32_e32 v23, 16, v23
	v_lshlrev_b32_e32 v24, 16, v24
	v_lshlrev_b32_e32 v25, 16, v25
	v_lshlrev_b32_e32 v26, 16, v26
	v_lshlrev_b32_e32 v27, 16, v27
	v_mul_f32_e32 v23, v196, v23
	v_mul_f32_e32 v26, v196, v26
	v_fmac_f32_e32 v23, v74, v22
	v_fmac_f32_e32 v26, v74, v25
	v_fmac_f32_e32 v23, v75, v24
	v_fmac_f32_e32 v26, v75, v27
	v_mul_f32_e32 v22, 0x39000000, v230
	v_mul_f32_e32 v25, 0xb9000000, v231
	v_add_f32_e32 v23, v195, v23
	v_add_f32_e32 v26, v195, v26
	v_mul_f32_e32 v22, v22, v23
	v_mul_f32_e32 v25, v25, v26
	v_cvt_pk_bf16_f32 v22, v22, v22
	v_cvt_pk_bf16_f32 v25, v25, v25
	global_store_short v[204:205], v22, off offset:1024
	global_store_short v[206:207], v25, off offset:1024
	s_waitcnt vmcnt(30)
	v_lshlrev_b32_e32 v28, 16, v28
	v_lshlrev_b32_e32 v29, 16, v29
	v_lshlrev_b32_e32 v30, 16, v30
	v_lshlrev_b32_e32 v31, 16, v31
	v_lshlrev_b32_e32 v32, 16, v32
	v_lshlrev_b32_e32 v34, 16, v34
	v_mul_f32_e32 v29, v196, v29
	v_mul_f32_e32 v32, v196, v32
	v_fmac_f32_e32 v29, v74, v28
	v_fmac_f32_e32 v32, v74, v31
	v_fmac_f32_e32 v29, v75, v30
	v_fmac_f32_e32 v32, v75, v34
	v_mul_f32_e32 v28, 0x39000000, v232
	v_mul_f32_e32 v31, 0xb9000000, v233
	v_add_f32_e32 v29, v195, v29
	v_add_f32_e32 v32, v195, v32
	v_mul_f32_e32 v28, v28, v29
	v_mul_f32_e32 v31, v31, v32
	v_cvt_pk_bf16_f32 v28, v28, v28
	v_cvt_pk_bf16_f32 v31, v31, v31
	global_store_short v[204:205], v28, off offset:1536
	global_store_short v[206:207], v31, off offset:1536
	s_waitcnt vmcnt(26)
	v_lshlrev_b32_e32 v35, 16, v35
	v_lshlrev_b32_e32 v36, 16, v36
	v_lshlrev_b32_e32 v37, 16, v37
	v_lshlrev_b32_e32 v38, 16, v38
	v_lshlrev_b32_e32 v39, 16, v39
	v_lshlrev_b32_e32 v40, 16, v40
	v_mul_f32_e32 v36, v196, v36
	v_mul_f32_e32 v39, v196, v39
	v_fmac_f32_e32 v36, v74, v35
	v_fmac_f32_e32 v39, v74, v38
	v_fmac_f32_e32 v36, v75, v37
	v_fmac_f32_e32 v39, v75, v40
	v_mul_f32_e32 v35, 0x39000000, v236
	v_mul_f32_e32 v38, 0xb9000000, v237
	v_add_f32_e32 v36, v195, v36
	v_add_f32_e32 v39, v195, v39
	v_mul_f32_e32 v35, v35, v36
	v_mul_f32_e32 v38, v38, v39
	v_cvt_pk_bf16_f32 v35, v35, v35
	v_cvt_pk_bf16_f32 v38, v38, v38
	global_store_short v[204:205], v35, off offset:2048
	global_store_short v[206:207], v38, off offset:2048
	s_waitcnt vmcnt(22)
	v_lshlrev_b32_e32 v41, 16, v41
	v_lshlrev_b32_e32 v42, 16, v42
	v_lshlrev_b32_e32 v43, 16, v43
	v_lshlrev_b32_e32 v44, 16, v44
	v_lshlrev_b32_e32 v45, 16, v45
	v_lshlrev_b32_e32 v46, 16, v46
	v_mul_f32_e32 v42, v196, v42
	v_mul_f32_e32 v45, v196, v45
	v_fmac_f32_e32 v42, v74, v41
	v_fmac_f32_e32 v45, v74, v44
	v_fmac_f32_e32 v42, v75, v43
	v_fmac_f32_e32 v45, v75, v46
	v_mul_f32_e32 v41, 0x39000000, v238
	v_mul_f32_e32 v44, 0xb9000000, v239
	v_add_f32_e32 v42, v195, v42
	v_add_f32_e32 v45, v195, v45
	v_mul_f32_e32 v41, v41, v42
	v_mul_f32_e32 v44, v44, v45
	v_cvt_pk_bf16_f32 v41, v41, v41
	v_cvt_pk_bf16_f32 v44, v44, v44
	global_store_short v[204:205], v41, off offset:2560
	global_store_short v[206:207], v44, off offset:2560
	s_waitcnt vmcnt(18)
	v_lshlrev_b32_e32 v47, 16, v47
	v_lshlrev_b32_e32 v48, 16, v48
	v_lshlrev_b32_e32 v49, 16, v49
	v_lshlrev_b32_e32 v50, 16, v50
	v_lshlrev_b32_e32 v51, 16, v51
	v_lshlrev_b32_e32 v52, 16, v52
	v_mul_f32_e32 v48, v196, v48
	v_mul_f32_e32 v51, v196, v51
	v_fmac_f32_e32 v48, v74, v47
	v_fmac_f32_e32 v51, v74, v50
	v_fmac_f32_e32 v48, v75, v49
	v_fmac_f32_e32 v51, v75, v52
	v_mul_f32_e32 v47, 0x39000000, v240
	v_mul_f32_e32 v50, 0xb9000000, v241
	v_add_f32_e32 v48, v195, v48
	v_add_f32_e32 v51, v195, v51
	v_mul_f32_e32 v47, v47, v48
	v_mul_f32_e32 v50, v50, v51
	v_cvt_pk_bf16_f32 v47, v47, v47
	v_cvt_pk_bf16_f32 v50, v50, v50
	global_store_short v[204:205], v47, off offset:3072
	global_store_short v[206:207], v50, off offset:3072
	s_waitcnt vmcnt(14)
	v_cndmask_b32_e64 v55, v55, 0, s[10:11]
	v_cndmask_b32_e64 v58, v58, 0, s[10:11]
	v_lshlrev_b32_e32 v53, 16, v53
	v_lshlrev_b32_e32 v54, 16, v54
	v_lshlrev_b32_e32 v55, 16, v55
	v_lshlrev_b32_e32 v56, 16, v56
	v_lshlrev_b32_e32 v57, 16, v57
	v_lshlrev_b32_e32 v58, 16, v58
	v_mul_f32_e32 v54, v196, v54
	v_mul_f32_e32 v57, v196, v57
	v_fmac_f32_e32 v54, v74, v53
	v_fmac_f32_e32 v57, v74, v56
	v_fmac_f32_e32 v54, v75, v55
	v_fmac_f32_e32 v57, v75, v58
	v_mul_f32_e32 v53, 0x39000000, v244
	v_mul_f32_e32 v56, 0xb9000000, v245
	v_add_f32_e32 v54, v195, v54
	v_add_f32_e32 v57, v195, v57
	v_mul_f32_e32 v53, v53, v54
	v_mul_f32_e32 v56, v56, v57
	v_cvt_pk_bf16_f32 v53, v53, v53
	v_cvt_pk_bf16_f32 v56, v56, v56
	global_store_short v[204:205], v53, off offset:3584
	global_store_short v[206:207], v56, off offset:3584
	s_branch .LBB0_936
